# v37 + phases 3+4 and 7+8 merged into 32-MFMA segments (12 instead of 16 barriers per 2 K-tiles), relaxed counted vmcnt(8)/(10); bit-identical
# baseline (speedup 1.0000x reference)
; #define PG8_WAIT_V(n) asm volatile("s_waitcnt vmcnt(" #n ")" ::: "memory")
; #define PG8_WAIT_L(n) asm volatile("s_waitcnt lgkmcnt(" #n ")" ::: "memory")
; #define PG8_BAR __builtin_amdgcn_s_barrier()
; #define PG8_SCHED __builtin_amdgcn_sched_barrier(0)
; template <class Epi, class AddrA, class AddrB>
; __device__ __forceinline__ void gemm_phase(const Sched S, const int lda, const int ldb, const int K, const AddrA addrA,
;                                            const AddrB addrB, const Epi E) {
;     ...
;       PG8_LDB(B0, 0, 0); PG8_SCHED; PG8_LDA(At, 0, 0); PG8_STAGE(PG8_SA(1, 1), a1 + hstepA, voffA);
;       PG8_WAIT_L(8); PG8_BAR; PG8_WAIT_L(0); PG8_MMA(0, 0, At, B0); PG8_BAR; PG8_SCHED;
;       PG8_LDB(B1, 0, 1); PG8_STAGE(PG8_SB(0, 0), b2, voffB);
;       PG8_BAR; PG8_WAIT_L(0); PG8_MMA(0, 1, At, B1); PG8_BAR;
;       PG8_LDA(At, 0, 1); PG8_STAGE(PG8_SA(0, 0), a2, voffA);
;       PG8_BAR; PG8_WAIT_L(0); PG8_MMA(1, 0, At, B0); PG8_BAR; PG8_SCHED;
;       PG8_STAGE(PG8_SB(0, 1), b2 + hstepB, voffB);
;       PG8_WAIT_V(6); PG8_BAR; PG8_MMA(1, 1, At, B1); PG8_BAR;
.LBB0_108:
	s_ashr_i32 s1, s0, 31
	s_lshl_b64 s[6:7], s[0:1], 20
	s_add_u32 s6, s20, s6
	s_addc_u32 s7, s21, s7
	s_and_b64 s[8:9], s[16:17], exec
	s_cselect_b32 s1, s7, s15
	s_cselect_b32 s11, s6, s14
	s_ashr_i32 s3, s2, 31
	s_lshl_b64 s[8:9], s[2:3], 20
	s_add_u32 s8, s22, s8
	s_addc_u32 s9, s23, s9
	s_and_b64 s[16:17], s[16:17], exec
	s_cselect_b32 s3, s9, s13
	s_cselect_b32 s36, s8, s12
	s_add_u32 s37, s12, 0x100
	s_addc_u32 s38, s13, 0
	s_add_u32 s12, s14, 0x80080
	s_addc_u32 s13, s15, 0
	s_mov_b32 s39, -2
	s_add_i32 s40, 0, 0x10000
	v_add_u32_e32 v142, s40, v145
	ds_read_b128 v[148:151], v142
	ds_read_b128 v[152:155], v142 offset:1024
	ds_read_b128 v[156:159], v142 offset:2048
	ds_read_b128 v[160:163], v142 offset:3072
	v_lshl_add_u64 v[142:143], s[12:13], 0, v[140:141]
	s_add_i32 m0, s24, 0xc000
	ds_read_b128 v[168:171], v146
	ds_read_b128 v[172:175], v146 offset:1024
	ds_read_b128 v[176:179], v146 offset:2048
	ds_read_b128 v[180:183], v146 offset:3072
	ds_read_b128 v[184:187], v146 offset:4096
	ds_read_b128 v[188:191], v146 offset:5120
	ds_read_b128 v[192:195], v146 offset:6144
	ds_read_b128 v[212:215], v146 offset:7168
	global_load_lds_dwordx4 v[142:143], off
	v_lshl_add_u64 v[142:143], s[12:13], 0, v[138:139]
	s_add_i32 m0, s24, 0xe000
	s_nop 0
	global_load_lds_dwordx4 v[142:143], off
	s_waitcnt lgkmcnt(6)
	s_setprio 1
	s_barrier
	v_mfma_f32_16x16x32_bf16 v[128:131], v[148:151], v[168:171], 0
	v_mfma_f32_16x16x32_bf16 v[128:131], v[152:155], v[172:175], v[128:131]
	s_waitcnt lgkmcnt(0)
	v_mfma_f32_16x16x32_bf16 v[120:123], v[148:151], v[176:179], 0
	v_mfma_f32_16x16x32_bf16 v[120:123], v[152:155], v[180:183], v[120:123]
	v_mfma_f32_16x16x32_bf16 v[104:107], v[148:151], v[184:187], 0
	v_mfma_f32_16x16x32_bf16 v[104:107], v[152:155], v[188:191], v[104:107]
	v_mfma_f32_16x16x32_bf16 v[88:91], v[148:151], v[192:195], 0
	v_mfma_f32_16x16x32_bf16 v[88:91], v[152:155], v[212:215], v[88:91]
	v_mfma_f32_16x16x32_bf16 v[124:127], v[156:159], v[168:171], 0
	v_mfma_f32_16x16x32_bf16 v[124:127], v[160:163], v[172:175], v[124:127]
	v_mfma_f32_16x16x32_bf16 v[112:115], v[156:159], v[176:179], 0
	v_mfma_f32_16x16x32_bf16 v[112:115], v[160:163], v[180:183], v[112:115]
	v_mfma_f32_16x16x32_bf16 v[96:99], v[156:159], v[184:187], 0
	v_mfma_f32_16x16x32_bf16 v[96:99], v[160:163], v[188:191], v[96:99]
	v_mfma_f32_16x16x32_bf16 v[80:83], v[156:159], v[192:195], 0
	v_mfma_f32_16x16x32_bf16 v[80:83], v[160:163], v[212:215], v[80:83]
	s_barrier
	s_setprio 0
	s_add_u32 s14, s12, 0xfff80080
	s_addc_u32 s15, s13, -1
	s_cmp_eq_u32 s39, 28
	s_cselect_b32 s17, s1, s15
	s_cselect_b32 s16, s11, s14
	s_cselect_b32 s15, s3, s38
	s_cselect_b32 s14, s36, s37
	s_add_i32 s42, 0, 0x14000
	v_add_u32_e32 v142, s42, v145
	s_add_i32 s40, s40, s19
	ds_read_b128 v[216:219], v142
	ds_read_b128 v[220:223], v142 offset:1024
	ds_read_b128 v[224:227], v142 offset:2048
	ds_read_b128 v[228:231], v142 offset:3072
	v_lshl_add_u64 v[142:143], s[14:15], 0, v[134:135]
	s_mov_b32 m0, s40
	v_lshl_add_u64 v[196:197], s[14:15], 0, v[0:1]
	global_load_lds_dwordx4 v[142:143], off
	s_add_i32 m0, s40, 0x2000
	s_nop 0
	global_load_lds_dwordx4 v[196:197], off
	s_mov_b32 m0, s24
	v_lshl_add_u64 v[232:233], s[16:17], 0, v[136:137]
	s_waitcnt vmcnt(10)
	s_waitcnt lgkmcnt(0)
	s_setprio 1
	s_barrier
	v_mfma_f32_16x16x32_bf16 v[116:119], v[216:219], v[168:171], 0
	v_mfma_f32_16x16x32_bf16 v[116:119], v[220:223], v[172:175], v[116:119]
	s_waitcnt lgkmcnt(0)
	v_mfma_f32_16x16x32_bf16 v[100:103], v[216:219], v[176:179], 0
	v_mfma_f32_16x16x32_bf16 v[100:103], v[220:223], v[180:183], v[100:103]
	v_mfma_f32_16x16x32_bf16 v[84:87], v[216:219], v[184:187], 0
	v_mfma_f32_16x16x32_bf16 v[84:87], v[220:223], v[188:191], v[84:87]
	v_mfma_f32_16x16x32_bf16 v[72:75], v[216:219], v[192:195], 0
	v_mfma_f32_16x16x32_bf16 v[72:75], v[220:223], v[212:215], v[72:75]
	v_mfma_f32_16x16x32_bf16 v[108:111], v[224:227], v[168:171], 0
	v_mfma_f32_16x16x32_bf16 v[108:111], v[228:231], v[172:175], v[108:111]
	v_mfma_f32_16x16x32_bf16 v[92:95], v[224:227], v[176:179], 0
	v_mfma_f32_16x16x32_bf16 v[92:95], v[228:231], v[180:183], v[92:95]
	v_mfma_f32_16x16x32_bf16 v[76:79], v[224:227], v[184:187], 0
	v_mfma_f32_16x16x32_bf16 v[76:79], v[228:231], v[188:191], v[76:79]
	v_mfma_f32_16x16x32_bf16 v[68:71], v[224:227], v[192:195], 0
	v_mfma_f32_16x16x32_bf16 v[68:71], v[228:231], v[212:215], v[68:71]
	s_barrier
	s_setprio 0
	ds_read_b128 v[168:171], v146 offset:16384
	ds_read_b128 v[172:175], v146 offset:17408
	ds_read_b128 v[176:179], v146 offset:18432
	ds_read_b128 v[180:183], v146 offset:19456
	ds_read_b128 v[184:187], v146 offset:20480
	ds_read_b128 v[188:191], v146 offset:21504
	ds_read_b128 v[192:195], v146 offset:22528
	ds_read_b128 v[212:215], v146 offset:23552
	global_load_lds_dwordx4 v[232:233], off
	v_lshl_add_u64 v[234:235], s[16:17], 0, v[132:133]
	s_mov_b32 m0, s25
	s_nop 0
	global_load_lds_dwordx4 v[234:235], off
	s_add_u32 s40, s14, 0x80000
	s_addc_u32 s41, s15, 0
	s_add_i32 s42, s42, s19
	v_lshl_add_u64 v[246:247], s[40:41], 0, v[134:135]
	s_mov_b32 m0, s42
	s_nop 0
	global_load_lds_dwordx4 v[246:247], off
	v_lshl_add_u64 v[246:247], s[40:41], 0, v[0:1]
	s_add_i32 m0, s42, 0x2000
	s_nop 0
	global_load_lds_dwordx4 v[246:247], off
	s_add_i32 s40, 0, 0x18000
	v_add_u32_e32 v147, s40, v145
	s_waitcnt vmcnt(8)
	s_waitcnt lgkmcnt(0)
	s_setprio 1
	s_barrier
; #define PG8_WAIT_V(n) asm volatile("s_waitcnt vmcnt(" #n ")" ::: "memory")
; #define PG8_WAIT_L(n) asm volatile("s_waitcnt lgkmcnt(" #n ")" ::: "memory")
; #define PG8_BAR __builtin_amdgcn_s_barrier()
; #define PG8_SCHED __builtin_amdgcn_sched_barrier(0)
; template <class Epi, class AddrA, class AddrB>
; __device__ __forceinline__ void gemm_phase(const Sched S, const int lda, const int ldb, const int K, const AddrA addrA,
;                                            const AddrB addrB, const Epi E) {
;     ...
;       PG8_BAR; PG8_WAIT_L(0); PG8_MMA(1, 0, At, B0); PG8_BAR; PG8_SCHED;
;       PG8_STAGE(PG8_SB(0, 1), b2 + hstepB, voffB);
;       PG8_WAIT_V(6); PG8_BAR; PG8_MMA(1, 1, At, B1); PG8_BAR;
;       PG8_LDB(B0, 1, 0); PG8_SCHED; PG8_LDA(At, 1, 0); PG8_STAGE(PG8_SA(0, 1), a2 + hstepA, voffA);
;       PG8_WAIT_L(8); PG8_BAR; PG8_WAIT_L(0); PG8_MMA(0, 0, At, B0); PG8_BAR; PG8_SCHED;
;       PG8_LDB(B1, 1, 1); PG8_STAGE(PG8_SB(1, 0), b3, voffB);
;       PG8_BAR; PG8_WAIT_L(0); PG8_MMA(0, 1, At, B1); PG8_BAR;
;       PG8_LDA(At, 1, 1); PG8_STAGE(PG8_SA(1, 0), a3, voffA);
;       PG8_BAR; PG8_WAIT_L(0); PG8_MMA(1, 0, At, B0); PG8_BAR; PG8_SCHED;
	v_mfma_f32_16x16x32_bf16 v[64:67], v[148:151], v[168:171], 0
	v_mfma_f32_16x16x32_bf16 v[64:67], v[152:155], v[172:175], v[64:67]
	s_waitcnt lgkmcnt(0)
	v_mfma_f32_16x16x32_bf16 v[56:59], v[148:151], v[176:179], 0
	v_mfma_f32_16x16x32_bf16 v[56:59], v[152:155], v[180:183], v[56:59]
	v_mfma_f32_16x16x32_bf16 v[40:43], v[148:151], v[184:187], 0
	v_mfma_f32_16x16x32_bf16 v[40:43], v[152:155], v[188:191], v[40:43]
	v_mfma_f32_16x16x32_bf16 v[24:27], v[148:151], v[192:195], 0
	v_mfma_f32_16x16x32_bf16 v[24:27], v[152:155], v[212:215], v[24:27]
	v_mfma_f32_16x16x32_bf16 v[60:63], v[156:159], v[168:171], 0
	v_mfma_f32_16x16x32_bf16 v[60:63], v[160:163], v[172:175], v[60:63]
	v_mfma_f32_16x16x32_bf16 v[48:51], v[156:159], v[176:179], 0
	v_mfma_f32_16x16x32_bf16 v[48:51], v[160:163], v[180:183], v[48:51]
	v_mfma_f32_16x16x32_bf16 v[32:35], v[156:159], v[184:187], 0
	v_mfma_f32_16x16x32_bf16 v[32:35], v[160:163], v[188:191], v[32:35]
	v_mfma_f32_16x16x32_bf16 v[16:19], v[156:159], v[192:195], 0
	v_mfma_f32_16x16x32_bf16 v[16:19], v[160:163], v[212:215], v[16:19]
	v_mfma_f32_16x16x32_bf16 v[52:55], v[216:219], v[168:171], 0
	v_mfma_f32_16x16x32_bf16 v[52:55], v[220:223], v[172:175], v[52:55]
	v_mfma_f32_16x16x32_bf16 v[36:39], v[216:219], v[176:179], 0
	v_mfma_f32_16x16x32_bf16 v[36:39], v[220:223], v[180:183], v[36:39]
	v_mfma_f32_16x16x32_bf16 v[20:23], v[216:219], v[184:187], 0
	v_mfma_f32_16x16x32_bf16 v[20:23], v[220:223], v[188:191], v[20:23]
	v_mfma_f32_16x16x32_bf16 v[8:11], v[216:219], v[192:195], 0
	v_mfma_f32_16x16x32_bf16 v[8:11], v[220:223], v[212:215], v[8:11]
	v_mfma_f32_16x16x32_bf16 v[44:47], v[224:227], v[168:171], 0
	v_mfma_f32_16x16x32_bf16 v[44:47], v[228:231], v[172:175], v[44:47]
	v_mfma_f32_16x16x32_bf16 v[28:31], v[224:227], v[176:179], 0
	v_mfma_f32_16x16x32_bf16 v[28:31], v[228:231], v[180:183], v[28:31]
	v_mfma_f32_16x16x32_bf16 v[12:15], v[224:227], v[184:187], 0
	v_mfma_f32_16x16x32_bf16 v[12:15], v[228:231], v[188:191], v[12:15]
	v_mfma_f32_16x16x32_bf16 v[4:7], v[224:227], v[192:195], 0
	v_mfma_f32_16x16x32_bf16 v[4:7], v[228:231], v[212:215], v[4:7]
	s_barrier
	s_setprio 0
	ds_read_b128 v[148:151], v147
	ds_read_b128 v[152:155], v147 offset:1024
	ds_read_b128 v[156:159], v147 offset:2048
	ds_read_b128 v[160:163], v147 offset:3072
	s_add_u32 s16, s16, 0x80000
	s_addc_u32 s17, s17, 0
	s_mov_b32 m0, s26
	v_lshl_add_u64 v[216:217], s[16:17], 0, v[136:137]
	ds_read_b128 v[168:171], v146 offset:32768
	ds_read_b128 v[172:175], v146 offset:33792
	ds_read_b128 v[176:179], v146 offset:34816
	ds_read_b128 v[180:183], v146 offset:35840
	ds_read_b128 v[184:187], v146 offset:36864
	ds_read_b128 v[188:191], v146 offset:37888
	ds_read_b128 v[192:195], v146 offset:38912
	ds_read_b128 v[212:215], v146 offset:39936
	global_load_lds_dwordx4 v[216:217], off
	v_lshl_add_u64 v[216:217], s[16:17], 0, v[132:133]
	s_mov_b32 m0, s27
	s_nop 0
	global_load_lds_dwordx4 v[216:217], off
	s_waitcnt lgkmcnt(6)
	s_setprio 1
	s_barrier
	v_mfma_f32_16x16x32_bf16 v[128:131], v[148:151], v[168:171], v[128:131]
	v_mfma_f32_16x16x32_bf16 v[128:131], v[152:155], v[172:175], v[128:131]
	s_waitcnt lgkmcnt(0)
	v_mfma_f32_16x16x32_bf16 v[120:123], v[148:151], v[176:179], v[120:123]
	v_mfma_f32_16x16x32_bf16 v[120:123], v[152:155], v[180:183], v[120:123]
	v_mfma_f32_16x16x32_bf16 v[104:107], v[148:151], v[184:187], v[104:107]
	v_mfma_f32_16x16x32_bf16 v[104:107], v[152:155], v[188:191], v[104:107]
	v_mfma_f32_16x16x32_bf16 v[88:91], v[148:151], v[192:195], v[88:91]
	v_mfma_f32_16x16x32_bf16 v[88:91], v[152:155], v[212:215], v[88:91]
	v_mfma_f32_16x16x32_bf16 v[124:127], v[156:159], v[168:171], v[124:127]
	v_mfma_f32_16x16x32_bf16 v[124:127], v[160:163], v[172:175], v[124:127]
	v_mfma_f32_16x16x32_bf16 v[112:115], v[156:159], v[176:179], v[112:115]
	v_mfma_f32_16x16x32_bf16 v[112:115], v[160:163], v[180:183], v[112:115]
	v_mfma_f32_16x16x32_bf16 v[96:99], v[156:159], v[184:187], v[96:99]
	v_mfma_f32_16x16x32_bf16 v[96:99], v[160:163], v[188:191], v[96:99]
	v_mfma_f32_16x16x32_bf16 v[80:83], v[156:159], v[192:195], v[80:83]
	v_mfma_f32_16x16x32_bf16 v[80:83], v[160:163], v[212:215], v[80:83]
	s_barrier
	s_setprio 0
	s_add_i32 s16, 0, 0x1c000
	s_add_i32 s17, s40, s19
	v_add_u32_e32 v147, s16, v145
	v_lshl_add_u64 v[142:143], v[142:143], 0, s[52:53]
	s_mov_b32 m0, s17
	ds_read_b128 v[216:219], v147
	ds_read_b128 v[220:223], v147 offset:1024
	ds_read_b128 v[224:227], v147 offset:2048
	ds_read_b128 v[228:231], v147 offset:3072
	global_load_lds_dwordx4 v[142:143], off
	v_lshl_add_u64 v[142:143], v[196:197], 0, s[52:53]
	s_add_i32 m0, s17, 0x2000
	s_nop 0
	global_load_lds_dwordx4 v[142:143], off
	s_mov_b32 m0, s30
	v_lshl_add_u64 v[142:143], v[232:233], 0, s[52:53]
	s_waitcnt vmcnt(10)
	s_waitcnt lgkmcnt(0)
	s_setprio 1
	s_barrier
	v_mfma_f32_16x16x32_bf16 v[116:119], v[216:219], v[168:171], v[116:119]
	v_mfma_f32_16x16x32_bf16 v[116:119], v[220:223], v[172:175], v[116:119]
	s_waitcnt lgkmcnt(0)
	v_mfma_f32_16x16x32_bf16 v[100:103], v[216:219], v[176:179], v[100:103]
	v_mfma_f32_16x16x32_bf16 v[100:103], v[220:223], v[180:183], v[100:103]
	v_mfma_f32_16x16x32_bf16 v[84:87], v[216:219], v[184:187], v[84:87]
	v_mfma_f32_16x16x32_bf16 v[84:87], v[220:223], v[188:191], v[84:87]
	v_mfma_f32_16x16x32_bf16 v[72:75], v[216:219], v[192:195], v[72:75]
	v_mfma_f32_16x16x32_bf16 v[72:75], v[220:223], v[212:215], v[72:75]
	v_mfma_f32_16x16x32_bf16 v[108:111], v[224:227], v[168:171], v[108:111]
	v_mfma_f32_16x16x32_bf16 v[108:111], v[228:231], v[172:175], v[108:111]
	v_mfma_f32_16x16x32_bf16 v[92:95], v[224:227], v[176:179], v[92:95]
	v_mfma_f32_16x16x32_bf16 v[92:95], v[228:231], v[180:183], v[92:95]
	v_mfma_f32_16x16x32_bf16 v[76:79], v[224:227], v[184:187], v[76:79]
	v_mfma_f32_16x16x32_bf16 v[76:79], v[228:231], v[188:191], v[76:79]
	v_mfma_f32_16x16x32_bf16 v[68:71], v[224:227], v[192:195], v[68:71]
	v_mfma_f32_16x16x32_bf16 v[68:71], v[228:231], v[212:215], v[68:71]
	s_barrier
; #define PG8_WAIT_V(n) asm volatile("s_waitcnt vmcnt(" #n ")" ::: "memory")
; #define PG8_WAIT_L(n) asm volatile("s_waitcnt lgkmcnt(" #n ")" ::: "memory")
; #define PG8_BAR __builtin_amdgcn_s_barrier()
; #define PG8_SCHED __builtin_amdgcn_sched_barrier(0)
; template <class Epi, class AddrA, class AddrB>
; __device__ __forceinline__ void gemm_phase(const Sched S, const int lda, const int ldb, const int K, const AddrA addrA,
;                                            const AddrB addrB, const Epi E) {
;     ...
;       PG8_LDB(B0, 0, 0); PG8_SCHED; PG8_LDA(At, 0, 0); PG8_STAGE(PG8_SA(1, 1), a1 + hstepA, voffA);
;       PG8_WAIT_L(8); PG8_BAR; PG8_WAIT_L(0); PG8_MMA(0, 0, At, B0); PG8_BAR; PG8_SCHED;
;       PG8_LDB(B1, 0, 1); PG8_STAGE(PG8_SB(0, 0), b2, voffB);
;       PG8_BAR; PG8_WAIT_L(0); PG8_MMA(0, 1, At, B1); PG8_BAR;
;       PG8_LDA(At, 0, 1); PG8_STAGE(PG8_SA(0, 0), a2, voffA);
;       PG8_BAR; PG8_WAIT_L(0); PG8_MMA(1, 0, At, B0); PG8_BAR; PG8_SCHED;
;       PG8_STAGE(PG8_SB(0, 1), b2 + hstepB, voffB);
;       PG8_WAIT_V(6); PG8_BAR; PG8_MMA(1, 1, At, B1); PG8_BAR;
;       PG8_LDB(B0, 1, 0); PG8_SCHED; PG8_LDA(At, 1, 0); PG8_STAGE(PG8_SA(0, 1), a2 + hstepA, voffA);
;       PG8_WAIT_L(8); PG8_BAR; PG8_WAIT_L(0); PG8_MMA(0, 0, At, B0); PG8_BAR; PG8_SCHED;
;       PG8_LDB(B1, 1, 1); PG8_STAGE(PG8_SB(1, 0), b3, voffB);
;       PG8_BAR; PG8_WAIT_L(0); PG8_MMA(0, 1, At, B1); PG8_BAR;
;       PG8_LDA(At, 1, 1); PG8_STAGE(PG8_SA(1, 0), a3, voffA);
;       PG8_BAR; PG8_WAIT_L(0); PG8_MMA(1, 0, At, B0); PG8_BAR; PG8_SCHED;
;       PG8_STAGE(PG8_SB(1, 1), b3 + hstepB, voffB);
;       PG8_WAIT_V(6); PG8_BAR; PG8_MMA(1, 1, At, B1); PG8_BAR;
	s_setprio 0
	ds_read_b128 v[168:171], v146 offset:49152
	ds_read_b128 v[172:175], v146 offset:50176
	ds_read_b128 v[176:179], v146 offset:51200
	ds_read_b128 v[180:183], v146 offset:52224
	ds_read_b128 v[184:187], v146 offset:53248
	ds_read_b128 v[188:191], v146 offset:54272
	ds_read_b128 v[192:195], v146 offset:55296
	ds_read_b128 v[212:215], v146 offset:56320
	global_load_lds_dwordx4 v[142:143], off
	v_lshl_add_u64 v[142:143], v[234:235], 0, s[52:53]
	s_mov_b32 m0, s31
	s_nop 0
	global_load_lds_dwordx4 v[142:143], off
	s_add_u32 s14, s14, 0x80080
	s_addc_u32 s15, s15, 0
	s_add_i32 s16, s16, s19
	v_lshl_add_u64 v[142:143], s[14:15], 0, v[134:135]
	s_mov_b32 m0, s16
	s_nop 0
	global_load_lds_dwordx4 v[142:143], off
	v_lshl_add_u64 v[142:143], s[14:15], 0, v[0:1]
	s_add_i32 m0, s16, 0x2000
	s_nop 0
	global_load_lds_dwordx4 v[142:143], off
	s_add_i32 s39, s39, 2
	s_add_u32 s37, s37, 0x100
	s_addc_u32 s38, s38, 0
	s_add_u32 s12, s12, 0x100
	s_addc_u32 s13, s13, 0
	s_waitcnt vmcnt(8)
	s_waitcnt lgkmcnt(0)
	s_setprio 1
	s_barrier
	v_mfma_f32_16x16x32_bf16 v[64:67], v[148:151], v[168:171], v[64:67]
	v_mfma_f32_16x16x32_bf16 v[64:67], v[152:155], v[172:175], v[64:67]
	s_waitcnt lgkmcnt(0)
	v_mfma_f32_16x16x32_bf16 v[56:59], v[148:151], v[176:179], v[56:59]
	v_mfma_f32_16x16x32_bf16 v[56:59], v[152:155], v[180:183], v[56:59]
	v_mfma_f32_16x16x32_bf16 v[40:43], v[148:151], v[184:187], v[40:43]
	v_mfma_f32_16x16x32_bf16 v[40:43], v[152:155], v[188:191], v[40:43]
	v_mfma_f32_16x16x32_bf16 v[24:27], v[148:151], v[192:195], v[24:27]
	v_mfma_f32_16x16x32_bf16 v[24:27], v[152:155], v[212:215], v[24:27]
	v_mfma_f32_16x16x32_bf16 v[60:63], v[156:159], v[168:171], v[60:63]
	v_mfma_f32_16x16x32_bf16 v[60:63], v[160:163], v[172:175], v[60:63]
	v_mfma_f32_16x16x32_bf16 v[48:51], v[156:159], v[176:179], v[48:51]
	v_mfma_f32_16x16x32_bf16 v[48:51], v[160:163], v[180:183], v[48:51]
	v_mfma_f32_16x16x32_bf16 v[32:35], v[156:159], v[184:187], v[32:35]
	v_mfma_f32_16x16x32_bf16 v[32:35], v[160:163], v[188:191], v[32:35]
	v_mfma_f32_16x16x32_bf16 v[16:19], v[156:159], v[192:195], v[16:19]
	v_mfma_f32_16x16x32_bf16 v[16:19], v[160:163], v[212:215], v[16:19]
	v_mfma_f32_16x16x32_bf16 v[52:55], v[216:219], v[168:171], v[52:55]
	v_mfma_f32_16x16x32_bf16 v[52:55], v[220:223], v[172:175], v[52:55]
	v_mfma_f32_16x16x32_bf16 v[36:39], v[216:219], v[176:179], v[36:39]
	v_mfma_f32_16x16x32_bf16 v[36:39], v[220:223], v[180:183], v[36:39]
	v_mfma_f32_16x16x32_bf16 v[20:23], v[216:219], v[184:187], v[20:23]
	v_mfma_f32_16x16x32_bf16 v[20:23], v[220:223], v[188:191], v[20:23]
	v_mfma_f32_16x16x32_bf16 v[8:11], v[216:219], v[192:195], v[8:11]
	v_mfma_f32_16x16x32_bf16 v[8:11], v[220:223], v[212:215], v[8:11]
	v_mfma_f32_16x16x32_bf16 v[44:47], v[224:227], v[168:171], v[44:47]
	v_mfma_f32_16x16x32_bf16 v[44:47], v[228:231], v[172:175], v[44:47]
	v_mfma_f32_16x16x32_bf16 v[28:31], v[224:227], v[176:179], v[28:31]
	v_mfma_f32_16x16x32_bf16 v[28:31], v[228:231], v[180:183], v[28:31]
	v_mfma_f32_16x16x32_bf16 v[12:15], v[224:227], v[184:187], v[12:15]
	v_mfma_f32_16x16x32_bf16 v[12:15], v[228:231], v[188:191], v[12:15]
	v_mfma_f32_16x16x32_bf16 v[4:7], v[224:227], v[192:195], v[4:7]
	v_mfma_f32_16x16x32_bf16 v[4:7], v[228:231], v[212:215], v[4:7]
	s_barrier
	s_setprio 0
	s_cmp_gt_u32 s39, 29
.LBB0_109:
	s_add_i32 s40, 0, 0x10000
	v_add_u32_e32 v142, s40, v145
	ds_read_b128 v[148:151], v142
	ds_read_b128 v[152:155], v142 offset:1024
	ds_read_b128 v[156:159], v142 offset:2048
	ds_read_b128 v[160:163], v142 offset:3072
	v_lshl_add_u64 v[142:143], s[12:13], 0, v[140:141]
	s_add_i32 m0, s24, 0xc000
	ds_read_b128 v[168:171], v146
	ds_read_b128 v[172:175], v146 offset:1024
	ds_read_b128 v[176:179], v146 offset:2048
	ds_read_b128 v[180:183], v146 offset:3072
	ds_read_b128 v[184:187], v146 offset:4096
	ds_read_b128 v[188:191], v146 offset:5120
	ds_read_b128 v[192:195], v146 offset:6144
	ds_read_b128 v[212:215], v146 offset:7168
	global_load_lds_dwordx4 v[142:143], off
	v_lshl_add_u64 v[142:143], s[12:13], 0, v[138:139]
	s_add_i32 m0, s24, 0xe000
	s_nop 0
	global_load_lds_dwordx4 v[142:143], off
	s_waitcnt lgkmcnt(6)
	s_setprio 1
	s_barrier
	v_mfma_f32_16x16x32_bf16 v[128:131], v[148:151], v[168:171], v[128:131]
	v_mfma_f32_16x16x32_bf16 v[128:131], v[152:155], v[172:175], v[128:131]
	s_waitcnt lgkmcnt(0)
	v_mfma_f32_16x16x32_bf16 v[120:123], v[148:151], v[176:179], v[120:123]
	v_mfma_f32_16x16x32_bf16 v[120:123], v[152:155], v[180:183], v[120:123]
	v_mfma_f32_16x16x32_bf16 v[104:107], v[148:151], v[184:187], v[104:107]
	v_mfma_f32_16x16x32_bf16 v[104:107], v[152:155], v[188:191], v[104:107]
	v_mfma_f32_16x16x32_bf16 v[88:91], v[148:151], v[192:195], v[88:91]
	v_mfma_f32_16x16x32_bf16 v[88:91], v[152:155], v[212:215], v[88:91]
	v_mfma_f32_16x16x32_bf16 v[124:127], v[156:159], v[168:171], v[124:127]
	v_mfma_f32_16x16x32_bf16 v[124:127], v[160:163], v[172:175], v[124:127]
	v_mfma_f32_16x16x32_bf16 v[112:115], v[156:159], v[176:179], v[112:115]
	v_mfma_f32_16x16x32_bf16 v[112:115], v[160:163], v[180:183], v[112:115]
	v_mfma_f32_16x16x32_bf16 v[96:99], v[156:159], v[184:187], v[96:99]
	v_mfma_f32_16x16x32_bf16 v[96:99], v[160:163], v[188:191], v[96:99]
	v_mfma_f32_16x16x32_bf16 v[80:83], v[156:159], v[192:195], v[80:83]
	v_mfma_f32_16x16x32_bf16 v[80:83], v[160:163], v[212:215], v[80:83]
	s_barrier
; #define PG8_WAIT_V(n) asm volatile("s_waitcnt vmcnt(" #n ")" ::: "memory")
; #define PG8_WAIT_L(n) asm volatile("s_waitcnt lgkmcnt(" #n ")" ::: "memory")
; #define PG8_BAR __builtin_amdgcn_s_barrier()
; #define PG8_SCHED __builtin_amdgcn_sched_barrier(0)
; template <class Epi, class AddrA, class AddrB>
; __device__ __forceinline__ void gemm_phase(const Sched S, const int lda, const int ldb, const int K, const AddrA addrA,
;                                            const AddrB addrB, const Epi E) {
;     ...
;       PG8_WAIT_L(8); PG8_BAR; PG8_WAIT_L(0); PG8_MMA(0, 0, At, B0); PG8_BAR; PG8_SCHED;
;       PG8_LDB(B1, 0, 1); PG8_STAGE(PG8_SB(0, 0), b2, voffB);
;       PG8_BAR; PG8_WAIT_L(0); PG8_MMA(0, 1, At, B1); PG8_BAR;
;       PG8_LDA(At, 0, 1); PG8_STAGE(PG8_SA(0, 0), a2, voffA);
;       PG8_BAR; PG8_WAIT_L(0); PG8_MMA(1, 0, At, B0); PG8_BAR; PG8_SCHED;
;       PG8_STAGE(PG8_SB(0, 1), b2 + hstepB, voffB);
;       PG8_WAIT_V(6); PG8_BAR; PG8_MMA(1, 1, At, B1); PG8_BAR;
;       PG8_LDB(B0, 1, 0); PG8_SCHED; PG8_LDA(At, 1, 0); PG8_STAGE(PG8_SA(0, 1), a2 + hstepA, voffA);
;       PG8_WAIT_L(8); PG8_BAR; PG8_WAIT_L(0); PG8_MMA(0, 0, At, B0); PG8_BAR; PG8_SCHED;
;       PG8_LDB(B1, 1, 1); PG8_STAGE(PG8_SB(1, 0), b3, voffB);
	s_setprio 0
	s_add_u32 s14, s12, 0xfff80080
	s_addc_u32 s15, s13, -1
	s_cmp_eq_u32 s39, 28
	s_cselect_b32 s17, s1, s15
	s_cselect_b32 s16, s11, s14
	s_cselect_b32 s15, s3, s38
	s_cselect_b32 s14, s36, s37
	s_add_i32 s42, 0, 0x14000
	v_add_u32_e32 v142, s42, v145
	s_add_i32 s40, s40, s19
	ds_read_b128 v[216:219], v142
	ds_read_b128 v[220:223], v142 offset:1024
	ds_read_b128 v[224:227], v142 offset:2048
	ds_read_b128 v[228:231], v142 offset:3072
	v_lshl_add_u64 v[142:143], s[14:15], 0, v[134:135]
	s_mov_b32 m0, s40
	v_lshl_add_u64 v[196:197], s[14:15], 0, v[0:1]
	global_load_lds_dwordx4 v[142:143], off
	s_add_i32 m0, s40, 0x2000
	s_nop 0
	global_load_lds_dwordx4 v[196:197], off
	s_mov_b32 m0, s24
	v_lshl_add_u64 v[232:233], s[16:17], 0, v[136:137]
	s_waitcnt vmcnt(10)
	s_waitcnt lgkmcnt(0)
	s_setprio 1
	s_barrier
	v_mfma_f32_16x16x32_bf16 v[116:119], v[216:219], v[168:171], v[116:119]
	v_mfma_f32_16x16x32_bf16 v[116:119], v[220:223], v[172:175], v[116:119]
	s_waitcnt lgkmcnt(0)
	v_mfma_f32_16x16x32_bf16 v[100:103], v[216:219], v[176:179], v[100:103]
	v_mfma_f32_16x16x32_bf16 v[100:103], v[220:223], v[180:183], v[100:103]
	v_mfma_f32_16x16x32_bf16 v[84:87], v[216:219], v[184:187], v[84:87]
	v_mfma_f32_16x16x32_bf16 v[84:87], v[220:223], v[188:191], v[84:87]
	v_mfma_f32_16x16x32_bf16 v[72:75], v[216:219], v[192:195], v[72:75]
	v_mfma_f32_16x16x32_bf16 v[72:75], v[220:223], v[212:215], v[72:75]
	v_mfma_f32_16x16x32_bf16 v[108:111], v[224:227], v[168:171], v[108:111]
	v_mfma_f32_16x16x32_bf16 v[108:111], v[228:231], v[172:175], v[108:111]
	v_mfma_f32_16x16x32_bf16 v[92:95], v[224:227], v[176:179], v[92:95]
	v_mfma_f32_16x16x32_bf16 v[92:95], v[228:231], v[180:183], v[92:95]
	v_mfma_f32_16x16x32_bf16 v[76:79], v[224:227], v[184:187], v[76:79]
	v_mfma_f32_16x16x32_bf16 v[76:79], v[228:231], v[188:191], v[76:79]
	v_mfma_f32_16x16x32_bf16 v[68:71], v[224:227], v[192:195], v[68:71]
	v_mfma_f32_16x16x32_bf16 v[68:71], v[228:231], v[212:215], v[68:71]
	s_barrier
	s_setprio 0
	ds_read_b128 v[168:171], v146 offset:16384
	ds_read_b128 v[172:175], v146 offset:17408
	ds_read_b128 v[176:179], v146 offset:18432
	ds_read_b128 v[180:183], v146 offset:19456
	ds_read_b128 v[184:187], v146 offset:20480
	ds_read_b128 v[188:191], v146 offset:21504
	ds_read_b128 v[192:195], v146 offset:22528
	ds_read_b128 v[212:215], v146 offset:23552
	global_load_lds_dwordx4 v[232:233], off
	v_lshl_add_u64 v[234:235], s[16:17], 0, v[132:133]
	s_mov_b32 m0, s25
	s_nop 0
	global_load_lds_dwordx4 v[234:235], off
	s_add_u32 s40, s14, 0x80000
	s_addc_u32 s41, s15, 0
	s_add_i32 s42, s42, s19
	v_lshl_add_u64 v[246:247], s[40:41], 0, v[134:135]
	s_mov_b32 m0, s42
	s_nop 0
	global_load_lds_dwordx4 v[246:247], off
	v_lshl_add_u64 v[246:247], s[40:41], 0, v[0:1]
	s_add_i32 m0, s42, 0x2000
	s_nop 0
	global_load_lds_dwordx4 v[246:247], off
	s_add_i32 s40, 0, 0x18000
	v_add_u32_e32 v147, s40, v145
	s_waitcnt vmcnt(8)
	s_waitcnt lgkmcnt(0)
	s_setprio 1
	s_barrier
	v_mfma_f32_16x16x32_bf16 v[64:67], v[148:151], v[168:171], v[64:67]
	v_mfma_f32_16x16x32_bf16 v[64:67], v[152:155], v[172:175], v[64:67]
	s_waitcnt lgkmcnt(0)
	v_mfma_f32_16x16x32_bf16 v[56:59], v[148:151], v[176:179], v[56:59]
	v_mfma_f32_16x16x32_bf16 v[56:59], v[152:155], v[180:183], v[56:59]
	v_mfma_f32_16x16x32_bf16 v[40:43], v[148:151], v[184:187], v[40:43]
	v_mfma_f32_16x16x32_bf16 v[40:43], v[152:155], v[188:191], v[40:43]
	v_mfma_f32_16x16x32_bf16 v[24:27], v[148:151], v[192:195], v[24:27]
	v_mfma_f32_16x16x32_bf16 v[24:27], v[152:155], v[212:215], v[24:27]
	v_mfma_f32_16x16x32_bf16 v[60:63], v[156:159], v[168:171], v[60:63]
	v_mfma_f32_16x16x32_bf16 v[60:63], v[160:163], v[172:175], v[60:63]
	v_mfma_f32_16x16x32_bf16 v[48:51], v[156:159], v[176:179], v[48:51]
	v_mfma_f32_16x16x32_bf16 v[48:51], v[160:163], v[180:183], v[48:51]
	v_mfma_f32_16x16x32_bf16 v[32:35], v[156:159], v[184:187], v[32:35]
	v_mfma_f32_16x16x32_bf16 v[32:35], v[160:163], v[188:191], v[32:35]
	v_mfma_f32_16x16x32_bf16 v[16:19], v[156:159], v[192:195], v[16:19]
	v_mfma_f32_16x16x32_bf16 v[16:19], v[160:163], v[212:215], v[16:19]
	v_mfma_f32_16x16x32_bf16 v[52:55], v[216:219], v[168:171], v[52:55]
	v_mfma_f32_16x16x32_bf16 v[52:55], v[220:223], v[172:175], v[52:55]
	v_mfma_f32_16x16x32_bf16 v[36:39], v[216:219], v[176:179], v[36:39]
	v_mfma_f32_16x16x32_bf16 v[36:39], v[220:223], v[180:183], v[36:39]
	v_mfma_f32_16x16x32_bf16 v[20:23], v[216:219], v[184:187], v[20:23]
	v_mfma_f32_16x16x32_bf16 v[20:23], v[220:223], v[188:191], v[20:23]
	v_mfma_f32_16x16x32_bf16 v[8:11], v[216:219], v[192:195], v[8:11]
	v_mfma_f32_16x16x32_bf16 v[8:11], v[220:223], v[212:215], v[8:11]
	v_mfma_f32_16x16x32_bf16 v[44:47], v[224:227], v[168:171], v[44:47]
	v_mfma_f32_16x16x32_bf16 v[44:47], v[228:231], v[172:175], v[44:47]
	v_mfma_f32_16x16x32_bf16 v[28:31], v[224:227], v[176:179], v[28:31]
	v_mfma_f32_16x16x32_bf16 v[28:31], v[228:231], v[180:183], v[28:31]
	v_mfma_f32_16x16x32_bf16 v[12:15], v[224:227], v[184:187], v[12:15]
	v_mfma_f32_16x16x32_bf16 v[12:15], v[228:231], v[188:191], v[12:15]
	v_mfma_f32_16x16x32_bf16 v[4:7], v[224:227], v[192:195], v[4:7]
	v_mfma_f32_16x16x32_bf16 v[4:7], v[228:231], v[212:215], v[4:7]
	s_barrier
	s_setprio 0
	ds_read_b128 v[148:151], v147
	ds_read_b128 v[152:155], v147 offset:1024
	ds_read_b128 v[156:159], v147 offset:2048
	ds_read_b128 v[160:163], v147 offset:3072
	s_add_u32 s16, s16, 0x80000
	s_addc_u32 s17, s17, 0
	s_mov_b32 m0, s26
	v_lshl_add_u64 v[216:217], s[16:17], 0, v[136:137]
	ds_read_b128 v[168:171], v146 offset:32768
	ds_read_b128 v[172:175], v146 offset:33792
	ds_read_b128 v[176:179], v146 offset:34816
	ds_read_b128 v[180:183], v146 offset:35840
	ds_read_b128 v[184:187], v146 offset:36864
	ds_read_b128 v[188:191], v146 offset:37888
	ds_read_b128 v[192:195], v146 offset:38912
	ds_read_b128 v[212:215], v146 offset:39936
	global_load_lds_dwordx4 v[216:217], off
	v_lshl_add_u64 v[216:217], s[16:17], 0, v[132:133]
	s_mov_b32 m0, s27
	s_nop 0
	global_load_lds_dwordx4 v[216:217], off
	s_waitcnt lgkmcnt(6)
	s_setprio 1
	s_barrier
; #define PG8_WAIT_V(n) asm volatile("s_waitcnt vmcnt(" #n ")" ::: "memory")
; #define PG8_WAIT_L(n) asm volatile("s_waitcnt lgkmcnt(" #n ")" ::: "memory")
; #define PG8_BAR __builtin_amdgcn_s_barrier()
; #define PG8_SCHED __builtin_amdgcn_sched_barrier(0)
; template <class Epi, class AddrA, class AddrB>
; __device__ __forceinline__ void gemm_phase(const Sched S, const int lda, const int ldb, const int K, const AddrA addrA,
;                                            const AddrB addrB, const Epi E) {
;     ...
;       PG8_LDB(B0, 1, 0); PG8_SCHED; PG8_LDA(At, 1, 0); PG8_STAGE(PG8_SA(0, 1), a2 + hstepA, voffA);
;       PG8_WAIT_L(8); PG8_BAR; PG8_WAIT_L(0); PG8_MMA(0, 0, At, B0); PG8_BAR; PG8_SCHED;
;       PG8_LDB(B1, 1, 1); PG8_STAGE(PG8_SB(1, 0), b3, voffB);
;       PG8_BAR; PG8_WAIT_L(0); PG8_MMA(0, 1, At, B1); PG8_BAR;
;       PG8_LDA(At, 1, 1); PG8_STAGE(PG8_SA(1, 0), a3, voffA);
;       PG8_BAR; PG8_WAIT_L(0); PG8_MMA(1, 0, At, B0); PG8_BAR; PG8_SCHED;
;       PG8_STAGE(PG8_SB(1, 1), b3 + hstepB, voffB);
;       PG8_WAIT_V(6); PG8_BAR; PG8_MMA(1, 1, At, B1); PG8_BAR;
	v_mfma_f32_16x16x32_bf16 v[128:131], v[148:151], v[168:171], v[128:131]
	v_mfma_f32_16x16x32_bf16 v[128:131], v[152:155], v[172:175], v[128:131]
	s_waitcnt lgkmcnt(0)
	v_mfma_f32_16x16x32_bf16 v[120:123], v[148:151], v[176:179], v[120:123]
	v_mfma_f32_16x16x32_bf16 v[120:123], v[152:155], v[180:183], v[120:123]
	v_mfma_f32_16x16x32_bf16 v[104:107], v[148:151], v[184:187], v[104:107]
	v_mfma_f32_16x16x32_bf16 v[104:107], v[152:155], v[188:191], v[104:107]
	v_mfma_f32_16x16x32_bf16 v[88:91], v[148:151], v[192:195], v[88:91]
	v_mfma_f32_16x16x32_bf16 v[88:91], v[152:155], v[212:215], v[88:91]
	v_mfma_f32_16x16x32_bf16 v[124:127], v[156:159], v[168:171], v[124:127]
	v_mfma_f32_16x16x32_bf16 v[124:127], v[160:163], v[172:175], v[124:127]
	v_mfma_f32_16x16x32_bf16 v[112:115], v[156:159], v[176:179], v[112:115]
	v_mfma_f32_16x16x32_bf16 v[112:115], v[160:163], v[180:183], v[112:115]
	v_mfma_f32_16x16x32_bf16 v[96:99], v[156:159], v[184:187], v[96:99]
	v_mfma_f32_16x16x32_bf16 v[96:99], v[160:163], v[188:191], v[96:99]
	v_mfma_f32_16x16x32_bf16 v[80:83], v[156:159], v[192:195], v[80:83]
	v_mfma_f32_16x16x32_bf16 v[80:83], v[160:163], v[212:215], v[80:83]
	s_barrier
	s_setprio 0
	s_add_i32 s16, 0, 0x1c000
	s_add_i32 s17, s40, s19
	v_add_u32_e32 v147, s16, v145
	v_lshl_add_u64 v[142:143], v[142:143], 0, s[52:53]
	s_mov_b32 m0, s17
	ds_read_b128 v[216:219], v147
	ds_read_b128 v[220:223], v147 offset:1024
	ds_read_b128 v[224:227], v147 offset:2048
	ds_read_b128 v[228:231], v147 offset:3072
	global_load_lds_dwordx4 v[142:143], off
	v_lshl_add_u64 v[142:143], v[196:197], 0, s[52:53]
	s_add_i32 m0, s17, 0x2000
	s_nop 0
	global_load_lds_dwordx4 v[142:143], off
	s_mov_b32 m0, s30
	v_lshl_add_u64 v[142:143], v[232:233], 0, s[52:53]
	s_waitcnt vmcnt(10)
	s_waitcnt lgkmcnt(0)
	s_setprio 1
	s_barrier
	v_mfma_f32_16x16x32_bf16 v[116:119], v[216:219], v[168:171], v[116:119]
	v_mfma_f32_16x16x32_bf16 v[116:119], v[220:223], v[172:175], v[116:119]
	s_waitcnt lgkmcnt(0)
	v_mfma_f32_16x16x32_bf16 v[100:103], v[216:219], v[176:179], v[100:103]
	v_mfma_f32_16x16x32_bf16 v[100:103], v[220:223], v[180:183], v[100:103]
	v_mfma_f32_16x16x32_bf16 v[84:87], v[216:219], v[184:187], v[84:87]
	v_mfma_f32_16x16x32_bf16 v[84:87], v[220:223], v[188:191], v[84:87]
	v_mfma_f32_16x16x32_bf16 v[72:75], v[216:219], v[192:195], v[72:75]
	v_mfma_f32_16x16x32_bf16 v[72:75], v[220:223], v[212:215], v[72:75]
	v_mfma_f32_16x16x32_bf16 v[108:111], v[224:227], v[168:171], v[108:111]
	v_mfma_f32_16x16x32_bf16 v[108:111], v[228:231], v[172:175], v[108:111]
	v_mfma_f32_16x16x32_bf16 v[92:95], v[224:227], v[176:179], v[92:95]
	v_mfma_f32_16x16x32_bf16 v[92:95], v[228:231], v[180:183], v[92:95]
	v_mfma_f32_16x16x32_bf16 v[76:79], v[224:227], v[184:187], v[76:79]
	v_mfma_f32_16x16x32_bf16 v[76:79], v[228:231], v[188:191], v[76:79]
	v_mfma_f32_16x16x32_bf16 v[68:71], v[224:227], v[192:195], v[68:71]
	v_mfma_f32_16x16x32_bf16 v[68:71], v[228:231], v[212:215], v[68:71]
	s_barrier
	s_setprio 0
	ds_read_b128 v[168:171], v146 offset:49152
	ds_read_b128 v[172:175], v146 offset:50176
	ds_read_b128 v[176:179], v146 offset:51200
	ds_read_b128 v[180:183], v146 offset:52224
	ds_read_b128 v[184:187], v146 offset:53248
	ds_read_b128 v[188:191], v146 offset:54272
	ds_read_b128 v[192:195], v146 offset:55296
	ds_read_b128 v[212:215], v146 offset:56320
	global_load_lds_dwordx4 v[142:143], off
	v_lshl_add_u64 v[142:143], v[234:235], 0, s[52:53]
	s_mov_b32 m0, s31
	s_nop 0
	global_load_lds_dwordx4 v[142:143], off
	s_add_u32 s14, s14, 0x80080
	s_addc_u32 s15, s15, 0
	s_add_i32 s16, s16, s19
	v_lshl_add_u64 v[142:143], s[14:15], 0, v[134:135]
	s_mov_b32 m0, s16
	s_nop 0
	global_load_lds_dwordx4 v[142:143], off
	v_lshl_add_u64 v[142:143], s[14:15], 0, v[0:1]
	s_add_i32 m0, s16, 0x2000
	s_nop 0
	global_load_lds_dwordx4 v[142:143], off
	s_add_i32 s39, s39, 2
	s_add_u32 s37, s37, 0x100
	s_addc_u32 s38, s38, 0
	s_add_u32 s12, s12, 0x100
	s_addc_u32 s13, s13, 0
	s_waitcnt vmcnt(8)
	s_waitcnt lgkmcnt(0)
	s_setprio 1
	s_barrier
	v_mfma_f32_16x16x32_bf16 v[64:67], v[148:151], v[168:171], v[64:67]
	v_mfma_f32_16x16x32_bf16 v[64:67], v[152:155], v[172:175], v[64:67]
	s_waitcnt lgkmcnt(0)
	v_mfma_f32_16x16x32_bf16 v[56:59], v[148:151], v[176:179], v[56:59]
	v_mfma_f32_16x16x32_bf16 v[56:59], v[152:155], v[180:183], v[56:59]
	v_mfma_f32_16x16x32_bf16 v[40:43], v[148:151], v[184:187], v[40:43]
	v_mfma_f32_16x16x32_bf16 v[40:43], v[152:155], v[188:191], v[40:43]
	v_mfma_f32_16x16x32_bf16 v[24:27], v[148:151], v[192:195], v[24:27]
	v_mfma_f32_16x16x32_bf16 v[24:27], v[152:155], v[212:215], v[24:27]
	v_mfma_f32_16x16x32_bf16 v[60:63], v[156:159], v[168:171], v[60:63]
	v_mfma_f32_16x16x32_bf16 v[60:63], v[160:163], v[172:175], v[60:63]
	v_mfma_f32_16x16x32_bf16 v[48:51], v[156:159], v[176:179], v[48:51]
	v_mfma_f32_16x16x32_bf16 v[48:51], v[160:163], v[180:183], v[48:51]
	v_mfma_f32_16x16x32_bf16 v[32:35], v[156:159], v[184:187], v[32:35]
	v_mfma_f32_16x16x32_bf16 v[32:35], v[160:163], v[188:191], v[32:35]
	v_mfma_f32_16x16x32_bf16 v[16:19], v[156:159], v[192:195], v[16:19]
	v_mfma_f32_16x16x32_bf16 v[16:19], v[160:163], v[212:215], v[16:19]
	v_mfma_f32_16x16x32_bf16 v[52:55], v[216:219], v[168:171], v[52:55]
	v_mfma_f32_16x16x32_bf16 v[52:55], v[220:223], v[172:175], v[52:55]
	v_mfma_f32_16x16x32_bf16 v[36:39], v[216:219], v[176:179], v[36:39]
	v_mfma_f32_16x16x32_bf16 v[36:39], v[220:223], v[180:183], v[36:39]
	v_mfma_f32_16x16x32_bf16 v[20:23], v[216:219], v[184:187], v[20:23]
	v_mfma_f32_16x16x32_bf16 v[20:23], v[220:223], v[188:191], v[20:23]
	v_mfma_f32_16x16x32_bf16 v[8:11], v[216:219], v[192:195], v[8:11]
	v_mfma_f32_16x16x32_bf16 v[8:11], v[220:223], v[212:215], v[8:11]
	v_mfma_f32_16x16x32_bf16 v[44:47], v[224:227], v[168:171], v[44:47]
	v_mfma_f32_16x16x32_bf16 v[44:47], v[228:231], v[172:175], v[44:47]
	v_mfma_f32_16x16x32_bf16 v[28:31], v[224:227], v[176:179], v[28:31]
	v_mfma_f32_16x16x32_bf16 v[28:31], v[228:231], v[180:183], v[28:31]
	v_mfma_f32_16x16x32_bf16 v[12:15], v[224:227], v[184:187], v[12:15]
	v_mfma_f32_16x16x32_bf16 v[12:15], v[228:231], v[188:191], v[12:15]
	v_mfma_f32_16x16x32_bf16 v[4:7], v[224:227], v[192:195], v[4:7]
	v_mfma_f32_16x16x32_bf16 v[4:7], v[228:231], v[212:215], v[4:7]
	s_barrier
; #define PG8_WAIT_V(n) asm volatile("s_waitcnt vmcnt(" #n ")" ::: "memory")
; #define PG8_BAR __builtin_amdgcn_s_barrier()
; template <class Epi, class AddrA, class AddrB>
; __device__ __forceinline__ void gemm_phase(const Sched S, const int lda, const int ldb, const int K, const AddrA addrA,
;                                            const AddrB addrB, const Epi E) {
;     ...
;     E(acc, cur, wr, wc, fr, fq);
;     if (!has_next) break;
;     if (!(Epi::KEEP && cur.br + 1 < S.nbr)) {
; #pragma unroll
;       for (int a = 0; a < 2; ++a)
; #pragma unroll
;         for (int b = 0; b < 2; ++b)
; #pragma unroll
;           for (int m = 0; m < 4; ++m)
; #pragma unroll
;             for (int n = 0; n < 2; ++n) acc[a][b][m][n] = (f32x4){0.f, 0.f, 0.f, 0.f};
;     }
;     cur = nxt; cA = nA; cB = nB; ++ui;
;   }
;   PG8_WAIT_V(0);
;   if (wr == 0) PG8_BAR;
;   PG8_BAR;
;   __device__ __forceinline__ void operator()(EPI_ARGS) const {
;     bf16_t* base = proj + ((size_t)u.pn * MTOK + (size_t)(u.pm * 256 + wr * 64 + fr)) * PLD + wc * 32 + 8 * fq;
; #pragma unroll
;     for (int ai = 0; ai < 2; ++ai)
; #pragma unroll
;       for (int m = 0; m < 4; ++m) {
;         bf16_t* rowp = base + (size_t)(ai * HALF + m * 16) * PLD;
; #pragma unroll
;         for (int bj = 0; bj < 2; ++bj) {
;           const f32x4 v0 = acc[ai][bj][m][0], v1 = acc[ai][bj][m][1];
;           u32x4 o;
;           o.x = pack2(v0[0], v0[1]); o.y = pack2(v0[2], v0[3]); o.z = pack2(v1[0], v1[1]); o.w = pack2(v1[2], v1[3]);
;           *(u32x4*)(rowp + bj * HALF) = o;
;         }
;       }
;   }
	s_setprio 0
	s_cmp_gt_u32 s39, 29
	s_cbranch_scc0 .LBB0_109
	s_ashr_i32 s11, s10, 31
	v_lshl_add_u32 v142, s35, 8, v144
	s_lshl_b64 s[10:11], s[10:11], 23
	v_ashrrev_i32_e32 v143, 31, v142
	s_add_u32 s10, s28, s10
	s_addc_u32 s11, s29, s11
	v_lshlrev_b64 v[142:143], 9, v[142:143]
	v_lshl_add_u64 v[142:143], s[10:11], 0, v[142:143]
	v_lshl_add_u64 v[142:143], v[142:143], 0, s[72:73]
	v_lshl_add_u64 v[142:143], v[142:143], 0, v[2:3]
	v_cvt_pk_bf16_f32 v116, v116, v117
	v_cvt_pk_bf16_f32 v117, v118, v119
	v_cvt_pk_bf16_f32 v119, v110, v111
	v_cvt_pk_bf16_f32 v110, v112, v113
	v_add_co_u32_e32 v112, vcc, s96, v142
	s_movk_i32 s1, 0x4000
	s_nop 0
	v_addc_co_u32_e32 v113, vcc, 0, v143, vcc
	v_cvt_pk_bf16_f32 v100, v100, v101
	v_cvt_pk_bf16_f32 v101, v102, v103
	v_cvt_pk_bf16_f32 v103, v94, v95
	v_cvt_pk_bf16_f32 v94, v96, v97
	v_add_co_u32_e32 v96, vcc, s1, v142
	s_movk_i32 s1, 0x6000
	s_nop 0
	v_addc_co_u32_e32 v97, vcc, 0, v143, vcc
	v_cvt_pk_bf16_f32 v84, v84, v85
	v_cvt_pk_bf16_f32 v85, v86, v87
	v_cvt_pk_bf16_f32 v87, v78, v79
	v_cvt_pk_bf16_f32 v78, v80, v81
	v_add_co_u32_e32 v80, vcc, s1, v142
	v_cvt_pk_bf16_f32 v64, v64, v65
	v_cvt_pk_bf16_f32 v65, v66, v67
	v_cvt_pk_bf16_f32 v66, v60, v61
	s_mov_b32 s1, 0x12000
	s_nop 0
	v_addc_co_u32_e32 v81, vcc, 0, v143, vcc
	v_add_co_u32_e32 v60, vcc, s67, v142
	v_cvt_pk_bf16_f32 v52, v52, v53
	v_cvt_pk_bf16_f32 v53, v54, v55
	v_cvt_pk_bf16_f32 v55, v46, v47
	v_cvt_pk_bf16_f32 v46, v48, v49
	s_nop 1
	v_addc_co_u32_e32 v61, vcc, 0, v143, vcc
	v_add_co_u32_e32 v48, vcc, s1, v142
	s_mov_b32 s1, 0x14000
	s_nop 0
	v_addc_co_u32_e32 v49, vcc, 0, v143, vcc
	v_cvt_pk_bf16_f32 v36, v36, v37
	v_cvt_pk_bf16_f32 v37, v38, v39
	v_cvt_pk_bf16_f32 v39, v30, v31
	v_cvt_pk_bf16_f32 v30, v32, v33
	v_add_co_u32_e32 v32, vcc, s1, v142
	s_mov_b32 s1, 0x16000
	s_nop 0
	v_addc_co_u32_e32 v33, vcc, 0, v143, vcc
	v_cvt_pk_bf16_f32 v20, v20, v21
	v_cvt_pk_bf16_f32 v21, v22, v23
	v_cvt_pk_bf16_f32 v23, v14, v15
	v_cvt_pk_bf16_f32 v14, v16, v17
	v_add_co_u32_e32 v16, vcc, s1, v142
	s_mov_b32 s10, s2
	s_nop 0
	v_addc_co_u32_e32 v17, vcc, 0, v143, vcc
	s_and_b64 vcc, exec, s[4:5]
	s_mov_b32 s35, s0
	s_mov_b64 s[12:13], s[8:9]
	s_mov_b64 s[14:15], s[6:7]
	v_cvt_pk_bf16_f32 v128, v128, v129
	v_cvt_pk_bf16_f32 v129, v130, v131
	v_cvt_pk_bf16_f32 v130, v124, v125
	v_cvt_pk_bf16_f32 v131, v126, v127
	flat_store_dwordx4 v[142:143], v[128:131]
	v_cvt_pk_bf16_f32 v118, v108, v109
	flat_store_dwordx4 v[142:143], v[116:119] offset:256
	v_cvt_pk_bf16_f32 v108, v120, v121
	v_cvt_pk_bf16_f32 v109, v122, v123
	v_cvt_pk_bf16_f32 v111, v114, v115
	flat_store_dwordx4 v[112:113], v[108:111]
	v_cvt_pk_bf16_f32 v102, v92, v93
	flat_store_dwordx4 v[112:113], v[100:103] offset:256
	v_cvt_pk_bf16_f32 v92, v104, v105
	v_cvt_pk_bf16_f32 v93, v106, v107
	v_cvt_pk_bf16_f32 v95, v98, v99
	flat_store_dwordx4 v[96:97], v[92:95]
	v_cvt_pk_bf16_f32 v86, v76, v77
	flat_store_dwordx4 v[96:97], v[84:87] offset:256
	v_cvt_pk_bf16_f32 v76, v88, v89
	v_cvt_pk_bf16_f32 v77, v90, v91
	v_cvt_pk_bf16_f32 v79, v82, v83
	flat_store_dwordx4 v[80:81], v[76:79]
	v_cvt_pk_bf16_f32 v72, v72, v73
	v_cvt_pk_bf16_f32 v73, v74, v75
	v_cvt_pk_bf16_f32 v74, v68, v69
	v_cvt_pk_bf16_f32 v75, v70, v71
	flat_store_dwordx4 v[80:81], v[72:75] offset:256
	v_cvt_pk_bf16_f32 v67, v62, v63
	flat_store_dwordx4 v[60:61], v[64:67]
	v_cvt_pk_bf16_f32 v54, v44, v45
	flat_store_dwordx4 v[60:61], v[52:55] offset:256
	v_cvt_pk_bf16_f32 v44, v56, v57
	v_cvt_pk_bf16_f32 v45, v58, v59
	v_cvt_pk_bf16_f32 v47, v50, v51
	flat_store_dwordx4 v[48:49], v[44:47]
	v_cvt_pk_bf16_f32 v38, v28, v29
	flat_store_dwordx4 v[48:49], v[36:39] offset:256
	v_cvt_pk_bf16_f32 v28, v40, v41
	v_cvt_pk_bf16_f32 v29, v42, v43
	v_cvt_pk_bf16_f32 v31, v34, v35
	flat_store_dwordx4 v[32:33], v[28:31]
	v_cvt_pk_bf16_f32 v22, v12, v13
	flat_store_dwordx4 v[32:33], v[20:23] offset:256
	v_cvt_pk_bf16_f32 v12, v24, v25
	v_cvt_pk_bf16_f32 v13, v26, v27
	v_cvt_pk_bf16_f32 v15, v18, v19
	flat_store_dwordx4 v[16:17], v[12:15]
	v_cvt_pk_bf16_f32 v8, v8, v9
	v_cvt_pk_bf16_f32 v9, v10, v11
	v_cvt_pk_bf16_f32 v10, v4, v5
	v_cvt_pk_bf16_f32 v11, v6, v7
	flat_store_dwordx4 v[16:17], v[8:11] offset:256
	s_cbranch_vccz .LBB0_106
	s_waitcnt vmcnt(0)
	s_cmpk_gt_u32 s18, 0xff
	s_cbranch_scc1 .LBB0_113
	s_barrier

; #define PG8_WAIT_V(n) asm volatile("s_waitcnt vmcnt(" #n ")" ::: "memory")
; #define PG8_WAIT_L(n) asm volatile("s_waitcnt lgkmcnt(" #n ")" ::: "memory")
; #define PG8_BAR __builtin_amdgcn_s_barrier()
; #define PG8_SCHED __builtin_amdgcn_sched_barrier(0)
; template <class Epi, class AddrA, class AddrB>
; __device__ __forceinline__ void gemm_phase(const Sched S, const int lda, const int ldb, const int K, const AddrA addrA,
;                                            const AddrB addrB, const Epi E) {
;     ...
;     for (int t = 0; t < nt; t += 2) {
;       const bool last = (t == nt - 2);
;       const char* a1 = cA + (size_t)(t + 1) * kstep;
;       const char* a2 = last ? nA : cA + (size_t)(t + 2) * kstep;
;       const char* b2 = last ? nB : cB + (size_t)(t + 2) * kstep;
;       const char* a3 = a2 + kstep;
;       const char* b3 = b2 + kstep;
;       PG8_LDB(B0, 0, 0); PG8_SCHED; PG8_LDA(At, 0, 0); PG8_STAGE(PG8_SA(1, 1), a1 + hstepA, voffA);
;       PG8_WAIT_L(8); PG8_BAR; PG8_WAIT_L(0); PG8_MMA(0, 0, At, B0); PG8_BAR; PG8_SCHED;
;       PG8_LDB(B1, 0, 1); PG8_STAGE(PG8_SB(0, 0), b2, voffB);
;       PG8_BAR; PG8_WAIT_L(0); PG8_MMA(0, 1, At, B1); PG8_BAR;
;       PG8_LDA(At, 0, 1); PG8_STAGE(PG8_SA(0, 0), a2, voffA);
;       PG8_BAR; PG8_WAIT_L(0); PG8_MMA(1, 0, At, B0); PG8_BAR; PG8_SCHED;
;       PG8_STAGE(PG8_SB(0, 1), b2 + hstepB, voffB);
;       PG8_WAIT_V(6); PG8_BAR; PG8_MMA(1, 1, At, B1); PG8_BAR;
.LBB0_484:
	s_ashr_i32 s15, s14, 31
	s_lshl_b64 s[20:21], s[14:15], 20
	s_add_u32 s3, s25, s20
	s_addc_u32 s15, s26, s21
	s_lshl_b32 s17, s16, 8
	s_and_b32 s20, s17, 0xfffffe00
	s_ashr_i32 s21, s20, 31
	s_lshl_b64 s[20:21], s[20:21], 1
	s_add_u32 s20, s3, s20
	s_addc_u32 s21, s15, s21
	s_and_b64 s[22:23], s[10:11], exec
	s_cselect_b32 s3, s21, s7
	s_cselect_b32 s15, s20, s6
	s_ashr_i32 s17, s16, 31
	s_lshl_b64 s[22:23], s[16:17], 18
	s_add_u32 s22, s27, s22
	s_addc_u32 s23, s28, s23
	s_and_b64 s[10:11], s[10:11], exec
	s_cselect_b32 s17, s23, s5
	s_cselect_b32 s40, s22, s4
	s_add_u32 s41, s4, 0x100
	s_addc_u32 s42, s5, 0
	s_add_u32 s4, s6, 0x80080
	s_addc_u32 s5, s7, 0
	s_mov_b32 s43, -2
	s_add_i32 s44, 0, 0x10000
	v_add_u32_e32 v2, s44, v167
	ds_read_b128 v[92:95], v2
	ds_read_b128 v[100:103], v2 offset:1024
	ds_read_b128 v[132:135], v2 offset:2048
	ds_read_b128 v[144:147], v2 offset:3072
	v_lshl_add_u64 v[196:197], s[4:5], 0, v[172:173]
	s_add_i32 m0, s30, 0xc000
	ds_read_b128 v[148:151], v169
	ds_read_b128 v[152:155], v169 offset:1024
	ds_read_b128 v[176:179], v169 offset:2048
	ds_read_b128 v[180:183], v169 offset:3072
	ds_read_b128 v[184:187], v169 offset:4096
	ds_read_b128 v[188:191], v169 offset:5120
	ds_read_b128 v[192:195], v169 offset:6144
	ds_read_b128 v[212:215], v169 offset:7168
	global_load_lds_dwordx4 v[196:197], off
	v_lshl_add_u64 v[196:197], s[4:5], 0, v[170:171]
	s_add_i32 m0, s30, 0xe000
	s_nop 0
	global_load_lds_dwordx4 v[196:197], off
	s_waitcnt lgkmcnt(6)
	s_setprio 1
	s_barrier
	v_mfma_f32_16x16x32_bf16 v[140:143], v[92:95], v[148:151], 0
	v_mfma_f32_16x16x32_bf16 v[140:143], v[100:103], v[152:155], v[140:143]
	s_waitcnt lgkmcnt(0)
	v_mfma_f32_16x16x32_bf16 v[128:131], v[92:95], v[176:179], 0
	v_mfma_f32_16x16x32_bf16 v[128:131], v[100:103], v[180:183], v[128:131]
	v_mfma_f32_16x16x32_bf16 v[120:123], v[92:95], v[184:187], 0
	v_mfma_f32_16x16x32_bf16 v[120:123], v[100:103], v[188:191], v[120:123]
	v_mfma_f32_16x16x32_bf16 v[112:115], v[92:95], v[192:195], 0
	v_mfma_f32_16x16x32_bf16 v[112:115], v[100:103], v[212:215], v[112:115]
	v_mfma_f32_16x16x32_bf16 v[136:139], v[132:135], v[148:151], 0
	v_mfma_f32_16x16x32_bf16 v[136:139], v[144:147], v[152:155], v[136:139]
	v_mfma_f32_16x16x32_bf16 v[124:127], v[132:135], v[176:179], 0
	v_mfma_f32_16x16x32_bf16 v[124:127], v[144:147], v[180:183], v[124:127]
	v_mfma_f32_16x16x32_bf16 v[116:119], v[132:135], v[184:187], 0
	v_mfma_f32_16x16x32_bf16 v[116:119], v[144:147], v[188:191], v[116:119]
	v_mfma_f32_16x16x32_bf16 v[108:111], v[132:135], v[192:195], 0
	v_mfma_f32_16x16x32_bf16 v[108:111], v[144:147], v[212:215], v[108:111]
	s_barrier
	s_setprio 0
	s_add_u32 s6, s4, 0xfff80080
	s_addc_u32 s7, s5, -1
	s_cmp_eq_u32 s43, 4
	s_cselect_b32 s11, s3, s7
	s_cselect_b32 s10, s15, s6
	s_cselect_b32 s7, s17, s42
	s_cselect_b32 s6, s40, s41
	s_add_i32 s46, 0, 0x14000
	s_add_i32 s44, s44, s29
	v_add_u32_e32 v2, s46, v167
	v_lshl_add_u64 v[196:197], s[6:7], 0, v[158:159]
	s_mov_b32 m0, s44
	ds_read_b128 v[216:219], v2
	ds_read_b128 v[220:223], v2 offset:1024
	ds_read_b128 v[224:227], v2 offset:2048
	ds_read_b128 v[228:231], v2 offset:3072
	global_load_lds_dwordx4 v[196:197], off
	v_lshl_add_u64 v[232:233], s[6:7], 0, v[0:1]
	s_add_i32 m0, s44, 0x2000
	s_nop 0
	global_load_lds_dwordx4 v[232:233], off
	s_mov_b32 m0, s30
	v_lshl_add_u64 v[234:235], s[10:11], 0, v[160:161]
	s_waitcnt vmcnt(10)
	s_waitcnt lgkmcnt(0)
	s_setprio 1
	s_barrier
	v_mfma_f32_16x16x32_bf16 v[64:67], v[216:219], v[148:151], 0
	v_mfma_f32_16x16x32_bf16 v[64:67], v[220:223], v[152:155], v[64:67]
	s_waitcnt lgkmcnt(0)
	v_mfma_f32_16x16x32_bf16 v[56:59], v[216:219], v[176:179], 0
	v_mfma_f32_16x16x32_bf16 v[56:59], v[220:223], v[180:183], v[56:59]
	v_mfma_f32_16x16x32_bf16 v[48:51], v[216:219], v[184:187], 0
	v_mfma_f32_16x16x32_bf16 v[48:51], v[220:223], v[188:191], v[48:51]
	v_mfma_f32_16x16x32_bf16 v[40:43], v[216:219], v[192:195], 0
	v_mfma_f32_16x16x32_bf16 v[40:43], v[220:223], v[212:215], v[40:43]
	v_mfma_f32_16x16x32_bf16 v[60:63], v[224:227], v[148:151], 0
	v_mfma_f32_16x16x32_bf16 v[60:63], v[228:231], v[152:155], v[60:63]
	v_mfma_f32_16x16x32_bf16 v[52:55], v[224:227], v[176:179], 0
	v_mfma_f32_16x16x32_bf16 v[52:55], v[228:231], v[180:183], v[52:55]
	v_mfma_f32_16x16x32_bf16 v[44:47], v[224:227], v[184:187], 0
	v_mfma_f32_16x16x32_bf16 v[44:47], v[228:231], v[188:191], v[44:47]
	v_mfma_f32_16x16x32_bf16 v[36:39], v[224:227], v[192:195], 0
	v_mfma_f32_16x16x32_bf16 v[36:39], v[228:231], v[212:215], v[36:39]
	s_barrier
	s_setprio 0
	ds_read_b128 v[148:151], v169 offset:16384
	ds_read_b128 v[152:155], v169 offset:17408
	ds_read_b128 v[176:179], v169 offset:18432
	ds_read_b128 v[180:183], v169 offset:19456
	ds_read_b128 v[184:187], v169 offset:20480
	ds_read_b128 v[188:191], v169 offset:21504
	ds_read_b128 v[192:195], v169 offset:22528
	ds_read_b128 v[212:215], v169 offset:23552
	global_load_lds_dwordx4 v[234:235], off
	v_lshl_add_u64 v[236:237], s[10:11], 0, v[156:157]
	s_mov_b32 m0, s31
	s_nop 0
	global_load_lds_dwordx4 v[236:237], off
	s_add_u32 s44, s6, 0x20000
	s_addc_u32 s45, s7, 0
	s_add_i32 s46, s46, s29
	v_lshl_add_u64 v[246:247], s[44:45], 0, v[158:159]
	s_mov_b32 m0, s46
	s_nop 0
	global_load_lds_dwordx4 v[246:247], off
	v_lshl_add_u64 v[246:247], s[44:45], 0, v[0:1]
	s_add_i32 m0, s46, 0x2000
	s_nop 0
	global_load_lds_dwordx4 v[246:247], off
	s_add_i32 s44, 0, 0x18000
	v_add_u32_e32 v2, s44, v167
	s_waitcnt vmcnt(8)
	s_waitcnt lgkmcnt(0)
	s_setprio 1
	s_barrier
; #define PG8_WAIT_V(n) asm volatile("s_waitcnt vmcnt(" #n ")" ::: "memory")
; #define PG8_WAIT_L(n) asm volatile("s_waitcnt lgkmcnt(" #n ")" ::: "memory")
; #define PG8_BAR __builtin_amdgcn_s_barrier()
; #define PG8_SCHED __builtin_amdgcn_sched_barrier(0)
; template <class Epi, class AddrA, class AddrB>
; __device__ __forceinline__ void gemm_phase(const Sched S, const int lda, const int ldb, const int K, const AddrA addrA,
;                                            const AddrB addrB, const Epi E) {
;     ...
;       PG8_LDB(B0, 0, 0); PG8_SCHED; PG8_LDA(At, 0, 0); PG8_STAGE(PG8_SA(1, 1), a1 + hstepA, voffA);
;       PG8_WAIT_L(8); PG8_BAR; PG8_WAIT_L(0); PG8_MMA(0, 0, At, B0); PG8_BAR; PG8_SCHED;
;       PG8_LDB(B1, 0, 1); PG8_STAGE(PG8_SB(0, 0), b2, voffB);
;       PG8_BAR; PG8_WAIT_L(0); PG8_MMA(0, 1, At, B1); PG8_BAR;
;       PG8_LDA(At, 0, 1); PG8_STAGE(PG8_SA(0, 0), a2, voffA);
;       PG8_BAR; PG8_WAIT_L(0); PG8_MMA(1, 0, At, B0); PG8_BAR; PG8_SCHED;
;       PG8_STAGE(PG8_SB(0, 1), b2 + hstepB, voffB);
;       PG8_WAIT_V(6); PG8_BAR; PG8_MMA(1, 1, At, B1); PG8_BAR;
;       PG8_LDB(B0, 1, 0); PG8_SCHED; PG8_LDA(At, 1, 0); PG8_STAGE(PG8_SA(0, 1), a2 + hstepA, voffA);
;       PG8_WAIT_L(8); PG8_BAR; PG8_WAIT_L(0); PG8_MMA(0, 0, At, B0); PG8_BAR; PG8_SCHED;
;       PG8_LDB(B1, 1, 1); PG8_STAGE(PG8_SB(1, 0), b3, voffB);
;       PG8_BAR; PG8_WAIT_L(0); PG8_MMA(0, 1, At, B1); PG8_BAR;
;       PG8_LDA(At, 1, 1); PG8_STAGE(PG8_SA(1, 0), a3, voffA);
;       PG8_BAR; PG8_WAIT_L(0); PG8_MMA(1, 0, At, B0); PG8_BAR; PG8_SCHED;
;       PG8_STAGE(PG8_SB(1, 1), b3 + hstepB, voffB);
;       PG8_WAIT_V(6); PG8_BAR; PG8_MMA(1, 1, At, B1); PG8_BAR;
	v_mfma_f32_16x16x32_bf16 v[104:107], v[92:95], v[148:151], 0
	v_mfma_f32_16x16x32_bf16 v[104:107], v[100:103], v[152:155], v[104:107]
	s_waitcnt lgkmcnt(0)
	v_mfma_f32_16x16x32_bf16 v[88:91], v[92:95], v[176:179], 0
	v_mfma_f32_16x16x32_bf16 v[88:91], v[100:103], v[180:183], v[88:91]
	v_mfma_f32_16x16x32_bf16 v[80:83], v[92:95], v[184:187], 0
	v_mfma_f32_16x16x32_bf16 v[80:83], v[100:103], v[188:191], v[80:83]
	v_mfma_f32_16x16x32_bf16 v[72:75], v[92:95], v[192:195], 0
	v_mfma_f32_16x16x32_bf16 v[72:75], v[100:103], v[212:215], v[72:75]
	v_mfma_f32_16x16x32_bf16 v[96:99], v[132:135], v[148:151], 0
	v_mfma_f32_16x16x32_bf16 v[96:99], v[144:147], v[152:155], v[96:99]
	v_mfma_f32_16x16x32_bf16 v[84:87], v[132:135], v[176:179], 0
	v_mfma_f32_16x16x32_bf16 v[84:87], v[144:147], v[180:183], v[84:87]
	v_mfma_f32_16x16x32_bf16 v[76:79], v[132:135], v[184:187], 0
	v_mfma_f32_16x16x32_bf16 v[76:79], v[144:147], v[188:191], v[76:79]
	v_mfma_f32_16x16x32_bf16 v[68:71], v[132:135], v[192:195], 0
	v_mfma_f32_16x16x32_bf16 v[68:71], v[144:147], v[212:215], v[68:71]
	v_mfma_f32_16x16x32_bf16 v[32:35], v[216:219], v[148:151], 0
	v_mfma_f32_16x16x32_bf16 v[32:35], v[220:223], v[152:155], v[32:35]
	v_mfma_f32_16x16x32_bf16 v[24:27], v[216:219], v[176:179], 0
	v_mfma_f32_16x16x32_bf16 v[24:27], v[220:223], v[180:183], v[24:27]
	v_mfma_f32_16x16x32_bf16 v[16:19], v[216:219], v[184:187], 0
	v_mfma_f32_16x16x32_bf16 v[16:19], v[220:223], v[188:191], v[16:19]
	v_mfma_f32_16x16x32_bf16 v[8:11], v[216:219], v[192:195], 0
	v_mfma_f32_16x16x32_bf16 v[8:11], v[220:223], v[212:215], v[8:11]
	v_mfma_f32_16x16x32_bf16 v[28:31], v[224:227], v[148:151], 0
	v_mfma_f32_16x16x32_bf16 v[28:31], v[228:231], v[152:155], v[28:31]
	v_mfma_f32_16x16x32_bf16 v[20:23], v[224:227], v[176:179], 0
	v_mfma_f32_16x16x32_bf16 v[20:23], v[228:231], v[180:183], v[20:23]
	v_mfma_f32_16x16x32_bf16 v[12:15], v[224:227], v[184:187], 0
	v_mfma_f32_16x16x32_bf16 v[12:15], v[228:231], v[188:191], v[12:15]
	v_mfma_f32_16x16x32_bf16 v[4:7], v[224:227], v[192:195], 0
	v_mfma_f32_16x16x32_bf16 v[4:7], v[228:231], v[212:215], v[4:7]
	s_barrier
	s_setprio 0
	ds_read_b128 v[92:95], v2
	ds_read_b128 v[100:103], v2 offset:1024
	ds_read_b128 v[132:135], v2 offset:2048
	ds_read_b128 v[144:147], v2 offset:3072
	s_add_u32 s10, s10, 0x80000
	s_addc_u32 s11, s11, 0
	s_mov_b32 m0, s34
	v_lshl_add_u64 v[216:217], s[10:11], 0, v[160:161]
	ds_read_b128 v[148:151], v169 offset:32768
	ds_read_b128 v[152:155], v169 offset:33792
	ds_read_b128 v[176:179], v169 offset:34816
	ds_read_b128 v[180:183], v169 offset:35840
	ds_read_b128 v[184:187], v169 offset:36864
	ds_read_b128 v[188:191], v169 offset:37888
	ds_read_b128 v[192:195], v169 offset:38912
	ds_read_b128 v[212:215], v169 offset:39936
	global_load_lds_dwordx4 v[216:217], off
	v_lshl_add_u64 v[216:217], s[10:11], 0, v[156:157]
	s_mov_b32 m0, s35
	s_nop 0
	global_load_lds_dwordx4 v[216:217], off
	s_waitcnt lgkmcnt(6)
	s_setprio 1
	s_barrier
	v_mfma_f32_16x16x32_bf16 v[140:143], v[92:95], v[148:151], v[140:143]
	v_mfma_f32_16x16x32_bf16 v[140:143], v[100:103], v[152:155], v[140:143]
	s_waitcnt lgkmcnt(0)
	v_mfma_f32_16x16x32_bf16 v[128:131], v[92:95], v[176:179], v[128:131]
	v_mfma_f32_16x16x32_bf16 v[128:131], v[100:103], v[180:183], v[128:131]
	v_mfma_f32_16x16x32_bf16 v[120:123], v[92:95], v[184:187], v[120:123]
	v_mfma_f32_16x16x32_bf16 v[120:123], v[100:103], v[188:191], v[120:123]
	v_mfma_f32_16x16x32_bf16 v[112:115], v[92:95], v[192:195], v[112:115]
	v_mfma_f32_16x16x32_bf16 v[112:115], v[100:103], v[212:215], v[112:115]
	v_mfma_f32_16x16x32_bf16 v[136:139], v[132:135], v[148:151], v[136:139]
	v_mfma_f32_16x16x32_bf16 v[136:139], v[144:147], v[152:155], v[136:139]
	v_mfma_f32_16x16x32_bf16 v[124:127], v[132:135], v[176:179], v[124:127]
	v_mfma_f32_16x16x32_bf16 v[124:127], v[144:147], v[180:183], v[124:127]
	v_mfma_f32_16x16x32_bf16 v[116:119], v[132:135], v[184:187], v[116:119]
	v_mfma_f32_16x16x32_bf16 v[116:119], v[144:147], v[188:191], v[116:119]
	v_mfma_f32_16x16x32_bf16 v[108:111], v[132:135], v[192:195], v[108:111]
	v_mfma_f32_16x16x32_bf16 v[108:111], v[144:147], v[212:215], v[108:111]
	s_barrier
	s_setprio 0
	s_add_i32 s10, 0, 0x1c000
	s_add_i32 s11, s44, s29
	v_add_u32_e32 v2, s10, v167
	v_lshl_add_u64 v[196:197], v[196:197], 0, s[52:53]
	s_mov_b32 m0, s11
	ds_read_b128 v[216:219], v2
	ds_read_b128 v[220:223], v2 offset:1024
	ds_read_b128 v[224:227], v2 offset:2048
	ds_read_b128 v[228:231], v2 offset:3072
	global_load_lds_dwordx4 v[196:197], off
	v_lshl_add_u64 v[196:197], v[232:233], 0, s[52:53]
	s_add_i32 m0, s11, 0x2000
	s_nop 0
	global_load_lds_dwordx4 v[196:197], off
	s_mov_b32 m0, s37
	v_lshl_add_u64 v[196:197], v[234:235], 0, s[52:53]
	s_waitcnt vmcnt(10)
	s_waitcnt lgkmcnt(0)
	s_setprio 1
	s_barrier
	v_mfma_f32_16x16x32_bf16 v[64:67], v[216:219], v[148:151], v[64:67]
	v_mfma_f32_16x16x32_bf16 v[64:67], v[220:223], v[152:155], v[64:67]
	s_waitcnt lgkmcnt(0)
	v_mfma_f32_16x16x32_bf16 v[56:59], v[216:219], v[176:179], v[56:59]
	v_mfma_f32_16x16x32_bf16 v[56:59], v[220:223], v[180:183], v[56:59]
	v_mfma_f32_16x16x32_bf16 v[48:51], v[216:219], v[184:187], v[48:51]
	v_mfma_f32_16x16x32_bf16 v[48:51], v[220:223], v[188:191], v[48:51]
	v_mfma_f32_16x16x32_bf16 v[40:43], v[216:219], v[192:195], v[40:43]
	v_mfma_f32_16x16x32_bf16 v[40:43], v[220:223], v[212:215], v[40:43]
	v_mfma_f32_16x16x32_bf16 v[60:63], v[224:227], v[148:151], v[60:63]
	v_mfma_f32_16x16x32_bf16 v[60:63], v[228:231], v[152:155], v[60:63]
	v_mfma_f32_16x16x32_bf16 v[52:55], v[224:227], v[176:179], v[52:55]
	v_mfma_f32_16x16x32_bf16 v[52:55], v[228:231], v[180:183], v[52:55]
	v_mfma_f32_16x16x32_bf16 v[44:47], v[224:227], v[184:187], v[44:47]
	v_mfma_f32_16x16x32_bf16 v[44:47], v[228:231], v[188:191], v[44:47]
	v_mfma_f32_16x16x32_bf16 v[36:39], v[224:227], v[192:195], v[36:39]
	v_mfma_f32_16x16x32_bf16 v[36:39], v[228:231], v[212:215], v[36:39]
	s_barrier
; #define PG8_WAIT_V(n) asm volatile("s_waitcnt vmcnt(" #n ")" ::: "memory")
; #define PG8_WAIT_L(n) asm volatile("s_waitcnt lgkmcnt(" #n ")" ::: "memory")
; #define PG8_BAR __builtin_amdgcn_s_barrier()
; #define PG8_SCHED __builtin_amdgcn_sched_barrier(0)
; template <class Epi, class AddrA, class AddrB>
; __device__ __forceinline__ void gemm_phase(const Sched S, const int lda, const int ldb, const int K, const AddrA addrA,
;                                            const AddrB addrB, const Epi E) {
;     ...
;       PG8_LDB(B0, 0, 0); PG8_SCHED; PG8_LDA(At, 0, 0); PG8_STAGE(PG8_SA(1, 1), a1 + hstepA, voffA);
;       PG8_WAIT_L(8); PG8_BAR; PG8_WAIT_L(0); PG8_MMA(0, 0, At, B0); PG8_BAR; PG8_SCHED;
;       PG8_LDB(B1, 0, 1); PG8_STAGE(PG8_SB(0, 0), b2, voffB);
;       PG8_BAR; PG8_WAIT_L(0); PG8_MMA(0, 1, At, B1); PG8_BAR;
;       PG8_LDA(At, 0, 1); PG8_STAGE(PG8_SA(0, 0), a2, voffA);
;       PG8_BAR; PG8_WAIT_L(0); PG8_MMA(1, 0, At, B0); PG8_BAR; PG8_SCHED;
;       PG8_STAGE(PG8_SB(0, 1), b2 + hstepB, voffB);
;       PG8_WAIT_V(6); PG8_BAR; PG8_MMA(1, 1, At, B1); PG8_BAR;
;       PG8_LDB(B0, 1, 0); PG8_SCHED; PG8_LDA(At, 1, 0); PG8_STAGE(PG8_SA(0, 1), a2 + hstepA, voffA);
;       PG8_WAIT_L(8); PG8_BAR; PG8_WAIT_L(0); PG8_MMA(0, 0, At, B0); PG8_BAR; PG8_SCHED;
;       PG8_LDB(B1, 1, 1); PG8_STAGE(PG8_SB(1, 0), b3, voffB);
;       PG8_BAR; PG8_WAIT_L(0); PG8_MMA(0, 1, At, B1); PG8_BAR;
;       PG8_LDA(At, 1, 1); PG8_STAGE(PG8_SA(1, 0), a3, voffA);
;       PG8_BAR; PG8_WAIT_L(0); PG8_MMA(1, 0, At, B0); PG8_BAR; PG8_SCHED;
;       PG8_STAGE(PG8_SB(1, 1), b3 + hstepB, voffB);
;       PG8_WAIT_V(6); PG8_BAR; PG8_MMA(1, 1, At, B1); PG8_BAR;
	s_setprio 0
	ds_read_b128 v[148:151], v169 offset:49152
	ds_read_b128 v[152:155], v169 offset:50176
	ds_read_b128 v[176:179], v169 offset:51200
	ds_read_b128 v[180:183], v169 offset:52224
	ds_read_b128 v[184:187], v169 offset:53248
	ds_read_b128 v[188:191], v169 offset:54272
	ds_read_b128 v[192:195], v169 offset:55296
	ds_read_b128 v[212:215], v169 offset:56320
	global_load_lds_dwordx4 v[196:197], off
	v_lshl_add_u64 v[196:197], v[236:237], 0, s[52:53]
	s_mov_b32 m0, s38
	s_nop 0
	global_load_lds_dwordx4 v[196:197], off
	s_add_u32 s6, s6, 0x20080
	s_addc_u32 s7, s7, 0
	s_add_i32 s10, s10, s29
	v_lshl_add_u64 v[246:247], s[6:7], 0, v[158:159]
	s_mov_b32 m0, s10
	s_nop 0
	global_load_lds_dwordx4 v[246:247], off
	v_lshl_add_u64 v[246:247], s[6:7], 0, v[0:1]
	s_add_i32 m0, s10, 0x2000
	s_nop 0
	global_load_lds_dwordx4 v[246:247], off
	s_add_i32 s43, s43, 2
	s_add_u32 s41, s41, 0x100
	s_addc_u32 s42, s42, 0
	s_add_u32 s4, s4, 0x100
	s_addc_u32 s5, s5, 0
	s_waitcnt vmcnt(8)
	s_waitcnt lgkmcnt(0)
	s_setprio 1
	s_barrier
	v_mfma_f32_16x16x32_bf16 v[104:107], v[92:95], v[148:151], v[104:107]
	v_mfma_f32_16x16x32_bf16 v[104:107], v[100:103], v[152:155], v[104:107]
	s_waitcnt lgkmcnt(0)
	v_mfma_f32_16x16x32_bf16 v[88:91], v[92:95], v[176:179], v[88:91]
	v_mfma_f32_16x16x32_bf16 v[88:91], v[100:103], v[180:183], v[88:91]
	v_mfma_f32_16x16x32_bf16 v[80:83], v[92:95], v[184:187], v[80:83]
	v_mfma_f32_16x16x32_bf16 v[80:83], v[100:103], v[188:191], v[80:83]
	v_mfma_f32_16x16x32_bf16 v[72:75], v[92:95], v[192:195], v[72:75]
	v_mfma_f32_16x16x32_bf16 v[72:75], v[100:103], v[212:215], v[72:75]
	v_mfma_f32_16x16x32_bf16 v[96:99], v[132:135], v[148:151], v[96:99]
	v_mfma_f32_16x16x32_bf16 v[96:99], v[144:147], v[152:155], v[96:99]
	v_mfma_f32_16x16x32_bf16 v[84:87], v[132:135], v[176:179], v[84:87]
	v_mfma_f32_16x16x32_bf16 v[84:87], v[144:147], v[180:183], v[84:87]
	v_mfma_f32_16x16x32_bf16 v[76:79], v[132:135], v[184:187], v[76:79]
	v_mfma_f32_16x16x32_bf16 v[76:79], v[144:147], v[188:191], v[76:79]
	v_mfma_f32_16x16x32_bf16 v[68:71], v[132:135], v[192:195], v[68:71]
	v_mfma_f32_16x16x32_bf16 v[68:71], v[144:147], v[212:215], v[68:71]
	v_mfma_f32_16x16x32_bf16 v[32:35], v[216:219], v[148:151], v[32:35]
	v_mfma_f32_16x16x32_bf16 v[32:35], v[220:223], v[152:155], v[32:35]
	v_mfma_f32_16x16x32_bf16 v[24:27], v[216:219], v[176:179], v[24:27]
	v_mfma_f32_16x16x32_bf16 v[24:27], v[220:223], v[180:183], v[24:27]
	v_mfma_f32_16x16x32_bf16 v[16:19], v[216:219], v[184:187], v[16:19]
	v_mfma_f32_16x16x32_bf16 v[16:19], v[220:223], v[188:191], v[16:19]
	v_mfma_f32_16x16x32_bf16 v[8:11], v[216:219], v[192:195], v[8:11]
	v_mfma_f32_16x16x32_bf16 v[8:11], v[220:223], v[212:215], v[8:11]
	v_mfma_f32_16x16x32_bf16 v[28:31], v[224:227], v[148:151], v[28:31]
	v_mfma_f32_16x16x32_bf16 v[28:31], v[228:231], v[152:155], v[28:31]
	v_mfma_f32_16x16x32_bf16 v[20:23], v[224:227], v[176:179], v[20:23]
	v_mfma_f32_16x16x32_bf16 v[20:23], v[228:231], v[180:183], v[20:23]
	v_mfma_f32_16x16x32_bf16 v[12:15], v[224:227], v[184:187], v[12:15]
	v_mfma_f32_16x16x32_bf16 v[12:15], v[228:231], v[188:191], v[12:15]
	v_mfma_f32_16x16x32_bf16 v[4:7], v[224:227], v[192:195], v[4:7]
	v_mfma_f32_16x16x32_bf16 v[4:7], v[228:231], v[212:215], v[4:7]
	s_barrier
	s_setprio 0
	s_cmp_gt_u32 s43, 5
.LBB0_485:
	s_add_i32 s44, 0, 0x10000
	v_add_u32_e32 v2, s44, v167
	ds_read_b128 v[92:95], v2
	ds_read_b128 v[100:103], v2 offset:1024
	ds_read_b128 v[132:135], v2 offset:2048
	ds_read_b128 v[144:147], v2 offset:3072
	v_lshl_add_u64 v[196:197], s[4:5], 0, v[172:173]
	s_add_i32 m0, s30, 0xc000
	ds_read_b128 v[148:151], v169
	ds_read_b128 v[152:155], v169 offset:1024
	ds_read_b128 v[176:179], v169 offset:2048
	ds_read_b128 v[180:183], v169 offset:3072
	ds_read_b128 v[184:187], v169 offset:4096
	ds_read_b128 v[188:191], v169 offset:5120
	ds_read_b128 v[192:195], v169 offset:6144
	ds_read_b128 v[212:215], v169 offset:7168
	global_load_lds_dwordx4 v[196:197], off
	v_lshl_add_u64 v[196:197], s[4:5], 0, v[170:171]
	s_add_i32 m0, s30, 0xe000
	s_nop 0
	global_load_lds_dwordx4 v[196:197], off
	s_waitcnt lgkmcnt(6)
	s_setprio 1
	s_barrier
	v_mfma_f32_16x16x32_bf16 v[140:143], v[92:95], v[148:151], v[140:143]
	v_mfma_f32_16x16x32_bf16 v[140:143], v[100:103], v[152:155], v[140:143]
	s_waitcnt lgkmcnt(0)
	v_mfma_f32_16x16x32_bf16 v[128:131], v[92:95], v[176:179], v[128:131]
	v_mfma_f32_16x16x32_bf16 v[128:131], v[100:103], v[180:183], v[128:131]
	v_mfma_f32_16x16x32_bf16 v[120:123], v[92:95], v[184:187], v[120:123]
	v_mfma_f32_16x16x32_bf16 v[120:123], v[100:103], v[188:191], v[120:123]
	v_mfma_f32_16x16x32_bf16 v[112:115], v[92:95], v[192:195], v[112:115]
	v_mfma_f32_16x16x32_bf16 v[112:115], v[100:103], v[212:215], v[112:115]
	v_mfma_f32_16x16x32_bf16 v[136:139], v[132:135], v[148:151], v[136:139]
	v_mfma_f32_16x16x32_bf16 v[136:139], v[144:147], v[152:155], v[136:139]
	v_mfma_f32_16x16x32_bf16 v[124:127], v[132:135], v[176:179], v[124:127]
	v_mfma_f32_16x16x32_bf16 v[124:127], v[144:147], v[180:183], v[124:127]
	v_mfma_f32_16x16x32_bf16 v[116:119], v[132:135], v[184:187], v[116:119]
	v_mfma_f32_16x16x32_bf16 v[116:119], v[144:147], v[188:191], v[116:119]
	v_mfma_f32_16x16x32_bf16 v[108:111], v[132:135], v[192:195], v[108:111]
	v_mfma_f32_16x16x32_bf16 v[108:111], v[144:147], v[212:215], v[108:111]
	s_barrier
; #define PG8_WAIT_V(n) asm volatile("s_waitcnt vmcnt(" #n ")" ::: "memory")
; #define PG8_WAIT_L(n) asm volatile("s_waitcnt lgkmcnt(" #n ")" ::: "memory")
; #define PG8_BAR __builtin_amdgcn_s_barrier()
; #define PG8_SCHED __builtin_amdgcn_sched_barrier(0)
; template <class Epi, class AddrA, class AddrB>
; __device__ __forceinline__ void gemm_phase(const Sched S, const int lda, const int ldb, const int K, const AddrA addrA,
;                                            const AddrB addrB, const Epi E) {
;     ...
;       PG8_LDB(B0, 0, 0); PG8_SCHED; PG8_LDA(At, 0, 0); PG8_STAGE(PG8_SA(1, 1), a1 + hstepA, voffA);
;       PG8_WAIT_L(8); PG8_BAR; PG8_WAIT_L(0); PG8_MMA(0, 0, At, B0); PG8_BAR; PG8_SCHED;
;       PG8_LDB(B1, 0, 1); PG8_STAGE(PG8_SB(0, 0), b2, voffB);
;       PG8_BAR; PG8_WAIT_L(0); PG8_MMA(0, 1, At, B1); PG8_BAR;
;       PG8_LDA(At, 0, 1); PG8_STAGE(PG8_SA(0, 0), a2, voffA);
;       PG8_BAR; PG8_WAIT_L(0); PG8_MMA(1, 0, At, B0); PG8_BAR; PG8_SCHED;
;       PG8_STAGE(PG8_SB(0, 1), b2 + hstepB, voffB);
;       PG8_WAIT_V(6); PG8_BAR; PG8_MMA(1, 1, At, B1); PG8_BAR;
;       PG8_LDB(B0, 1, 0); PG8_SCHED; PG8_LDA(At, 1, 0); PG8_STAGE(PG8_SA(0, 1), a2 + hstepA, voffA);
;       PG8_WAIT_L(8); PG8_BAR; PG8_WAIT_L(0); PG8_MMA(0, 0, At, B0); PG8_BAR; PG8_SCHED;
;       PG8_LDB(B1, 1, 1); PG8_STAGE(PG8_SB(1, 0), b3, voffB);
;       PG8_BAR; PG8_WAIT_L(0); PG8_MMA(0, 1, At, B1); PG8_BAR;
;       PG8_LDA(At, 1, 1); PG8_STAGE(PG8_SA(1, 0), a3, voffA);
;       PG8_BAR; PG8_WAIT_L(0); PG8_MMA(1, 0, At, B0); PG8_BAR; PG8_SCHED;
;       PG8_STAGE(PG8_SB(1, 1), b3 + hstepB, voffB);
;       PG8_WAIT_V(6); PG8_BAR; PG8_MMA(1, 1, At, B1); PG8_BAR;
	s_setprio 0
	s_add_u32 s6, s4, 0xfff80080
	s_addc_u32 s7, s5, -1
	s_cmp_eq_u32 s43, 4
	s_cselect_b32 s11, s3, s7
	s_cselect_b32 s10, s15, s6
	s_cselect_b32 s7, s17, s42
	s_cselect_b32 s6, s40, s41
	s_add_i32 s46, 0, 0x14000
	s_add_i32 s44, s44, s29
	v_add_u32_e32 v2, s46, v167
	v_lshl_add_u64 v[196:197], s[6:7], 0, v[158:159]
	s_mov_b32 m0, s44
	ds_read_b128 v[216:219], v2
	ds_read_b128 v[220:223], v2 offset:1024
	ds_read_b128 v[224:227], v2 offset:2048
	ds_read_b128 v[228:231], v2 offset:3072
	global_load_lds_dwordx4 v[196:197], off
	v_lshl_add_u64 v[232:233], s[6:7], 0, v[0:1]
	s_add_i32 m0, s44, 0x2000
	s_nop 0
	global_load_lds_dwordx4 v[232:233], off
	s_mov_b32 m0, s30
	v_lshl_add_u64 v[234:235], s[10:11], 0, v[160:161]
	s_waitcnt vmcnt(10)
	s_waitcnt lgkmcnt(0)
	s_setprio 1
	s_barrier
	v_mfma_f32_16x16x32_bf16 v[64:67], v[216:219], v[148:151], v[64:67]
	v_mfma_f32_16x16x32_bf16 v[64:67], v[220:223], v[152:155], v[64:67]
	s_waitcnt lgkmcnt(0)
	v_mfma_f32_16x16x32_bf16 v[56:59], v[216:219], v[176:179], v[56:59]
	v_mfma_f32_16x16x32_bf16 v[56:59], v[220:223], v[180:183], v[56:59]
	v_mfma_f32_16x16x32_bf16 v[48:51], v[216:219], v[184:187], v[48:51]
	v_mfma_f32_16x16x32_bf16 v[48:51], v[220:223], v[188:191], v[48:51]
	v_mfma_f32_16x16x32_bf16 v[40:43], v[216:219], v[192:195], v[40:43]
	v_mfma_f32_16x16x32_bf16 v[40:43], v[220:223], v[212:215], v[40:43]
	v_mfma_f32_16x16x32_bf16 v[60:63], v[224:227], v[148:151], v[60:63]
	v_mfma_f32_16x16x32_bf16 v[60:63], v[228:231], v[152:155], v[60:63]
	v_mfma_f32_16x16x32_bf16 v[52:55], v[224:227], v[176:179], v[52:55]
	v_mfma_f32_16x16x32_bf16 v[52:55], v[228:231], v[180:183], v[52:55]
	v_mfma_f32_16x16x32_bf16 v[44:47], v[224:227], v[184:187], v[44:47]
	v_mfma_f32_16x16x32_bf16 v[44:47], v[228:231], v[188:191], v[44:47]
	v_mfma_f32_16x16x32_bf16 v[36:39], v[224:227], v[192:195], v[36:39]
	v_mfma_f32_16x16x32_bf16 v[36:39], v[228:231], v[212:215], v[36:39]
	s_barrier
	s_setprio 0
	ds_read_b128 v[148:151], v169 offset:16384
	ds_read_b128 v[152:155], v169 offset:17408
	ds_read_b128 v[176:179], v169 offset:18432
	ds_read_b128 v[180:183], v169 offset:19456
	ds_read_b128 v[184:187], v169 offset:20480
	ds_read_b128 v[188:191], v169 offset:21504
	ds_read_b128 v[192:195], v169 offset:22528
	ds_read_b128 v[212:215], v169 offset:23552
	global_load_lds_dwordx4 v[234:235], off
	v_lshl_add_u64 v[236:237], s[10:11], 0, v[156:157]
	s_mov_b32 m0, s31
	s_nop 0
	global_load_lds_dwordx4 v[236:237], off
	s_add_u32 s44, s6, 0x20000
	s_addc_u32 s45, s7, 0
	s_add_i32 s46, s46, s29
	v_lshl_add_u64 v[246:247], s[44:45], 0, v[158:159]
	s_mov_b32 m0, s46
	s_nop 0
	global_load_lds_dwordx4 v[246:247], off
	v_lshl_add_u64 v[246:247], s[44:45], 0, v[0:1]
	s_add_i32 m0, s46, 0x2000
	s_nop 0
	global_load_lds_dwordx4 v[246:247], off
	s_add_i32 s44, 0, 0x18000
	v_add_u32_e32 v2, s44, v167
	s_waitcnt vmcnt(8)
	s_waitcnt lgkmcnt(0)
	s_setprio 1
	s_barrier
	v_mfma_f32_16x16x32_bf16 v[104:107], v[92:95], v[148:151], v[104:107]
	v_mfma_f32_16x16x32_bf16 v[104:107], v[100:103], v[152:155], v[104:107]
	s_waitcnt lgkmcnt(0)
	v_mfma_f32_16x16x32_bf16 v[88:91], v[92:95], v[176:179], v[88:91]
	v_mfma_f32_16x16x32_bf16 v[88:91], v[100:103], v[180:183], v[88:91]
	v_mfma_f32_16x16x32_bf16 v[80:83], v[92:95], v[184:187], v[80:83]
	v_mfma_f32_16x16x32_bf16 v[80:83], v[100:103], v[188:191], v[80:83]
	v_mfma_f32_16x16x32_bf16 v[72:75], v[92:95], v[192:195], v[72:75]
	v_mfma_f32_16x16x32_bf16 v[72:75], v[100:103], v[212:215], v[72:75]
	v_mfma_f32_16x16x32_bf16 v[96:99], v[132:135], v[148:151], v[96:99]
	v_mfma_f32_16x16x32_bf16 v[96:99], v[144:147], v[152:155], v[96:99]
	v_mfma_f32_16x16x32_bf16 v[84:87], v[132:135], v[176:179], v[84:87]
	v_mfma_f32_16x16x32_bf16 v[84:87], v[144:147], v[180:183], v[84:87]
	v_mfma_f32_16x16x32_bf16 v[76:79], v[132:135], v[184:187], v[76:79]
	v_mfma_f32_16x16x32_bf16 v[76:79], v[144:147], v[188:191], v[76:79]
	v_mfma_f32_16x16x32_bf16 v[68:71], v[132:135], v[192:195], v[68:71]
	v_mfma_f32_16x16x32_bf16 v[68:71], v[144:147], v[212:215], v[68:71]
	v_mfma_f32_16x16x32_bf16 v[32:35], v[216:219], v[148:151], v[32:35]
	v_mfma_f32_16x16x32_bf16 v[32:35], v[220:223], v[152:155], v[32:35]
	v_mfma_f32_16x16x32_bf16 v[24:27], v[216:219], v[176:179], v[24:27]
	v_mfma_f32_16x16x32_bf16 v[24:27], v[220:223], v[180:183], v[24:27]
	v_mfma_f32_16x16x32_bf16 v[16:19], v[216:219], v[184:187], v[16:19]
	v_mfma_f32_16x16x32_bf16 v[16:19], v[220:223], v[188:191], v[16:19]
	v_mfma_f32_16x16x32_bf16 v[8:11], v[216:219], v[192:195], v[8:11]
	v_mfma_f32_16x16x32_bf16 v[8:11], v[220:223], v[212:215], v[8:11]
	v_mfma_f32_16x16x32_bf16 v[28:31], v[224:227], v[148:151], v[28:31]
	v_mfma_f32_16x16x32_bf16 v[28:31], v[228:231], v[152:155], v[28:31]
	v_mfma_f32_16x16x32_bf16 v[20:23], v[224:227], v[176:179], v[20:23]
	v_mfma_f32_16x16x32_bf16 v[20:23], v[228:231], v[180:183], v[20:23]
	v_mfma_f32_16x16x32_bf16 v[12:15], v[224:227], v[184:187], v[12:15]
	v_mfma_f32_16x16x32_bf16 v[12:15], v[228:231], v[188:191], v[12:15]
	v_mfma_f32_16x16x32_bf16 v[4:7], v[224:227], v[192:195], v[4:7]
	v_mfma_f32_16x16x32_bf16 v[4:7], v[228:231], v[212:215], v[4:7]
	s_barrier
	s_setprio 0
	ds_read_b128 v[92:95], v2
	ds_read_b128 v[100:103], v2 offset:1024
	ds_read_b128 v[132:135], v2 offset:2048
	ds_read_b128 v[144:147], v2 offset:3072
	s_add_u32 s10, s10, 0x80000
	s_addc_u32 s11, s11, 0
	s_mov_b32 m0, s34
	v_lshl_add_u64 v[216:217], s[10:11], 0, v[160:161]
	ds_read_b128 v[148:151], v169 offset:32768
	ds_read_b128 v[152:155], v169 offset:33792
	ds_read_b128 v[176:179], v169 offset:34816
	ds_read_b128 v[180:183], v169 offset:35840
	ds_read_b128 v[184:187], v169 offset:36864
	ds_read_b128 v[188:191], v169 offset:37888
	ds_read_b128 v[192:195], v169 offset:38912
	ds_read_b128 v[212:215], v169 offset:39936
	global_load_lds_dwordx4 v[216:217], off
	v_lshl_add_u64 v[216:217], s[10:11], 0, v[156:157]
	s_mov_b32 m0, s35
	s_nop 0
	global_load_lds_dwordx4 v[216:217], off
	s_waitcnt lgkmcnt(6)
	s_setprio 1
	s_barrier
; #define PG8_WAIT_V(n) asm volatile("s_waitcnt vmcnt(" #n ")" ::: "memory")
; #define PG8_WAIT_L(n) asm volatile("s_waitcnt lgkmcnt(" #n ")" ::: "memory")
; #define PG8_BAR __builtin_amdgcn_s_barrier()
; #define PG8_SCHED __builtin_amdgcn_sched_barrier(0)
; template <class Epi, class AddrA, class AddrB>
; __device__ __forceinline__ void gemm_phase(const Sched S, const int lda, const int ldb, const int K, const AddrA addrA,
;                                            const AddrB addrB, const Epi E) {
;     ...
;       PG8_LDB(B0, 1, 0); PG8_SCHED; PG8_LDA(At, 1, 0); PG8_STAGE(PG8_SA(0, 1), a2 + hstepA, voffA);
;       PG8_WAIT_L(8); PG8_BAR; PG8_WAIT_L(0); PG8_MMA(0, 0, At, B0); PG8_BAR; PG8_SCHED;
;       PG8_LDB(B1, 1, 1); PG8_STAGE(PG8_SB(1, 0), b3, voffB);
;       PG8_BAR; PG8_WAIT_L(0); PG8_MMA(0, 1, At, B1); PG8_BAR;
;       PG8_LDA(At, 1, 1); PG8_STAGE(PG8_SA(1, 0), a3, voffA);
;       PG8_BAR; PG8_WAIT_L(0); PG8_MMA(1, 0, At, B0); PG8_BAR; PG8_SCHED;
;       PG8_STAGE(PG8_SB(1, 1), b3 + hstepB, voffB);
;       PG8_WAIT_V(6); PG8_BAR; PG8_MMA(1, 1, At, B1); PG8_BAR;
	v_mfma_f32_16x16x32_bf16 v[140:143], v[92:95], v[148:151], v[140:143]
	v_mfma_f32_16x16x32_bf16 v[140:143], v[100:103], v[152:155], v[140:143]
	s_waitcnt lgkmcnt(0)
	v_mfma_f32_16x16x32_bf16 v[128:131], v[92:95], v[176:179], v[128:131]
	v_mfma_f32_16x16x32_bf16 v[128:131], v[100:103], v[180:183], v[128:131]
	v_mfma_f32_16x16x32_bf16 v[120:123], v[92:95], v[184:187], v[120:123]
	v_mfma_f32_16x16x32_bf16 v[120:123], v[100:103], v[188:191], v[120:123]
	v_mfma_f32_16x16x32_bf16 v[112:115], v[92:95], v[192:195], v[112:115]
	v_mfma_f32_16x16x32_bf16 v[112:115], v[100:103], v[212:215], v[112:115]
	v_mfma_f32_16x16x32_bf16 v[136:139], v[132:135], v[148:151], v[136:139]
	v_mfma_f32_16x16x32_bf16 v[136:139], v[144:147], v[152:155], v[136:139]
	v_mfma_f32_16x16x32_bf16 v[124:127], v[132:135], v[176:179], v[124:127]
	v_mfma_f32_16x16x32_bf16 v[124:127], v[144:147], v[180:183], v[124:127]
	v_mfma_f32_16x16x32_bf16 v[116:119], v[132:135], v[184:187], v[116:119]
	v_mfma_f32_16x16x32_bf16 v[116:119], v[144:147], v[188:191], v[116:119]
	v_mfma_f32_16x16x32_bf16 v[108:111], v[132:135], v[192:195], v[108:111]
	v_mfma_f32_16x16x32_bf16 v[108:111], v[144:147], v[212:215], v[108:111]
	s_barrier
	s_setprio 0
	s_add_i32 s10, 0, 0x1c000
	s_add_i32 s11, s44, s29
	v_add_u32_e32 v2, s10, v167
	v_lshl_add_u64 v[196:197], v[196:197], 0, s[52:53]
	s_mov_b32 m0, s11
	ds_read_b128 v[216:219], v2
	ds_read_b128 v[220:223], v2 offset:1024
	ds_read_b128 v[224:227], v2 offset:2048
	ds_read_b128 v[228:231], v2 offset:3072
	global_load_lds_dwordx4 v[196:197], off
	v_lshl_add_u64 v[196:197], v[232:233], 0, s[52:53]
	s_add_i32 m0, s11, 0x2000
	s_nop 0
	global_load_lds_dwordx4 v[196:197], off
	s_mov_b32 m0, s37
	v_lshl_add_u64 v[196:197], v[234:235], 0, s[52:53]
	s_waitcnt vmcnt(10)
	s_waitcnt lgkmcnt(0)
	s_setprio 1
	s_barrier
	v_mfma_f32_16x16x32_bf16 v[64:67], v[216:219], v[148:151], v[64:67]
	v_mfma_f32_16x16x32_bf16 v[64:67], v[220:223], v[152:155], v[64:67]
	s_waitcnt lgkmcnt(0)
	v_mfma_f32_16x16x32_bf16 v[56:59], v[216:219], v[176:179], v[56:59]
	v_mfma_f32_16x16x32_bf16 v[56:59], v[220:223], v[180:183], v[56:59]
	v_mfma_f32_16x16x32_bf16 v[48:51], v[216:219], v[184:187], v[48:51]
	v_mfma_f32_16x16x32_bf16 v[48:51], v[220:223], v[188:191], v[48:51]
	v_mfma_f32_16x16x32_bf16 v[40:43], v[216:219], v[192:195], v[40:43]
	v_mfma_f32_16x16x32_bf16 v[40:43], v[220:223], v[212:215], v[40:43]
	v_mfma_f32_16x16x32_bf16 v[60:63], v[224:227], v[148:151], v[60:63]
	v_mfma_f32_16x16x32_bf16 v[60:63], v[228:231], v[152:155], v[60:63]
	v_mfma_f32_16x16x32_bf16 v[52:55], v[224:227], v[176:179], v[52:55]
	v_mfma_f32_16x16x32_bf16 v[52:55], v[228:231], v[180:183], v[52:55]
	v_mfma_f32_16x16x32_bf16 v[44:47], v[224:227], v[184:187], v[44:47]
	v_mfma_f32_16x16x32_bf16 v[44:47], v[228:231], v[188:191], v[44:47]
	v_mfma_f32_16x16x32_bf16 v[36:39], v[224:227], v[192:195], v[36:39]
	v_mfma_f32_16x16x32_bf16 v[36:39], v[228:231], v[212:215], v[36:39]
	s_barrier
	s_setprio 0
	ds_read_b128 v[148:151], v169 offset:49152
	ds_read_b128 v[152:155], v169 offset:50176
	ds_read_b128 v[176:179], v169 offset:51200
	ds_read_b128 v[180:183], v169 offset:52224
	ds_read_b128 v[184:187], v169 offset:53248
	ds_read_b128 v[188:191], v169 offset:54272
	ds_read_b128 v[192:195], v169 offset:55296
	ds_read_b128 v[212:215], v169 offset:56320
	global_load_lds_dwordx4 v[196:197], off
	v_lshl_add_u64 v[196:197], v[236:237], 0, s[52:53]
	s_mov_b32 m0, s38
	s_nop 0
	global_load_lds_dwordx4 v[196:197], off
	s_add_u32 s6, s6, 0x20080
	s_addc_u32 s7, s7, 0
	s_add_i32 s10, s10, s29
	v_lshl_add_u64 v[246:247], s[6:7], 0, v[158:159]
	s_mov_b32 m0, s10
	s_nop 0
	global_load_lds_dwordx4 v[246:247], off
	v_lshl_add_u64 v[246:247], s[6:7], 0, v[0:1]
	s_add_i32 m0, s10, 0x2000
	s_nop 0
	global_load_lds_dwordx4 v[246:247], off
	s_add_i32 s43, s43, 2
	s_add_u32 s41, s41, 0x100
	s_addc_u32 s42, s42, 0
	s_add_u32 s4, s4, 0x100
	s_addc_u32 s5, s5, 0
	s_waitcnt vmcnt(8)
	s_waitcnt lgkmcnt(0)
	s_setprio 1
	s_barrier
	v_mfma_f32_16x16x32_bf16 v[104:107], v[92:95], v[148:151], v[104:107]
	v_mfma_f32_16x16x32_bf16 v[104:107], v[100:103], v[152:155], v[104:107]
	s_waitcnt lgkmcnt(0)
	v_mfma_f32_16x16x32_bf16 v[88:91], v[92:95], v[176:179], v[88:91]
	v_mfma_f32_16x16x32_bf16 v[88:91], v[100:103], v[180:183], v[88:91]
	v_mfma_f32_16x16x32_bf16 v[80:83], v[92:95], v[184:187], v[80:83]
	v_mfma_f32_16x16x32_bf16 v[80:83], v[100:103], v[188:191], v[80:83]
	v_mfma_f32_16x16x32_bf16 v[72:75], v[92:95], v[192:195], v[72:75]
	v_mfma_f32_16x16x32_bf16 v[72:75], v[100:103], v[212:215], v[72:75]
	v_mfma_f32_16x16x32_bf16 v[96:99], v[132:135], v[148:151], v[96:99]
	v_mfma_f32_16x16x32_bf16 v[96:99], v[144:147], v[152:155], v[96:99]
	v_mfma_f32_16x16x32_bf16 v[84:87], v[132:135], v[176:179], v[84:87]
	v_mfma_f32_16x16x32_bf16 v[84:87], v[144:147], v[180:183], v[84:87]
	v_mfma_f32_16x16x32_bf16 v[76:79], v[132:135], v[184:187], v[76:79]
	v_mfma_f32_16x16x32_bf16 v[76:79], v[144:147], v[188:191], v[76:79]
	v_mfma_f32_16x16x32_bf16 v[68:71], v[132:135], v[192:195], v[68:71]
	v_mfma_f32_16x16x32_bf16 v[68:71], v[144:147], v[212:215], v[68:71]
	v_mfma_f32_16x16x32_bf16 v[32:35], v[216:219], v[148:151], v[32:35]
	v_mfma_f32_16x16x32_bf16 v[32:35], v[220:223], v[152:155], v[32:35]
	v_mfma_f32_16x16x32_bf16 v[24:27], v[216:219], v[176:179], v[24:27]
	v_mfma_f32_16x16x32_bf16 v[24:27], v[220:223], v[180:183], v[24:27]
	v_mfma_f32_16x16x32_bf16 v[16:19], v[216:219], v[184:187], v[16:19]
	v_mfma_f32_16x16x32_bf16 v[16:19], v[220:223], v[188:191], v[16:19]
	v_mfma_f32_16x16x32_bf16 v[8:11], v[216:219], v[192:195], v[8:11]
	v_mfma_f32_16x16x32_bf16 v[8:11], v[220:223], v[212:215], v[8:11]
	v_mfma_f32_16x16x32_bf16 v[28:31], v[224:227], v[148:151], v[28:31]
	v_mfma_f32_16x16x32_bf16 v[28:31], v[228:231], v[152:155], v[28:31]
	v_mfma_f32_16x16x32_bf16 v[20:23], v[224:227], v[176:179], v[20:23]
	v_mfma_f32_16x16x32_bf16 v[20:23], v[228:231], v[180:183], v[20:23]
	v_mfma_f32_16x16x32_bf16 v[12:15], v[224:227], v[184:187], v[12:15]
	v_mfma_f32_16x16x32_bf16 v[12:15], v[228:231], v[188:191], v[12:15]
	v_mfma_f32_16x16x32_bf16 v[4:7], v[224:227], v[192:195], v[4:7]
	v_mfma_f32_16x16x32_bf16 v[4:7], v[228:231], v[212:215], v[4:7]
	s_barrier
; __device__ __forceinline__ size_t pidx(size_t row, int col) { return ((size_t)(col >> 8) * MTOK + row) * PLD + (col & 255); }
; __device__ __forceinline__ float bflo(unsigned v) { return __uint_as_float(v << 16); }
; __device__ __forceinline__ float bfhi(unsigned v) { return __uint_as_float(v & 0xffff0000u); }
; __device__ __forceinline__ float siluf_(float x) { return x * __builtin_amdgcn_rcpf(1.0f + __expf(-x)); }
;   __device__ __forceinline__ void operator()(EPI_ARGS) const {
;     const size_t row0 = (size_t)u.pm * 256 + wr * 64 + fr;
;     const int col0 = u.pn * 256 + wc * 32 + 8 * fq;
; #pragma unroll
;     for (int bj = 0; bj < 2; ++bj) {
;       const int c = col0 + bj * HALF;
;       const f32x4 s0 = *(const f32x4*)(psc + c), s1 = *(const f32x4*)(psc + c + 4);
; #pragma unroll
;       for (int ai = 0; ai < 2; ++ai) {
;         u32x4 z[4];
; #pragma unroll
;         for (int m = 0; m < 4; ++m) z[m] = *(const u32x4*)(proj + pidx(row0 + ai * HALF + m * 16, PZ + c));
;         __builtin_amdgcn_sched_barrier(0);
; #pragma unroll
;         for (int m = 0; m < 4; ++m) {
;           const size_t row = row0 + ai * HALF + m * 16;
;           const f32x4 v0 = acc[ai][bj][m][0], v1 = acc[ai][bj][m][1];
;           u32x4 o;
;           o.x = pack2(v0[0] * s0[0] * siluf_(bflo(z[m].x)), v0[1] * s0[1] * siluf_(bfhi(z[m].x)));
;           o.y = pack2(v0[2] * s0[2] * siluf_(bflo(z[m].y)), v0[3] * s0[3] * siluf_(bfhi(z[m].y)));
;           o.z = pack2(v1[0] * s1[0] * siluf_(bflo(z[m].z)), v1[1] * s1[1] * siluf_(bfhi(z[m].z)));
;           o.w = pack2(v1[2] * s1[2] * siluf_(bflo(z[m].w)), v1[3] * s1[3] * siluf_(bfhi(z[m].w)));
;           *(u32x4*)(y0 + row * DM + c) = o;
;         }
	s_setprio 0
	s_cmp_gt_u32 s43, 5
	s_cbranch_scc0 .LBB0_485
	s_ashr_i32 s3, s2, 31
	s_lshl_b64 s[2:3], s[2:3], 8
	v_lshl_add_u64 v[186:187], s[2:3], 0, v[162:163]
	s_lshl_b32 s2, s33, 8
	v_or_b32_e32 v196, s2, v168
	s_addk_i32 s2, 0x800
	s_ashr_i32 s2, s2, 8
	s_ashr_i32 s3, s2, 31
	s_lshl_b64 s[2:3], s[2:3], 23
	s_add_u32 s2, s0, s2
	s_addc_u32 s3, s1, s3
	v_lshlrev_b32_e32 v2, 1, v168
	v_or_b32_e32 v194, 16, v186
	v_mov_b32_e32 v195, v187
	v_ashrrev_i32_e32 v197, 31, v196
	v_lshl_add_u64 v[188:189], s[2:3], 0, v[2:3]
	v_lshlrev_b64 v[178:179], 9, v[186:187]
	v_lshlrev_b64 v[180:181], 9, v[194:195]
	v_or_b32_e32 v192, 32, v186
	v_mov_b32_e32 v193, v187
	v_or_b32_e32 v190, 48, v186
	v_mov_b32_e32 v191, v187
	v_lshl_add_u64 v[176:177], v[196:197], 2, s[12:13]
	v_lshl_add_u64 v[132:133], v[188:189], 0, v[178:179]
	v_lshl_add_u64 v[134:135], v[188:189], 0, v[180:181]
	v_lshlrev_b64 v[182:183], 9, v[192:193]
	v_lshlrev_b64 v[184:185], 9, v[190:191]
	global_load_dwordx4 v[92:95], v[176:177], off offset:16
	global_load_dwordx4 v[100:103], v[176:177], off
	flat_load_dwordx4 v[152:155], v[132:133]
	flat_load_dwordx4 v[148:151], v[134:135]
	v_lshl_add_u64 v[132:133], v[188:189], 0, v[182:183]
	v_lshl_add_u64 v[134:135], v[188:189], 0, v[184:185]
	flat_load_dwordx4 v[144:147], v[132:133]
	s_nop 0
	flat_load_dwordx4 v[132:135], v[134:135]
	s_waitcnt vmcnt(0) lgkmcnt(0)
	v_lshlrev_b32_e32 v213, 16, v152
	v_mul_f32_e32 v2, 0xbfb8aa3b, v213
	v_exp_f32_e32 v2, v2
	v_mov_b32_e32 v214, v140
	v_mov_b32_e32 v212, v100
	s_mov_b64 s[4:5], 0x90
	v_add_f32_e32 v2, 1.0, v2
	v_rcp_f32_e32 v215, v2
	s_nop 0
	v_pk_mul_f32 v[212:213], v[214:215], v[212:213]
	s_nop 0
	v_mul_f32_e32 v2, v212, v213
	v_and_b32_e32 v213, 0xffff0000, v152
	v_mul_f32_e32 v140, 0xbfb8aa3b, v213
	v_exp_f32_e32 v140, v140
	v_mov_b32_e32 v214, v141
	v_mov_b32_e32 v212, v101
	v_add_f32_e32 v140, 1.0, v140
	v_rcp_f32_e32 v215, v140
	s_nop 0
	v_pk_mul_f32 v[140:141], v[214:215], v[212:213]
	s_nop 0
	v_mul_f32_e32 v140, v140, v141
	v_lshlrev_b32_e32 v141, 16, v153
	v_cvt_pk_bf16_f32 v152, v2, v140
	v_mul_f32_e32 v2, 0xbfb8aa3b, v141
	v_exp_f32_e32 v2, v2
	v_mov_b32_e32 v212, v142
	v_mov_b32_e32 v140, v102
	v_mov_b32_e32 v142, v136
	v_add_f32_e32 v2, 1.0, v2
	v_rcp_f32_e32 v213, v2
	s_nop 0
	v_pk_mul_f32 v[140:141], v[212:213], v[140:141]
	s_nop 0
	v_mul_f32_e32 v2, v140, v141
	v_and_b32_e32 v141, 0xffff0000, v153
	v_mul_f32_e32 v140, 0xbfb8aa3b, v141
	v_exp_f32_e32 v140, v140
	v_mov_b32_e32 v212, v143
	v_add_f32_e32 v140, 1.0, v140
	v_rcp_f32_e32 v213, v140
	v_mov_b32_e32 v140, v103
	v_pk_mul_f32 v[140:141], v[212:213], v[140:141]
	s_nop 0
	v_mul_f32_e32 v140, v140, v141
	v_lshlrev_b32_e32 v141, 16, v154
	v_cvt_pk_bf16_f32 v153, v2, v140
	v_mul_f32_e32 v2, 0xbfb8aa3b, v141
	v_exp_f32_e32 v2, v2
	v_mov_b32_e32 v140, v92
	v_add_f32_e32 v2, 1.0, v2
	v_rcp_f32_e32 v143, v2
	s_nop 0
	v_pk_mul_f32 v[140:141], v[142:143], v[140:141]
	s_nop 0
	v_mul_f32_e32 v2, v140, v141
	v_and_b32_e32 v141, 0xffff0000, v154
	v_mul_f32_e32 v136, 0xbfb8aa3b, v141
	v_exp_f32_e32 v136, v136
	v_mov_b32_e32 v142, v137
	v_mov_b32_e32 v140, v93
	v_add_f32_e32 v136, 1.0, v136
	v_rcp_f32_e32 v143, v136
	s_nop 0
	v_pk_mul_f32 v[136:137], v[142:143], v[140:141]
	s_nop 0
	v_mul_f32_e32 v136, v136, v137
	v_lshlrev_b32_e32 v137, 16, v155
	v_cvt_pk_bf16_f32 v154, v2, v136
	v_mul_f32_e32 v2, 0xbfb8aa3b, v137
	v_exp_f32_e32 v2, v2
	v_mov_b32_e32 v140, v138
	v_mov_b32_e32 v136, v94
	v_mov_b32_e32 v142, v128
	v_add_f32_e32 v2, 1.0, v2
	v_rcp_f32_e32 v141, v2
	v_mov_b32_e32 v138, v100
	v_pk_mul_f32 v[136:137], v[140:141], v[136:137]
	s_nop 0
	v_mul_f32_e32 v2, v136, v137
	v_and_b32_e32 v137, 0xffff0000, v155
	v_mul_f32_e32 v136, 0xbfb8aa3b, v137
	v_exp_f32_e32 v136, v136
	v_mov_b32_e32 v140, v139
	v_lshlrev_b32_e32 v139, 16, v148
	v_add_f32_e32 v136, 1.0, v136
	v_rcp_f32_e32 v141, v136
	v_mov_b32_e32 v136, v95
	v_pk_mul_f32 v[136:137], v[140:141], v[136:137]
	s_nop 0
	v_mul_f32_e32 v136, v136, v137
	v_cvt_pk_bf16_f32 v155, v2, v136
	v_mul_f32_e32 v2, 0xbfb8aa3b, v139
	v_exp_f32_e32 v2, v2
	v_lshlrev_b64 v[140:141], 1, v[196:197]
	v_lshlrev_b64 v[136:137], 12, v[186:187]
	v_lshl_add_u64 v[136:137], s[8:9], 0, v[136:137]
	v_add_f32_e32 v2, 1.0, v2
	v_rcp_f32_e32 v143, v2
	v_lshl_add_u64 v[136:137], v[136:137], 0, v[140:141]
	flat_store_dwordx4 v[136:137], v[152:155]
	v_pk_mul_f32 v[138:139], v[142:143], v[138:139]
	s_nop 0
	v_mul_f32_e32 v2, v138, v139
	v_and_b32_e32 v139, 0xffff0000, v148
	v_mul_f32_e32 v128, 0xbfb8aa3b, v139
	v_exp_f32_e32 v128, v128
	v_mov_b32_e32 v142, v129
	v_mov_b32_e32 v138, v101
	v_add_f32_e32 v128, 1.0, v128
	v_rcp_f32_e32 v143, v128
	s_nop 0
	v_pk_mul_f32 v[128:129], v[142:143], v[138:139]
	s_nop 0
	v_mul_f32_e32 v128, v128, v129
	v_lshlrev_b32_e32 v139, 16, v149
	v_cvt_pk_bf16_f32 v128, v2, v128
	v_mul_f32_e32 v2, 0xbfb8aa3b, v139
	v_exp_f32_e32 v2, v2
	v_mov_b32_e32 v142, v130
	v_mov_b32_e32 v138, v102
	v_add_f32_e32 v2, 1.0, v2
	v_rcp_f32_e32 v143, v2
	s_nop 0
	v_pk_mul_f32 v[138:139], v[142:143], v[138:139]
	s_nop 0
	v_mul_f32_e32 v2, v138, v139
	v_and_b32_e32 v139, 0xffff0000, v149
	v_mul_f32_e32 v129, 0xbfb8aa3b, v139
	v_exp_f32_e32 v129, v129
	v_mov_b32_e32 v142, v131
	v_mov_b32_e32 v138, v103
	v_lshl_add_u64 v[148:149], v[186:187], 0, s[52:53]
	v_add_f32_e32 v129, 1.0, v129
	v_rcp_f32_e32 v143, v129
	s_nop 0
	v_pk_mul_f32 v[130:131], v[142:143], v[138:139]
	s_nop 0
	v_mul_f32_e32 v129, v130, v131
	v_lshlrev_b32_e32 v131, 16, v150
	v_cvt_pk_bf16_f32 v129, v2, v129
	v_mul_f32_e32 v2, 0xbfb8aa3b, v131
	v_exp_f32_e32 v2, v2
	v_mov_b32_e32 v138, v124
	v_mov_b32_e32 v130, v92
	v_add_f32_e32 v2, 1.0, v2
; __device__ __forceinline__ size_t pidx(size_t row, int col) { return ((size_t)(col >> 8) * MTOK + row) * PLD + (col & 255); }
; __device__ __forceinline__ float bflo(unsigned v) { return __uint_as_float(v << 16); }
; __device__ __forceinline__ float bfhi(unsigned v) { return __uint_as_float(v & 0xffff0000u); }
; __device__ __forceinline__ float siluf_(float x) { return x * __builtin_amdgcn_rcpf(1.0f + __expf(-x)); }
;   __device__ __forceinline__ void operator()(EPI_ARGS) const {
;     ...
;       for (int ai = 0; ai < 2; ++ai) {
;         u32x4 z[4];
; #pragma unroll
;         for (int m = 0; m < 4; ++m) z[m] = *(const u32x4*)(proj + pidx(row0 + ai * HALF + m * 16, PZ + c));
;         __builtin_amdgcn_sched_barrier(0);
; #pragma unroll
;         for (int m = 0; m < 4; ++m) {
;           const size_t row = row0 + ai * HALF + m * 16;
;           const f32x4 v0 = acc[ai][bj][m][0], v1 = acc[ai][bj][m][1];
;           u32x4 o;
;           o.x = pack2(v0[0] * s0[0] * siluf_(bflo(z[m].x)), v0[1] * s0[1] * siluf_(bfhi(z[m].x)));
;           o.y = pack2(v0[2] * s0[2] * siluf_(bflo(z[m].y)), v0[3] * s0[3] * siluf_(bfhi(z[m].y)));
;           o.z = pack2(v1[0] * s1[0] * siluf_(bflo(z[m].z)), v1[1] * s1[1] * siluf_(bfhi(z[m].z)));
;           o.w = pack2(v1[2] * s1[2] * siluf_(bflo(z[m].w)), v1[3] * s1[3] * siluf_(bfhi(z[m].w)));
;           *(u32x4*)(y0 + row * DM + c) = o;
;         }
	v_rcp_f32_e32 v139, v2
	s_nop 0
	v_pk_mul_f32 v[130:131], v[138:139], v[130:131]
	s_nop 0
	v_mul_f32_e32 v2, v130, v131
	v_and_b32_e32 v131, 0xffff0000, v150
	v_mul_f32_e32 v124, 0xbfb8aa3b, v131
	v_exp_f32_e32 v124, v124
	v_mov_b32_e32 v138, v125
	v_mov_b32_e32 v130, v93
	v_add_f32_e32 v124, 1.0, v124
	v_rcp_f32_e32 v139, v124
	s_nop 0
	v_pk_mul_f32 v[124:125], v[138:139], v[130:131]
	s_nop 0
	v_mul_f32_e32 v124, v124, v125
	v_lshlrev_b32_e32 v125, 16, v151
	v_cvt_pk_bf16_f32 v130, v2, v124
	v_mul_f32_e32 v2, 0xbfb8aa3b, v125
	v_exp_f32_e32 v2, v2
	v_mov_b32_e32 v138, v126
	v_mov_b32_e32 v124, v94
	v_mov_b32_e32 v126, v100
	v_add_f32_e32 v2, 1.0, v2
	v_rcp_f32_e32 v139, v2
	s_nop 0
	v_pk_mul_f32 v[124:125], v[138:139], v[124:125]
	s_nop 0
	v_mul_f32_e32 v2, v124, v125
	v_and_b32_e32 v125, 0xffff0000, v151
	v_mul_f32_e32 v124, 0xbfb8aa3b, v125
	v_exp_f32_e32 v124, v124
	v_mov_b32_e32 v138, v127
	v_lshlrev_b32_e32 v127, 16, v144
	v_add_f32_e32 v124, 1.0, v124
	v_rcp_f32_e32 v139, v124
	v_mov_b32_e32 v124, v95
	v_pk_mul_f32 v[124:125], v[138:139], v[124:125]
	s_nop 0
	v_mul_f32_e32 v124, v124, v125
	v_cvt_pk_bf16_f32 v131, v2, v124
	v_mul_f32_e32 v2, 0xbfb8aa3b, v127
	v_exp_f32_e32 v2, v2
	v_lshlrev_b64 v[124:125], 12, v[194:195]
	v_lshl_add_u64 v[124:125], s[8:9], 0, v[124:125]
	v_lshl_add_u64 v[124:125], v[124:125], 0, v[140:141]
	v_add_f32_e32 v2, 1.0, v2
	flat_store_dwordx4 v[124:125], v[128:131]
	s_nop 1
	v_rcp_f32_e32 v129, v2
	v_mov_b32_e32 v128, v120
	v_lshlrev_b64 v[130:131], 9, v[148:149]
	v_pk_mul_f32 v[126:127], v[128:129], v[126:127]
	s_nop 0
	v_mul_f32_e32 v2, v126, v127
	v_and_b32_e32 v127, 0xffff0000, v144
	v_mul_f32_e32 v120, 0xbfb8aa3b, v127
	v_exp_f32_e32 v120, v120
	v_mov_b32_e32 v128, v121
	v_mov_b32_e32 v126, v101
	v_add_f32_e32 v120, 1.0, v120
	v_rcp_f32_e32 v129, v120
	s_nop 0
	v_pk_mul_f32 v[120:121], v[128:129], v[126:127]
	s_nop 0
	v_mul_f32_e32 v120, v120, v121
	v_lshlrev_b32_e32 v127, 16, v145
	v_cvt_pk_bf16_f32 v120, v2, v120
	v_mul_f32_e32 v2, 0xbfb8aa3b, v127
	v_exp_f32_e32 v2, v2
	v_mov_b32_e32 v128, v122
	v_mov_b32_e32 v126, v102
	v_add_f32_e32 v2, 1.0, v2
	v_rcp_f32_e32 v129, v2
	s_nop 0
	v_pk_mul_f32 v[126:127], v[128:129], v[126:127]
	s_nop 0
	v_mul_f32_e32 v2, v126, v127
	v_and_b32_e32 v127, 0xffff0000, v145
	v_mul_f32_e32 v121, 0xbfb8aa3b, v127
	v_exp_f32_e32 v121, v121
	v_mov_b32_e32 v128, v123
	v_mov_b32_e32 v126, v103
	v_add_f32_e32 v121, 1.0, v121
	v_rcp_f32_e32 v129, v121
	s_nop 0
	v_pk_mul_f32 v[122:123], v[128:129], v[126:127]
	s_nop 0
	v_mul_f32_e32 v121, v122, v123
	v_lshlrev_b32_e32 v123, 16, v146
	v_cvt_pk_bf16_f32 v121, v2, v121
	v_mul_f32_e32 v2, 0xbfb8aa3b, v123
	v_exp_f32_e32 v2, v2
	v_mov_b32_e32 v126, v116
	v_mov_b32_e32 v122, v92
	v_add_f32_e32 v2, 1.0, v2
	v_rcp_f32_e32 v127, v2
	s_nop 0
	v_pk_mul_f32 v[122:123], v[126:127], v[122:123]
	s_nop 0
	v_mul_f32_e32 v2, v122, v123
	v_and_b32_e32 v123, 0xffff0000, v146
	v_mul_f32_e32 v116, 0xbfb8aa3b, v123
	v_exp_f32_e32 v116, v116
	v_mov_b32_e32 v126, v117
	v_mov_b32_e32 v122, v93
	v_add_f32_e32 v116, 1.0, v116
	v_rcp_f32_e32 v127, v116
	s_nop 0
	v_pk_mul_f32 v[116:117], v[126:127], v[122:123]
	s_nop 0
	v_mul_f32_e32 v116, v116, v117
	v_lshlrev_b32_e32 v117, 16, v147
	v_cvt_pk_bf16_f32 v122, v2, v116
	v_mul_f32_e32 v2, 0xbfb8aa3b, v117
	v_exp_f32_e32 v2, v2
	v_mov_b32_e32 v126, v118
	v_mov_b32_e32 v116, v94
	v_mov_b32_e32 v118, v112
	v_add_f32_e32 v2, 1.0, v2
	v_rcp_f32_e32 v127, v2
	s_nop 0
	v_pk_mul_f32 v[116:117], v[126:127], v[116:117]
	s_nop 0
	v_mul_f32_e32 v2, v116, v117
	v_and_b32_e32 v117, 0xffff0000, v147
	v_mul_f32_e32 v116, 0xbfb8aa3b, v117
	v_exp_f32_e32 v116, v116
	v_mov_b32_e32 v126, v119
	v_lshl_add_u64 v[146:147], v[186:187], 0, s[4:5]
	s_mov_b64 s[4:5], 0xa0
	v_add_f32_e32 v116, 1.0, v116
	v_rcp_f32_e32 v127, v116
	v_mov_b32_e32 v116, v95
	v_lshl_add_u64 v[144:145], v[186:187], 0, s[4:5]
	s_mov_b64 s[4:5], 0xb0
	v_pk_mul_f32 v[116:117], v[126:127], v[116:117]
	v_lshl_add_u64 v[142:143], v[186:187], 0, s[4:5]
	v_mul_f32_e32 v116, v116, v117
	v_cvt_pk_bf16_f32 v123, v2, v116
	v_lshlrev_b64 v[116:117], 12, v[192:193]
	v_lshl_add_u64 v[116:117], s[8:9], 0, v[116:117]
	v_lshl_add_u64 v[128:129], v[116:117], 0, v[140:141]
	v_lshlrev_b32_e32 v117, 16, v132
	v_mul_f32_e32 v2, 0xbfb8aa3b, v117
	v_exp_f32_e32 v2, v2
	v_mov_b32_e32 v116, v100
	flat_store_dwordx4 v[128:129], v[120:123]
	v_lshlrev_b64 v[138:139], 9, v[142:143]
	v_add_f32_e32 v2, 1.0, v2
	v_rcp_f32_e32 v119, v2
	s_nop 0
	v_pk_mul_f32 v[116:117], v[118:119], v[116:117]
	s_nop 0
	v_mul_f32_e32 v2, v116, v117
	v_and_b32_e32 v117, 0xffff0000, v132
	v_mul_f32_e32 v112, 0xbfb8aa3b, v117
	v_exp_f32_e32 v112, v112
	v_mov_b32_e32 v118, v113
	v_mov_b32_e32 v116, v101
	v_add_f32_e32 v112, 1.0, v112
	v_rcp_f32_e32 v119, v112
	s_nop 0
	v_pk_mul_f32 v[112:113], v[118:119], v[116:117]
	s_nop 0
	v_mul_f32_e32 v112, v112, v113
	v_lshlrev_b32_e32 v117, 16, v133
	v_cvt_pk_bf16_f32 v112, v2, v112
	v_mul_f32_e32 v2, 0xbfb8aa3b, v117
	v_exp_f32_e32 v2, v2
	v_mov_b32_e32 v118, v114
	v_mov_b32_e32 v116, v102
	v_add_f32_e32 v2, 1.0, v2
	v_rcp_f32_e32 v119, v2
	s_nop 0
	v_pk_mul_f32 v[116:117], v[118:119], v[116:117]
	s_nop 0
	v_mul_f32_e32 v2, v116, v117
	v_and_b32_e32 v117, 0xffff0000, v133
	v_mul_f32_e32 v113, 0xbfb8aa3b, v117
	v_exp_f32_e32 v113, v113
	v_mov_b32_e32 v118, v115
	v_mov_b32_e32 v116, v103
	v_lshlrev_b64 v[132:133], 9, v[146:147]
	v_add_f32_e32 v113, 1.0, v113
	v_rcp_f32_e32 v119, v113
	s_nop 0
	v_pk_mul_f32 v[114:115], v[118:119], v[116:117]
	s_nop 0
	v_mul_f32_e32 v113, v114, v115
	v_lshlrev_b32_e32 v115, 16, v134
	v_cvt_pk_bf16_f32 v113, v2, v113
	v_mul_f32_e32 v2, 0xbfb8aa3b, v115
; __device__ __forceinline__ size_t pidx(size_t row, int col) { return ((size_t)(col >> 8) * MTOK + row) * PLD + (col & 255); }
; __device__ __forceinline__ float bflo(unsigned v) { return __uint_as_float(v << 16); }
; __device__ __forceinline__ float bfhi(unsigned v) { return __uint_as_float(v & 0xffff0000u); }
; __device__ __forceinline__ float siluf_(float x) { return x * __builtin_amdgcn_rcpf(1.0f + __expf(-x)); }
;   __device__ __forceinline__ void operator()(EPI_ARGS) const {
;     ...
;       for (int ai = 0; ai < 2; ++ai) {
;         u32x4 z[4];
; #pragma unroll
;         for (int m = 0; m < 4; ++m) z[m] = *(const u32x4*)(proj + pidx(row0 + ai * HALF + m * 16, PZ + c));
;         __builtin_amdgcn_sched_barrier(0);
; #pragma unroll
;         for (int m = 0; m < 4; ++m) {
;           const size_t row = row0 + ai * HALF + m * 16;
;           const f32x4 v0 = acc[ai][bj][m][0], v1 = acc[ai][bj][m][1];
;           u32x4 o;
;           o.x = pack2(v0[0] * s0[0] * siluf_(bflo(z[m].x)), v0[1] * s0[1] * siluf_(bfhi(z[m].x)));
;           o.y = pack2(v0[2] * s0[2] * siluf_(bflo(z[m].y)), v0[3] * s0[3] * siluf_(bfhi(z[m].y)));
;           o.z = pack2(v1[0] * s1[0] * siluf_(bflo(z[m].z)), v1[1] * s1[1] * siluf_(bfhi(z[m].z)));
;           o.w = pack2(v1[2] * s1[2] * siluf_(bflo(z[m].w)), v1[3] * s1[3] * siluf_(bfhi(z[m].w)));
;           *(u32x4*)(y0 + row * DM + c) = o;
;         }
	v_exp_f32_e32 v2, v2
	v_mov_b32_e32 v116, v108
	v_mov_b32_e32 v114, v92
	v_add_f32_e32 v2, 1.0, v2
	v_rcp_f32_e32 v117, v2
	s_nop 0
	v_pk_mul_f32 v[114:115], v[116:117], v[114:115]
	s_nop 0
	v_mul_f32_e32 v2, v114, v115
	v_and_b32_e32 v115, 0xffff0000, v134
	v_mul_f32_e32 v108, 0xbfb8aa3b, v115
	v_exp_f32_e32 v108, v108
	v_mov_b32_e32 v116, v109
	v_mov_b32_e32 v114, v93
	v_add_f32_e32 v108, 1.0, v108
	v_rcp_f32_e32 v117, v108
	s_nop 0
	v_pk_mul_f32 v[108:109], v[116:117], v[114:115]
	s_nop 0
	v_mul_f32_e32 v108, v108, v109
	v_lshlrev_b32_e32 v109, 16, v135
	v_cvt_pk_bf16_f32 v114, v2, v108
	v_mul_f32_e32 v2, 0xbfb8aa3b, v109
	v_exp_f32_e32 v2, v2
	v_mov_b32_e32 v116, v110
	v_mov_b32_e32 v108, v94
	v_add_f32_e32 v2, 1.0, v2
	v_rcp_f32_e32 v117, v2
	s_nop 0
	v_pk_mul_f32 v[108:109], v[116:117], v[108:109]
	s_nop 0
	v_mul_f32_e32 v2, v108, v109
	v_and_b32_e32 v109, 0xffff0000, v135
	v_mul_f32_e32 v108, 0xbfb8aa3b, v109
	v_exp_f32_e32 v108, v108
	v_mov_b32_e32 v116, v111
	v_lshlrev_b64 v[134:135], 9, v[144:145]
	v_add_f32_e32 v108, 1.0, v108
	v_rcp_f32_e32 v117, v108
	v_mov_b32_e32 v108, v95
	v_pk_mul_f32 v[108:109], v[116:117], v[108:109]
	s_nop 0
	v_mul_f32_e32 v108, v108, v109
	v_cvt_pk_bf16_f32 v115, v2, v108
	v_lshlrev_b64 v[108:109], 12, v[190:191]
	v_lshl_add_u64 v[108:109], s[8:9], 0, v[108:109]
	v_lshl_add_u64 v[126:127], v[108:109], 0, v[140:141]
	flat_store_dwordx4 v[126:127], v[112:115]
	v_lshl_add_u64 v[108:109], v[188:189], 0, v[130:131]
	flat_load_dwordx4 v[120:123], v[108:109]
	v_lshl_add_u64 v[108:109], v[188:189], 0, v[132:133]
	flat_load_dwordx4 v[116:119], v[108:109]
	v_lshl_add_u64 v[108:109], v[188:189], 0, v[134:135]
	flat_load_dwordx4 v[112:115], v[108:109]
	v_lshl_add_u64 v[108:109], v[188:189], 0, v[138:139]
	flat_load_dwordx4 v[108:111], v[108:109]
	s_waitcnt vmcnt(0) lgkmcnt(0)
	v_lshlrev_b32_e32 v151, 16, v120
	v_mul_f32_e32 v2, 0xbfb8aa3b, v151
	v_exp_f32_e32 v2, v2
	v_mov_b32_e32 v152, v104
	v_mov_b32_e32 v150, v100
	v_mov_b32_e32 v175, v3
	v_add_f32_e32 v2, 1.0, v2
	v_rcp_f32_e32 v153, v2
	s_nop 0
	v_pk_mul_f32 v[150:151], v[152:153], v[150:151]
	s_nop 0
	v_mul_f32_e32 v2, v150, v151
	v_and_b32_e32 v151, 0xffff0000, v120
	v_mul_f32_e32 v104, 0xbfb8aa3b, v151
	v_exp_f32_e32 v104, v104
	v_mov_b32_e32 v152, v105
	v_mov_b32_e32 v150, v101
	v_mov_b32_e32 v120, v103
	v_add_f32_e32 v104, 1.0, v104
	v_rcp_f32_e32 v153, v104
	s_nop 0
	v_pk_mul_f32 v[104:105], v[152:153], v[150:151]
	s_nop 0
	v_mul_f32_e32 v104, v104, v105
	v_lshlrev_b32_e32 v151, 16, v121
	v_cvt_pk_bf16_f32 v104, v2, v104
	v_mul_f32_e32 v2, 0xbfb8aa3b, v151
	v_exp_f32_e32 v2, v2
	v_and_b32_e32 v121, 0xffff0000, v121
	v_mul_f32_e32 v105, 0xbfb8aa3b, v121
	v_exp_f32_e32 v105, v105
	v_add_f32_e32 v2, 1.0, v2
	v_rcp_f32_e32 v153, v2
	v_mov_b32_e32 v152, v106
	v_mov_b32_e32 v150, v102
	v_add_f32_e32 v105, 1.0, v105
	v_pk_mul_f32 v[150:151], v[152:153], v[150:151]
	s_nop 0
	v_mul_f32_e32 v2, v150, v151
	v_rcp_f32_e32 v151, v105
	v_mov_b32_e32 v150, v107
	v_pk_mul_f32 v[106:107], v[150:151], v[120:121]
	s_nop 0
	v_mul_f32_e32 v105, v106, v107
	v_lshlrev_b32_e32 v107, 16, v122
	v_cvt_pk_bf16_f32 v105, v2, v105
	v_mul_f32_e32 v2, 0xbfb8aa3b, v107
	v_exp_f32_e32 v2, v2
	v_mov_b32_e32 v120, v96
	v_mov_b32_e32 v106, v92
	v_add_f32_e32 v2, 1.0, v2
	v_rcp_f32_e32 v121, v2
	s_nop 0
	v_pk_mul_f32 v[106:107], v[120:121], v[106:107]
	s_nop 0
	v_mul_f32_e32 v2, v106, v107
	v_and_b32_e32 v107, 0xffff0000, v122
	v_mul_f32_e32 v96, 0xbfb8aa3b, v107
	v_exp_f32_e32 v96, v96
	v_mov_b32_e32 v120, v97
	v_mov_b32_e32 v106, v93
	v_add_f32_e32 v96, 1.0, v96
	v_rcp_f32_e32 v121, v96
	s_nop 0
	v_pk_mul_f32 v[96:97], v[120:121], v[106:107]
	s_nop 0
	v_mul_f32_e32 v96, v96, v97
	v_lshlrev_b32_e32 v97, 16, v123
	v_cvt_pk_bf16_f32 v106, v2, v96
	v_mul_f32_e32 v2, 0xbfb8aa3b, v97
	v_exp_f32_e32 v2, v2
	v_mov_b32_e32 v120, v98
	v_mov_b32_e32 v96, v94
	v_mov_b32_e32 v98, v100
	v_add_f32_e32 v2, 1.0, v2
	v_rcp_f32_e32 v121, v2
	s_nop 0
	v_pk_mul_f32 v[96:97], v[120:121], v[96:97]
	s_nop 0
	v_mul_f32_e32 v2, v96, v97
	v_and_b32_e32 v97, 0xffff0000, v123
	v_mul_f32_e32 v96, 0xbfb8aa3b, v97
	v_exp_f32_e32 v96, v96
	v_mov_b32_e32 v120, v99
	v_lshlrev_b32_e32 v99, 16, v116
	v_add_f32_e32 v96, 1.0, v96
	v_rcp_f32_e32 v121, v96
	v_mov_b32_e32 v96, v95
	v_pk_mul_f32 v[96:97], v[120:121], v[96:97]
	s_nop 0
	v_mul_f32_e32 v96, v96, v97
	v_cvt_pk_bf16_f32 v107, v2, v96
	v_mul_f32_e32 v2, 0xbfb8aa3b, v99
	v_exp_f32_e32 v2, v2
	v_lshlrev_b64 v[96:97], 12, v[148:149]
	v_lshl_add_u64 v[96:97], s[8:9], 0, v[96:97]
	v_lshl_add_u64 v[96:97], v[96:97], 0, v[140:141]
	v_add_f32_e32 v2, 1.0, v2
	flat_store_dwordx4 v[96:97], v[104:107]
	s_nop 1
	v_rcp_f32_e32 v105, v2
	v_mov_b32_e32 v104, v88
	v_pk_mul_f32 v[98:99], v[104:105], v[98:99]
	s_nop 0
	v_mul_f32_e32 v2, v98, v99
	v_and_b32_e32 v99, 0xffff0000, v116
	v_mul_f32_e32 v88, 0xbfb8aa3b, v99
	v_exp_f32_e32 v88, v88
	v_mov_b32_e32 v104, v89
	v_mov_b32_e32 v98, v101
	v_add_f32_e32 v88, 1.0, v88
	v_rcp_f32_e32 v105, v88
	s_nop 0
	v_pk_mul_f32 v[88:89], v[104:105], v[98:99]
	s_nop 0
	v_mul_f32_e32 v88, v88, v89
	v_lshlrev_b32_e32 v99, 16, v117
	v_cvt_pk_bf16_f32 v88, v2, v88
	v_mul_f32_e32 v2, 0xbfb8aa3b, v99
	v_exp_f32_e32 v2, v2
	v_mov_b32_e32 v104, v90
	v_mov_b32_e32 v98, v102
	v_add_f32_e32 v2, 1.0, v2
	v_rcp_f32_e32 v105, v2
	s_nop 0
	v_pk_mul_f32 v[98:99], v[104:105], v[98:99]
	s_nop 0
	v_mul_f32_e32 v2, v98, v99
	v_and_b32_e32 v99, 0xffff0000, v117
	v_mul_f32_e32 v89, 0xbfb8aa3b, v99
	v_exp_f32_e32 v89, v89
	v_mov_b32_e32 v104, v91
	v_mov_b32_e32 v98, v103
	v_add_f32_e32 v89, 1.0, v89
	v_rcp_f32_e32 v105, v89
	s_nop 0
	v_pk_mul_f32 v[90:91], v[104:105], v[98:99]
; __device__ __forceinline__ size_t pidx(size_t row, int col) { return ((size_t)(col >> 8) * MTOK + row) * PLD + (col & 255); }
; __device__ __forceinline__ float bflo(unsigned v) { return __uint_as_float(v << 16); }
; __device__ __forceinline__ float bfhi(unsigned v) { return __uint_as_float(v & 0xffff0000u); }
; __device__ __forceinline__ float siluf_(float x) { return x * __builtin_amdgcn_rcpf(1.0f + __expf(-x)); }
;   __device__ __forceinline__ void operator()(EPI_ARGS) const {
;     ...
;       for (int ai = 0; ai < 2; ++ai) {
;         u32x4 z[4];
; #pragma unroll
;         for (int m = 0; m < 4; ++m) z[m] = *(const u32x4*)(proj + pidx(row0 + ai * HALF + m * 16, PZ + c));
;         __builtin_amdgcn_sched_barrier(0);
; #pragma unroll
;         for (int m = 0; m < 4; ++m) {
;           const size_t row = row0 + ai * HALF + m * 16;
;           const f32x4 v0 = acc[ai][bj][m][0], v1 = acc[ai][bj][m][1];
;           u32x4 o;
;           o.x = pack2(v0[0] * s0[0] * siluf_(bflo(z[m].x)), v0[1] * s0[1] * siluf_(bfhi(z[m].x)));
;           o.y = pack2(v0[2] * s0[2] * siluf_(bflo(z[m].y)), v0[3] * s0[3] * siluf_(bfhi(z[m].y)));
;           o.z = pack2(v1[0] * s1[0] * siluf_(bflo(z[m].z)), v1[1] * s1[1] * siluf_(bfhi(z[m].z)));
;           o.w = pack2(v1[2] * s1[2] * siluf_(bflo(z[m].w)), v1[3] * s1[3] * siluf_(bfhi(z[m].w)));
;           *(u32x4*)(y0 + row * DM + c) = o;
;         }
	s_nop 0
	v_mul_f32_e32 v89, v90, v91
	v_lshlrev_b32_e32 v91, 16, v118
	v_cvt_pk_bf16_f32 v89, v2, v89
	v_mul_f32_e32 v2, 0xbfb8aa3b, v91
	v_exp_f32_e32 v2, v2
	v_mov_b32_e32 v98, v84
	v_mov_b32_e32 v90, v92
	v_add_f32_e32 v2, 1.0, v2
	v_rcp_f32_e32 v99, v2
	s_nop 0
	v_pk_mul_f32 v[90:91], v[98:99], v[90:91]
	s_nop 0
	v_mul_f32_e32 v2, v90, v91
	v_and_b32_e32 v91, 0xffff0000, v118
	v_mul_f32_e32 v84, 0xbfb8aa3b, v91
	v_exp_f32_e32 v84, v84
	v_mov_b32_e32 v98, v85
	v_mov_b32_e32 v90, v93
	v_add_f32_e32 v84, 1.0, v84
	v_rcp_f32_e32 v99, v84
	s_nop 0
	v_pk_mul_f32 v[84:85], v[98:99], v[90:91]
	s_nop 0
	v_mul_f32_e32 v84, v84, v85
	v_lshlrev_b32_e32 v85, 16, v119
	v_cvt_pk_bf16_f32 v90, v2, v84
	v_mul_f32_e32 v2, 0xbfb8aa3b, v85
	v_exp_f32_e32 v2, v2
	v_mov_b32_e32 v98, v86
	v_mov_b32_e32 v84, v94
	v_mov_b32_e32 v86, v80
	v_add_f32_e32 v2, 1.0, v2
	v_rcp_f32_e32 v99, v2
	s_nop 0
	v_pk_mul_f32 v[84:85], v[98:99], v[84:85]
	s_nop 0
	v_mul_f32_e32 v2, v84, v85
	v_and_b32_e32 v85, 0xffff0000, v119
	v_mul_f32_e32 v84, 0xbfb8aa3b, v85
	v_exp_f32_e32 v84, v84
	v_mov_b32_e32 v98, v87
	v_add_f32_e32 v84, 1.0, v84
	v_rcp_f32_e32 v99, v84
	v_mov_b32_e32 v84, v95
	v_pk_mul_f32 v[84:85], v[98:99], v[84:85]
	s_nop 0
	v_mul_f32_e32 v84, v84, v85
	v_cvt_pk_bf16_f32 v91, v2, v84
	v_lshlrev_b64 v[84:85], 12, v[146:147]
	v_lshl_add_u64 v[84:85], s[8:9], 0, v[84:85]
	v_lshl_add_u64 v[98:99], v[84:85], 0, v[140:141]
	v_lshlrev_b32_e32 v85, 16, v112
	v_mul_f32_e32 v2, 0xbfb8aa3b, v85
	v_exp_f32_e32 v2, v2
	v_mov_b32_e32 v84, v100
	flat_store_dwordx4 v[98:99], v[88:91]
	v_add_f32_e32 v2, 1.0, v2
	v_rcp_f32_e32 v87, v2
	s_nop 0
	v_pk_mul_f32 v[84:85], v[86:87], v[84:85]
	s_nop 0
	v_mul_f32_e32 v2, v84, v85
	v_and_b32_e32 v85, 0xffff0000, v112
	v_mul_f32_e32 v80, 0xbfb8aa3b, v85
	v_exp_f32_e32 v80, v80
	v_mov_b32_e32 v86, v81
	v_mov_b32_e32 v84, v101
	v_add_f32_e32 v80, 1.0, v80
	v_rcp_f32_e32 v87, v80
	s_nop 0
	v_pk_mul_f32 v[80:81], v[86:87], v[84:85]
	s_nop 0
	v_mul_f32_e32 v80, v80, v81
	v_lshlrev_b32_e32 v85, 16, v113
	v_cvt_pk_bf16_f32 v80, v2, v80
	v_mul_f32_e32 v2, 0xbfb8aa3b, v85
	v_exp_f32_e32 v2, v2
	v_mov_b32_e32 v86, v82
	v_mov_b32_e32 v84, v102
	v_add_f32_e32 v2, 1.0, v2
	v_rcp_f32_e32 v87, v2
	s_nop 0
	v_pk_mul_f32 v[84:85], v[86:87], v[84:85]
	s_nop 0
	v_mul_f32_e32 v2, v84, v85
	v_and_b32_e32 v85, 0xffff0000, v113
	v_mul_f32_e32 v81, 0xbfb8aa3b, v85
	v_exp_f32_e32 v81, v81
	v_mov_b32_e32 v86, v83
	v_mov_b32_e32 v84, v103
	v_add_f32_e32 v81, 1.0, v81
	v_rcp_f32_e32 v87, v81
	s_nop 0
	v_pk_mul_f32 v[82:83], v[86:87], v[84:85]
	s_nop 0
	v_mul_f32_e32 v81, v82, v83
	v_lshlrev_b32_e32 v83, 16, v114
	v_cvt_pk_bf16_f32 v81, v2, v81
	v_mul_f32_e32 v2, 0xbfb8aa3b, v83
	v_exp_f32_e32 v2, v2
	v_mov_b32_e32 v84, v76
	v_mov_b32_e32 v82, v92
	v_add_f32_e32 v2, 1.0, v2
	v_rcp_f32_e32 v85, v2
	s_nop 0
	v_pk_mul_f32 v[82:83], v[84:85], v[82:83]
	s_nop 0
	v_mul_f32_e32 v2, v82, v83
	v_and_b32_e32 v83, 0xffff0000, v114
	v_mul_f32_e32 v76, 0xbfb8aa3b, v83
	v_exp_f32_e32 v76, v76
	v_mov_b32_e32 v84, v77
	v_mov_b32_e32 v82, v93
	v_add_f32_e32 v76, 1.0, v76
	v_rcp_f32_e32 v85, v76
	s_nop 0
	v_pk_mul_f32 v[76:77], v[84:85], v[82:83]
	s_nop 0
	v_mul_f32_e32 v76, v76, v77
	v_lshlrev_b32_e32 v77, 16, v115
	v_cvt_pk_bf16_f32 v82, v2, v76
	v_mul_f32_e32 v2, 0xbfb8aa3b, v77
	v_exp_f32_e32 v2, v2
	v_mov_b32_e32 v84, v78
	v_mov_b32_e32 v76, v94
	v_mov_b32_e32 v78, v72
	v_add_f32_e32 v2, 1.0, v2
	v_rcp_f32_e32 v85, v2
	s_nop 0
	v_pk_mul_f32 v[76:77], v[84:85], v[76:77]
	s_nop 0
	v_mul_f32_e32 v2, v76, v77
	v_and_b32_e32 v77, 0xffff0000, v115
	v_mul_f32_e32 v76, 0xbfb8aa3b, v77
	v_exp_f32_e32 v76, v76
	v_mov_b32_e32 v84, v79
	v_add_f32_e32 v76, 1.0, v76
	v_rcp_f32_e32 v85, v76
	v_mov_b32_e32 v76, v95
	v_pk_mul_f32 v[76:77], v[84:85], v[76:77]
	s_nop 0
	v_mul_f32_e32 v76, v76, v77
	v_cvt_pk_bf16_f32 v83, v2, v76
	v_lshlrev_b64 v[76:77], 12, v[144:145]
	v_lshl_add_u64 v[76:77], s[8:9], 0, v[76:77]
	v_lshl_add_u64 v[104:105], v[76:77], 0, v[140:141]
	v_lshlrev_b32_e32 v77, 16, v108
	v_mul_f32_e32 v2, 0xbfb8aa3b, v77
	v_exp_f32_e32 v2, v2
	v_mov_b32_e32 v76, v100
	flat_store_dwordx4 v[104:105], v[80:83]
	v_add_f32_e32 v2, 1.0, v2
	v_rcp_f32_e32 v79, v2
	s_nop 0
	v_pk_mul_f32 v[76:77], v[78:79], v[76:77]
	s_nop 0
	v_mul_f32_e32 v2, v76, v77
	v_and_b32_e32 v77, 0xffff0000, v108
	v_mul_f32_e32 v72, 0xbfb8aa3b, v77
	v_exp_f32_e32 v72, v72
	v_mov_b32_e32 v78, v73
	v_mov_b32_e32 v76, v101
	v_add_f32_e32 v72, 1.0, v72
	v_rcp_f32_e32 v79, v72
	s_nop 0
	v_pk_mul_f32 v[72:73], v[78:79], v[76:77]
	s_nop 0
	v_mul_f32_e32 v72, v72, v73
	v_lshlrev_b32_e32 v77, 16, v109
	v_cvt_pk_bf16_f32 v72, v2, v72
	v_mul_f32_e32 v2, 0xbfb8aa3b, v77
	v_exp_f32_e32 v2, v2
	v_mov_b32_e32 v78, v74
	v_mov_b32_e32 v76, v102
	v_add_f32_e32 v2, 1.0, v2
	v_rcp_f32_e32 v79, v2
	s_nop 0
	v_pk_mul_f32 v[76:77], v[78:79], v[76:77]
	s_nop 0
	v_mul_f32_e32 v2, v76, v77
	v_and_b32_e32 v77, 0xffff0000, v109
	v_mul_f32_e32 v73, 0xbfb8aa3b, v77
	v_exp_f32_e32 v73, v73
	v_mov_b32_e32 v78, v75
	v_mov_b32_e32 v76, v103
	v_add_f32_e32 v73, 1.0, v73
	v_rcp_f32_e32 v79, v73
	s_nop 0
	v_pk_mul_f32 v[74:75], v[78:79], v[76:77]
	s_nop 0
	v_mul_f32_e32 v73, v74, v75
	v_lshlrev_b32_e32 v75, 16, v110
	v_cvt_pk_bf16_f32 v73, v2, v73
	v_mul_f32_e32 v2, 0xbfb8aa3b, v75
	v_exp_f32_e32 v2, v2
	v_mov_b32_e32 v76, v68
	v_mov_b32_e32 v74, v92
	v_add_f32_e32 v2, 1.0, v2
	v_rcp_f32_e32 v77, v2
	s_nop 0
	v_pk_mul_f32 v[74:75], v[76:77], v[74:75]
	s_nop 0
	v_mul_f32_e32 v2, v74, v75
	v_and_b32_e32 v75, 0xffff0000, v110
	v_mul_f32_e32 v68, 0xbfb8aa3b, v75
	v_exp_f32_e32 v68, v68
	v_mov_b32_e32 v76, v69
	v_mov_b32_e32 v74, v93
	v_add_f32_e32 v68, 1.0, v68
; __device__ __forceinline__ size_t pidx(size_t row, int col) { return ((size_t)(col >> 8) * MTOK + row) * PLD + (col & 255); }
; __device__ __forceinline__ float bflo(unsigned v) { return __uint_as_float(v << 16); }
; __device__ __forceinline__ float bfhi(unsigned v) { return __uint_as_float(v & 0xffff0000u); }
; __device__ __forceinline__ float siluf_(float x) { return x * __builtin_amdgcn_rcpf(1.0f + __expf(-x)); }
;   __device__ __forceinline__ void operator()(EPI_ARGS) const {
;     ...
;     for (int bj = 0; bj < 2; ++bj) {
;       const int c = col0 + bj * HALF;
;       const f32x4 s0 = *(const f32x4*)(psc + c), s1 = *(const f32x4*)(psc + c + 4);
; #pragma unroll
;       for (int ai = 0; ai < 2; ++ai) {
;         u32x4 z[4];
; #pragma unroll
;         for (int m = 0; m < 4; ++m) z[m] = *(const u32x4*)(proj + pidx(row0 + ai * HALF + m * 16, PZ + c));
;         __builtin_amdgcn_sched_barrier(0);
; #pragma unroll
;         for (int m = 0; m < 4; ++m) {
;           const size_t row = row0 + ai * HALF + m * 16;
;           const f32x4 v0 = acc[ai][bj][m][0], v1 = acc[ai][bj][m][1];
;           u32x4 o;
;           o.x = pack2(v0[0] * s0[0] * siluf_(bflo(z[m].x)), v0[1] * s0[1] * siluf_(bfhi(z[m].x)));
;           o.y = pack2(v0[2] * s0[2] * siluf_(bflo(z[m].y)), v0[3] * s0[3] * siluf_(bfhi(z[m].y)));
;           o.z = pack2(v1[0] * s1[0] * siluf_(bflo(z[m].z)), v1[1] * s1[1] * siluf_(bfhi(z[m].z)));
;           o.w = pack2(v1[2] * s1[2] * siluf_(bflo(z[m].w)), v1[3] * s1[3] * siluf_(bfhi(z[m].w)));
;           *(u32x4*)(y0 + row * DM + c) = o;
;         }
	v_rcp_f32_e32 v77, v68
	s_nop 0
	v_pk_mul_f32 v[68:69], v[76:77], v[74:75]
	s_nop 0
	v_mul_f32_e32 v68, v68, v69
	v_lshlrev_b32_e32 v69, 16, v111
	v_cvt_pk_bf16_f32 v74, v2, v68
	v_mul_f32_e32 v2, 0xbfb8aa3b, v69
	v_exp_f32_e32 v2, v2
	v_mov_b32_e32 v76, v70
	v_mov_b32_e32 v68, v94
	v_add_f32_e32 v2, 1.0, v2
	v_rcp_f32_e32 v77, v2
	s_nop 0
	v_pk_mul_f32 v[68:69], v[76:77], v[68:69]
	s_nop 0
	v_mul_f32_e32 v2, v68, v69
	v_and_b32_e32 v69, 0xffff0000, v111
	v_mul_f32_e32 v68, 0xbfb8aa3b, v69
	v_exp_f32_e32 v68, v68
	v_mov_b32_e32 v76, v71
	v_add_f32_e32 v68, 1.0, v68
	v_rcp_f32_e32 v77, v68
	v_mov_b32_e32 v68, v95
	v_lshl_add_u64 v[94:95], s[2:3], 0, v[174:175]
	v_pk_mul_f32 v[68:69], v[76:77], v[68:69]
	s_nop 0
	v_mul_f32_e32 v68, v68, v69
	v_cvt_pk_bf16_f32 v75, v2, v68
	v_lshlrev_b64 v[68:69], 12, v[142:143]
	v_lshl_add_u64 v[68:69], s[8:9], 0, v[68:69]
	v_lshl_add_u64 v[92:93], v[68:69], 0, v[140:141]
	flat_store_dwordx4 v[92:93], v[72:75]
	v_lshl_add_u64 v[76:77], v[94:95], 0, v[178:179]
	global_load_dwordx4 v[68:71], v[176:177], off offset:528
	global_load_dwordx4 v[72:75], v[176:177], off offset:512
	flat_load_dwordx4 v[88:91], v[76:77]
	v_lshl_add_u64 v[76:77], v[94:95], 0, v[180:181]
	flat_load_dwordx4 v[84:87], v[76:77]
	v_lshl_add_u64 v[76:77], v[94:95], 0, v[182:183]
	flat_load_dwordx4 v[80:83], v[76:77]
	v_lshl_add_u64 v[76:77], v[94:95], 0, v[184:185]
	flat_load_dwordx4 v[76:79], v[76:77]
	s_waitcnt vmcnt(0) lgkmcnt(0)
	v_lshlrev_b32_e32 v101, 16, v88
	v_mul_f32_e32 v2, 0xbfb8aa3b, v101
	v_exp_f32_e32 v2, v2
	v_mov_b32_e32 v102, v64
	v_mov_b32_e32 v100, v72
	v_add_f32_e32 v2, 1.0, v2
	v_rcp_f32_e32 v103, v2
	s_nop 0
	v_pk_mul_f32 v[100:101], v[102:103], v[100:101]
	s_nop 0
	v_mul_f32_e32 v2, v100, v101
	v_and_b32_e32 v101, 0xffff0000, v88
	v_mul_f32_e32 v64, 0xbfb8aa3b, v101
	v_exp_f32_e32 v64, v64
	v_mov_b32_e32 v102, v65
	v_mov_b32_e32 v100, v73
	v_mov_b32_e32 v88, v75
	v_add_f32_e32 v64, 1.0, v64
	v_rcp_f32_e32 v103, v64
	s_nop 0
	v_pk_mul_f32 v[64:65], v[102:103], v[100:101]
	s_nop 0
	v_mul_f32_e32 v64, v64, v65
	v_lshlrev_b32_e32 v101, 16, v89
	v_cvt_pk_bf16_f32 v64, v2, v64
	v_mul_f32_e32 v2, 0xbfb8aa3b, v101
	v_exp_f32_e32 v2, v2
	v_and_b32_e32 v89, 0xffff0000, v89
	v_mul_f32_e32 v65, 0xbfb8aa3b, v89
	v_exp_f32_e32 v65, v65
	v_add_f32_e32 v2, 1.0, v2
	v_rcp_f32_e32 v103, v2
	v_mov_b32_e32 v102, v66
	v_mov_b32_e32 v100, v74
	v_add_f32_e32 v65, 1.0, v65
	v_pk_mul_f32 v[100:101], v[102:103], v[100:101]
	s_nop 0
	v_mul_f32_e32 v2, v100, v101
	v_rcp_f32_e32 v101, v65
	v_mov_b32_e32 v100, v67
	v_pk_mul_f32 v[66:67], v[100:101], v[88:89]
	s_nop 0
	v_mul_f32_e32 v65, v66, v67
	v_lshlrev_b32_e32 v67, 16, v90
	v_cvt_pk_bf16_f32 v65, v2, v65
	v_mul_f32_e32 v2, 0xbfb8aa3b, v67
	v_exp_f32_e32 v2, v2
	v_mov_b32_e32 v88, v60
	v_mov_b32_e32 v66, v68
	v_add_f32_e32 v2, 1.0, v2
	v_rcp_f32_e32 v89, v2
	s_nop 0
	v_pk_mul_f32 v[66:67], v[88:89], v[66:67]
	s_nop 0
	v_mul_f32_e32 v2, v66, v67
	v_and_b32_e32 v67, 0xffff0000, v90
	v_mul_f32_e32 v60, 0xbfb8aa3b, v67
	v_exp_f32_e32 v60, v60
	v_mov_b32_e32 v88, v61
	v_mov_b32_e32 v66, v69
	v_add_f32_e32 v60, 1.0, v60
	v_rcp_f32_e32 v89, v60
	s_nop 0
	v_pk_mul_f32 v[60:61], v[88:89], v[66:67]
	s_nop 0
	v_mul_f32_e32 v60, v60, v61
	v_lshlrev_b32_e32 v61, 16, v91
	v_cvt_pk_bf16_f32 v66, v2, v60
	v_mul_f32_e32 v2, 0xbfb8aa3b, v61
	v_exp_f32_e32 v2, v2
	v_mov_b32_e32 v88, v62
	v_mov_b32_e32 v60, v70
	v_mov_b32_e32 v62, v56
	v_add_f32_e32 v2, 1.0, v2
	v_rcp_f32_e32 v89, v2
	s_nop 0
	v_pk_mul_f32 v[60:61], v[88:89], v[60:61]
	s_nop 0
	v_mul_f32_e32 v2, v60, v61
	v_and_b32_e32 v61, 0xffff0000, v91
	v_mul_f32_e32 v60, 0xbfb8aa3b, v61
	v_exp_f32_e32 v60, v60
	v_mov_b32_e32 v88, v63
	v_add_f32_e32 v60, 1.0, v60
	v_rcp_f32_e32 v89, v60
	v_mov_b32_e32 v60, v71
	v_pk_mul_f32 v[60:61], v[88:89], v[60:61]
	s_nop 0
	v_mul_f32_e32 v60, v60, v61
	v_lshlrev_b32_e32 v61, 16, v84
	v_cvt_pk_bf16_f32 v67, v2, v60
	v_mul_f32_e32 v2, 0xbfb8aa3b, v61
	v_exp_f32_e32 v2, v2
	v_mov_b32_e32 v60, v72
	flat_store_dwordx4 v[136:137], v[64:67] offset:256
	v_add_f32_e32 v2, 1.0, v2
	v_rcp_f32_e32 v63, v2
	s_nop 0
	v_pk_mul_f32 v[60:61], v[62:63], v[60:61]
	s_nop 0
	v_mul_f32_e32 v2, v60, v61
	v_and_b32_e32 v61, 0xffff0000, v84
	v_mul_f32_e32 v56, 0xbfb8aa3b, v61
	v_exp_f32_e32 v56, v56
	v_mov_b32_e32 v62, v57
	v_mov_b32_e32 v60, v73
	v_add_f32_e32 v56, 1.0, v56
	v_rcp_f32_e32 v63, v56
	s_nop 0
	v_pk_mul_f32 v[56:57], v[62:63], v[60:61]
	s_nop 0
	v_mul_f32_e32 v56, v56, v57
	v_lshlrev_b32_e32 v61, 16, v85
	v_cvt_pk_bf16_f32 v56, v2, v56
	v_mul_f32_e32 v2, 0xbfb8aa3b, v61
	v_exp_f32_e32 v2, v2
	v_mov_b32_e32 v62, v58
	v_mov_b32_e32 v60, v74
	v_add_f32_e32 v2, 1.0, v2
	v_rcp_f32_e32 v63, v2
	s_nop 0
	v_pk_mul_f32 v[60:61], v[62:63], v[60:61]
	s_nop 0
	v_mul_f32_e32 v2, v60, v61
	v_and_b32_e32 v61, 0xffff0000, v85
	v_mul_f32_e32 v57, 0xbfb8aa3b, v61
	v_exp_f32_e32 v57, v57
	v_mov_b32_e32 v62, v59
	v_mov_b32_e32 v60, v75
	v_add_f32_e32 v57, 1.0, v57
	v_rcp_f32_e32 v63, v57
	s_nop 0
	v_pk_mul_f32 v[58:59], v[62:63], v[60:61]
	s_nop 0
	v_mul_f32_e32 v57, v58, v59
	v_lshlrev_b32_e32 v59, 16, v86
	v_cvt_pk_bf16_f32 v57, v2, v57
	v_mul_f32_e32 v2, 0xbfb8aa3b, v59
	v_exp_f32_e32 v2, v2
	v_mov_b32_e32 v60, v52
	v_mov_b32_e32 v58, v68
	v_add_f32_e32 v2, 1.0, v2
	v_rcp_f32_e32 v61, v2
	s_nop 0
	v_pk_mul_f32 v[58:59], v[60:61], v[58:59]
	s_nop 0
	v_mul_f32_e32 v2, v58, v59
	v_and_b32_e32 v59, 0xffff0000, v86
	v_mul_f32_e32 v52, 0xbfb8aa3b, v59
	v_exp_f32_e32 v52, v52
	v_mov_b32_e32 v60, v53
	v_mov_b32_e32 v58, v69
	v_add_f32_e32 v52, 1.0, v52
	v_rcp_f32_e32 v61, v52
	s_nop 0
	v_pk_mul_f32 v[52:53], v[60:61], v[58:59]
	s_nop 0
	v_mul_f32_e32 v52, v52, v53
; __device__ __forceinline__ size_t pidx(size_t row, int col) { return ((size_t)(col >> 8) * MTOK + row) * PLD + (col & 255); }
; __device__ __forceinline__ float bflo(unsigned v) { return __uint_as_float(v << 16); }
; __device__ __forceinline__ float bfhi(unsigned v) { return __uint_as_float(v & 0xffff0000u); }
; __device__ __forceinline__ float siluf_(float x) { return x * __builtin_amdgcn_rcpf(1.0f + __expf(-x)); }
;   __device__ __forceinline__ void operator()(EPI_ARGS) const {
;     ...
;       for (int ai = 0; ai < 2; ++ai) {
;         u32x4 z[4];
; #pragma unroll
;         for (int m = 0; m < 4; ++m) z[m] = *(const u32x4*)(proj + pidx(row0 + ai * HALF + m * 16, PZ + c));
;         __builtin_amdgcn_sched_barrier(0);
; #pragma unroll
;         for (int m = 0; m < 4; ++m) {
;           const size_t row = row0 + ai * HALF + m * 16;
;           const f32x4 v0 = acc[ai][bj][m][0], v1 = acc[ai][bj][m][1];
;           u32x4 o;
;           o.x = pack2(v0[0] * s0[0] * siluf_(bflo(z[m].x)), v0[1] * s0[1] * siluf_(bfhi(z[m].x)));
;           o.y = pack2(v0[2] * s0[2] * siluf_(bflo(z[m].y)), v0[3] * s0[3] * siluf_(bfhi(z[m].y)));
;           o.z = pack2(v1[0] * s1[0] * siluf_(bflo(z[m].z)), v1[1] * s1[1] * siluf_(bfhi(z[m].z)));
;           o.w = pack2(v1[2] * s1[2] * siluf_(bflo(z[m].w)), v1[3] * s1[3] * siluf_(bfhi(z[m].w)));
;           *(u32x4*)(y0 + row * DM + c) = o;
;         }
	v_lshlrev_b32_e32 v53, 16, v87
	v_cvt_pk_bf16_f32 v58, v2, v52
	v_mul_f32_e32 v2, 0xbfb8aa3b, v53
	v_exp_f32_e32 v2, v2
	v_mov_b32_e32 v60, v54
	v_mov_b32_e32 v52, v70
	v_mov_b32_e32 v54, v48
	v_add_f32_e32 v2, 1.0, v2
	v_rcp_f32_e32 v61, v2
	s_nop 0
	v_pk_mul_f32 v[52:53], v[60:61], v[52:53]
	s_nop 0
	v_mul_f32_e32 v2, v52, v53
	v_and_b32_e32 v53, 0xffff0000, v87
	v_mul_f32_e32 v52, 0xbfb8aa3b, v53
	v_exp_f32_e32 v52, v52
	v_mov_b32_e32 v60, v55
	v_add_f32_e32 v52, 1.0, v52
	v_rcp_f32_e32 v61, v52
	v_mov_b32_e32 v52, v71
	v_pk_mul_f32 v[52:53], v[60:61], v[52:53]
	s_nop 0
	v_mul_f32_e32 v52, v52, v53
	v_lshlrev_b32_e32 v53, 16, v80
	v_cvt_pk_bf16_f32 v59, v2, v52
	v_mul_f32_e32 v2, 0xbfb8aa3b, v53
	v_exp_f32_e32 v2, v2
	v_mov_b32_e32 v52, v72
	flat_store_dwordx4 v[124:125], v[56:59] offset:256
	v_add_f32_e32 v2, 1.0, v2
	v_rcp_f32_e32 v55, v2
	s_nop 0
	v_pk_mul_f32 v[52:53], v[54:55], v[52:53]
	s_nop 0
	v_mul_f32_e32 v2, v52, v53
	v_and_b32_e32 v53, 0xffff0000, v80
	v_mul_f32_e32 v48, 0xbfb8aa3b, v53
	v_exp_f32_e32 v48, v48
	v_mov_b32_e32 v54, v49
	v_mov_b32_e32 v52, v73
	v_add_f32_e32 v48, 1.0, v48
	v_rcp_f32_e32 v55, v48
	s_nop 0
	v_pk_mul_f32 v[48:49], v[54:55], v[52:53]
	s_nop 0
	v_mul_f32_e32 v48, v48, v49
	v_lshlrev_b32_e32 v53, 16, v81
	v_cvt_pk_bf16_f32 v48, v2, v48
	v_mul_f32_e32 v2, 0xbfb8aa3b, v53
	v_exp_f32_e32 v2, v2
	v_mov_b32_e32 v54, v50
	v_mov_b32_e32 v52, v74
	v_add_f32_e32 v2, 1.0, v2
	v_rcp_f32_e32 v55, v2
	s_nop 0
	v_pk_mul_f32 v[52:53], v[54:55], v[52:53]
	s_nop 0
	v_mul_f32_e32 v2, v52, v53
	v_and_b32_e32 v53, 0xffff0000, v81
	v_mul_f32_e32 v49, 0xbfb8aa3b, v53
	v_exp_f32_e32 v49, v49
	v_mov_b32_e32 v54, v51
	v_mov_b32_e32 v52, v75
	v_add_f32_e32 v49, 1.0, v49
	v_rcp_f32_e32 v55, v49
	s_nop 0
	v_pk_mul_f32 v[50:51], v[54:55], v[52:53]
	s_nop 0
	v_mul_f32_e32 v49, v50, v51
	v_lshlrev_b32_e32 v51, 16, v82
	v_cvt_pk_bf16_f32 v49, v2, v49
	v_mul_f32_e32 v2, 0xbfb8aa3b, v51
	v_exp_f32_e32 v2, v2
	v_mov_b32_e32 v52, v44
	v_mov_b32_e32 v50, v68
	v_add_f32_e32 v2, 1.0, v2
	v_rcp_f32_e32 v53, v2
	s_nop 0
	v_pk_mul_f32 v[50:51], v[52:53], v[50:51]
	s_nop 0
	v_mul_f32_e32 v2, v50, v51
	v_and_b32_e32 v51, 0xffff0000, v82
	v_mul_f32_e32 v44, 0xbfb8aa3b, v51
	v_exp_f32_e32 v44, v44
	v_mov_b32_e32 v52, v45
	v_mov_b32_e32 v50, v69
	v_add_f32_e32 v44, 1.0, v44
	v_rcp_f32_e32 v53, v44
	s_nop 0
	v_pk_mul_f32 v[44:45], v[52:53], v[50:51]
	s_nop 0
	v_mul_f32_e32 v44, v44, v45
	v_lshlrev_b32_e32 v45, 16, v83
	v_cvt_pk_bf16_f32 v50, v2, v44
	v_mul_f32_e32 v2, 0xbfb8aa3b, v45
	v_exp_f32_e32 v2, v2
	v_mov_b32_e32 v52, v46
	v_mov_b32_e32 v44, v70
	v_mov_b32_e32 v46, v40
	v_add_f32_e32 v2, 1.0, v2
	v_rcp_f32_e32 v53, v2
	s_nop 0
	v_pk_mul_f32 v[44:45], v[52:53], v[44:45]
	s_nop 0
	v_mul_f32_e32 v2, v44, v45
	v_and_b32_e32 v45, 0xffff0000, v83
	v_mul_f32_e32 v44, 0xbfb8aa3b, v45
	v_exp_f32_e32 v44, v44
	v_mov_b32_e32 v52, v47
	v_add_f32_e32 v44, 1.0, v44
	v_rcp_f32_e32 v53, v44
	v_mov_b32_e32 v44, v71
	v_pk_mul_f32 v[44:45], v[52:53], v[44:45]
	s_nop 0
	v_mul_f32_e32 v44, v44, v45
	v_lshlrev_b32_e32 v45, 16, v76
	v_cvt_pk_bf16_f32 v51, v2, v44
	v_mul_f32_e32 v2, 0xbfb8aa3b, v45
	v_exp_f32_e32 v2, v2
	v_mov_b32_e32 v44, v72
	flat_store_dwordx4 v[128:129], v[48:51] offset:256
	v_add_f32_e32 v2, 1.0, v2
	v_rcp_f32_e32 v47, v2
	s_nop 0
	v_pk_mul_f32 v[44:45], v[46:47], v[44:45]
	s_nop 0
	v_mul_f32_e32 v2, v44, v45
	v_and_b32_e32 v45, 0xffff0000, v76
	v_mul_f32_e32 v40, 0xbfb8aa3b, v45
	v_exp_f32_e32 v40, v40
	v_mov_b32_e32 v46, v41
	v_mov_b32_e32 v44, v73
	v_add_f32_e32 v40, 1.0, v40
	v_rcp_f32_e32 v47, v40
	s_nop 0
	v_pk_mul_f32 v[40:41], v[46:47], v[44:45]
	s_nop 0
	v_mul_f32_e32 v40, v40, v41
	v_lshlrev_b32_e32 v45, 16, v77
	v_cvt_pk_bf16_f32 v40, v2, v40
	v_mul_f32_e32 v2, 0xbfb8aa3b, v45
	v_exp_f32_e32 v2, v2
	v_mov_b32_e32 v46, v42
	v_mov_b32_e32 v44, v74
	v_add_f32_e32 v2, 1.0, v2
	v_rcp_f32_e32 v47, v2
	s_nop 0
	v_pk_mul_f32 v[44:45], v[46:47], v[44:45]
	s_nop 0
	v_mul_f32_e32 v2, v44, v45
	v_and_b32_e32 v45, 0xffff0000, v77
	v_mul_f32_e32 v41, 0xbfb8aa3b, v45
	v_exp_f32_e32 v41, v41
	v_mov_b32_e32 v46, v43
	v_mov_b32_e32 v44, v75
	v_add_f32_e32 v41, 1.0, v41
	v_rcp_f32_e32 v47, v41
	s_nop 0
	v_pk_mul_f32 v[42:43], v[46:47], v[44:45]
	s_nop 0
	v_mul_f32_e32 v41, v42, v43
	v_lshlrev_b32_e32 v43, 16, v78
	v_cvt_pk_bf16_f32 v41, v2, v41
	v_mul_f32_e32 v2, 0xbfb8aa3b, v43
	v_exp_f32_e32 v2, v2
	v_mov_b32_e32 v44, v36
	v_mov_b32_e32 v42, v68
	v_add_f32_e32 v2, 1.0, v2
	v_rcp_f32_e32 v45, v2
	s_nop 0
	v_pk_mul_f32 v[42:43], v[44:45], v[42:43]
	s_nop 0
	v_mul_f32_e32 v2, v42, v43
	v_and_b32_e32 v43, 0xffff0000, v78
	v_mul_f32_e32 v36, 0xbfb8aa3b, v43
	v_exp_f32_e32 v36, v36
	v_mov_b32_e32 v44, v37
	v_mov_b32_e32 v42, v69
	v_add_f32_e32 v36, 1.0, v36
	v_rcp_f32_e32 v45, v36
	s_nop 0
	v_pk_mul_f32 v[36:37], v[44:45], v[42:43]
	s_nop 0
	v_mul_f32_e32 v36, v36, v37
	v_lshlrev_b32_e32 v37, 16, v79
	v_cvt_pk_bf16_f32 v42, v2, v36
	v_mul_f32_e32 v2, 0xbfb8aa3b, v37
	v_exp_f32_e32 v2, v2
	v_mov_b32_e32 v44, v38
	v_mov_b32_e32 v36, v70
	v_add_f32_e32 v2, 1.0, v2
	v_rcp_f32_e32 v45, v2
	s_nop 0
	v_pk_mul_f32 v[36:37], v[44:45], v[36:37]
	s_nop 0
	v_mul_f32_e32 v2, v36, v37
	v_and_b32_e32 v37, 0xffff0000, v79
	v_mul_f32_e32 v36, 0xbfb8aa3b, v37
	v_exp_f32_e32 v36, v36
	v_mov_b32_e32 v44, v39
	v_add_f32_e32 v36, 1.0, v36
	v_rcp_f32_e32 v45, v36
	v_mov_b32_e32 v36, v71
	v_pk_mul_f32 v[36:37], v[44:45], v[36:37]
	s_nop 0
	v_mul_f32_e32 v36, v36, v37
	v_cvt_pk_bf16_f32 v43, v2, v36
	flat_store_dwordx4 v[126:127], v[40:43] offset:256
	v_lshl_add_u64 v[36:37], v[94:95], 0, v[130:131]
	flat_load_dwordx4 v[48:51], v[36:37]
	v_lshl_add_u64 v[36:37], v[94:95], 0, v[132:133]
	flat_load_dwordx4 v[44:47], v[36:37]
	v_lshl_add_u64 v[36:37], v[94:95], 0, v[134:135]
	flat_load_dwordx4 v[40:43], v[36:37]
	v_lshl_add_u64 v[36:37], v[94:95], 0, v[138:139]
	flat_load_dwordx4 v[36:39], v[36:37]
	s_waitcnt vmcnt(0) lgkmcnt(0)
; __device__ __forceinline__ size_t pidx(size_t row, int col) { return ((size_t)(col >> 8) * MTOK + row) * PLD + (col & 255); }
; __device__ __forceinline__ float bflo(unsigned v) { return __uint_as_float(v << 16); }
; __device__ __forceinline__ float bfhi(unsigned v) { return __uint_as_float(v & 0xffff0000u); }
; __device__ __forceinline__ float siluf_(float x) { return x * __builtin_amdgcn_rcpf(1.0f + __expf(-x)); }
;   __device__ __forceinline__ void operator()(EPI_ARGS) const {
;     ...
;       for (int ai = 0; ai < 2; ++ai) {
;         u32x4 z[4];
; #pragma unroll
;         for (int m = 0; m < 4; ++m) z[m] = *(const u32x4*)(proj + pidx(row0 + ai * HALF + m * 16, PZ + c));
;         __builtin_amdgcn_sched_barrier(0);
; #pragma unroll
;         for (int m = 0; m < 4; ++m) {
;           const size_t row = row0 + ai * HALF + m * 16;
;           const f32x4 v0 = acc[ai][bj][m][0], v1 = acc[ai][bj][m][1];
;           u32x4 o;
;           o.x = pack2(v0[0] * s0[0] * siluf_(bflo(z[m].x)), v0[1] * s0[1] * siluf_(bfhi(z[m].x)));
;           o.y = pack2(v0[2] * s0[2] * siluf_(bflo(z[m].y)), v0[3] * s0[3] * siluf_(bfhi(z[m].y)));
;           o.z = pack2(v1[0] * s1[0] * siluf_(bflo(z[m].z)), v1[1] * s1[1] * siluf_(bfhi(z[m].z)));
;           o.w = pack2(v1[2] * s1[2] * siluf_(bflo(z[m].w)), v1[3] * s1[3] * siluf_(bfhi(z[m].w)));
;           *(u32x4*)(y0 + row * DM + c) = o;
;         }
	v_lshlrev_b32_e32 v53, 16, v48
	v_mul_f32_e32 v2, 0xbfb8aa3b, v53
	v_exp_f32_e32 v2, v2
	v_mov_b32_e32 v54, v32
	v_mov_b32_e32 v52, v72
	s_and_b64 vcc, exec, s[18:19]
	v_add_f32_e32 v2, 1.0, v2
	v_rcp_f32_e32 v55, v2
	s_mov_b32 s33, s16
	s_mov_b32 s2, s14
	s_mov_b64 s[4:5], s[22:23]
	v_pk_mul_f32 v[52:53], v[54:55], v[52:53]
	v_mov_b32_e32 v54, v33
	v_mul_f32_e32 v2, v52, v53
	v_and_b32_e32 v53, 0xffff0000, v48
	v_mul_f32_e32 v32, 0xbfb8aa3b, v53
	v_exp_f32_e32 v32, v32
	v_mov_b32_e32 v52, v73
	v_mov_b32_e32 v48, v75
	s_mov_b64 s[6:7], s[20:21]
	v_add_f32_e32 v32, 1.0, v32
	v_rcp_f32_e32 v55, v32
	s_nop 0
	v_pk_mul_f32 v[32:33], v[54:55], v[52:53]
	s_nop 0
	v_mul_f32_e32 v32, v32, v33
	v_lshlrev_b32_e32 v53, 16, v49
	v_cvt_pk_bf16_f32 v32, v2, v32
	v_mul_f32_e32 v2, 0xbfb8aa3b, v53
	v_exp_f32_e32 v2, v2
	v_and_b32_e32 v49, 0xffff0000, v49
	v_mul_f32_e32 v33, 0xbfb8aa3b, v49
	v_exp_f32_e32 v33, v33
	v_add_f32_e32 v2, 1.0, v2
	v_rcp_f32_e32 v55, v2
	v_mov_b32_e32 v54, v34
	v_mov_b32_e32 v52, v74
	v_add_f32_e32 v33, 1.0, v33
	v_pk_mul_f32 v[52:53], v[54:55], v[52:53]
	s_nop 0
	v_mul_f32_e32 v2, v52, v53
	v_rcp_f32_e32 v53, v33
	v_mov_b32_e32 v52, v35
	v_pk_mul_f32 v[34:35], v[52:53], v[48:49]
	s_nop 0
	v_mul_f32_e32 v33, v34, v35
	v_lshlrev_b32_e32 v35, 16, v50
	v_cvt_pk_bf16_f32 v33, v2, v33
	v_mul_f32_e32 v2, 0xbfb8aa3b, v35
	v_exp_f32_e32 v2, v2
	v_mov_b32_e32 v48, v28
	v_mov_b32_e32 v34, v68
	v_add_f32_e32 v2, 1.0, v2
	v_rcp_f32_e32 v49, v2
	s_nop 0
	v_pk_mul_f32 v[34:35], v[48:49], v[34:35]
	s_nop 0
	v_mul_f32_e32 v2, v34, v35
	v_and_b32_e32 v35, 0xffff0000, v50
	v_mul_f32_e32 v28, 0xbfb8aa3b, v35
	v_exp_f32_e32 v28, v28
	v_mov_b32_e32 v48, v29
	v_mov_b32_e32 v34, v69
	v_add_f32_e32 v28, 1.0, v28
	v_rcp_f32_e32 v49, v28
	s_nop 0
	v_pk_mul_f32 v[28:29], v[48:49], v[34:35]
	s_nop 0
	v_mul_f32_e32 v28, v28, v29
	v_lshlrev_b32_e32 v29, 16, v51
	v_cvt_pk_bf16_f32 v34, v2, v28
	v_mul_f32_e32 v2, 0xbfb8aa3b, v29
	v_exp_f32_e32 v2, v2
	v_mov_b32_e32 v48, v30
	v_mov_b32_e32 v28, v70
	v_mov_b32_e32 v30, v24
	v_add_f32_e32 v2, 1.0, v2
	v_rcp_f32_e32 v49, v2
	s_nop 0
	v_pk_mul_f32 v[28:29], v[48:49], v[28:29]
	s_nop 0
	v_mul_f32_e32 v2, v28, v29
	v_and_b32_e32 v29, 0xffff0000, v51
	v_mul_f32_e32 v28, 0xbfb8aa3b, v29
	v_exp_f32_e32 v28, v28
	v_mov_b32_e32 v48, v31
	v_add_f32_e32 v28, 1.0, v28
	v_rcp_f32_e32 v49, v28
	v_mov_b32_e32 v28, v71
	v_pk_mul_f32 v[28:29], v[48:49], v[28:29]
	s_nop 0
	v_mul_f32_e32 v28, v28, v29
	v_lshlrev_b32_e32 v29, 16, v44
	v_cvt_pk_bf16_f32 v35, v2, v28
	v_mul_f32_e32 v2, 0xbfb8aa3b, v29
	v_exp_f32_e32 v2, v2
	v_mov_b32_e32 v28, v72
	flat_store_dwordx4 v[96:97], v[32:35] offset:256
	v_add_f32_e32 v2, 1.0, v2
	v_rcp_f32_e32 v31, v2
	s_nop 0
	v_pk_mul_f32 v[28:29], v[30:31], v[28:29]
	s_nop 0
	v_mul_f32_e32 v2, v28, v29
	v_and_b32_e32 v29, 0xffff0000, v44
	v_mul_f32_e32 v24, 0xbfb8aa3b, v29
	v_exp_f32_e32 v24, v24
	v_mov_b32_e32 v30, v25
	v_mov_b32_e32 v28, v73
	v_add_f32_e32 v24, 1.0, v24
	v_rcp_f32_e32 v31, v24
	s_nop 0
	v_pk_mul_f32 v[24:25], v[30:31], v[28:29]
	s_nop 0
	v_mul_f32_e32 v24, v24, v25
	v_lshlrev_b32_e32 v29, 16, v45
	v_cvt_pk_bf16_f32 v24, v2, v24
	v_mul_f32_e32 v2, 0xbfb8aa3b, v29
	v_exp_f32_e32 v2, v2
	v_mov_b32_e32 v30, v26
	v_mov_b32_e32 v28, v74
	v_add_f32_e32 v2, 1.0, v2
	v_rcp_f32_e32 v31, v2
	s_nop 0
	v_pk_mul_f32 v[28:29], v[30:31], v[28:29]
	s_nop 0
	v_mul_f32_e32 v2, v28, v29
	v_and_b32_e32 v29, 0xffff0000, v45
	v_mul_f32_e32 v25, 0xbfb8aa3b, v29
	v_exp_f32_e32 v25, v25
	v_mov_b32_e32 v30, v27
	v_mov_b32_e32 v28, v75
	v_add_f32_e32 v25, 1.0, v25
	v_rcp_f32_e32 v31, v25
	s_nop 0
	v_pk_mul_f32 v[26:27], v[30:31], v[28:29]
	s_nop 0
	v_mul_f32_e32 v25, v26, v27
	v_lshlrev_b32_e32 v27, 16, v46
	v_cvt_pk_bf16_f32 v25, v2, v25
	v_mul_f32_e32 v2, 0xbfb8aa3b, v27
	v_exp_f32_e32 v2, v2
	v_mov_b32_e32 v28, v20
	v_mov_b32_e32 v26, v68
	v_add_f32_e32 v2, 1.0, v2
	v_rcp_f32_e32 v29, v2
	s_nop 0
	v_pk_mul_f32 v[26:27], v[28:29], v[26:27]
	s_nop 0
	v_mul_f32_e32 v2, v26, v27
	v_and_b32_e32 v27, 0xffff0000, v46
	v_mul_f32_e32 v20, 0xbfb8aa3b, v27
	v_exp_f32_e32 v20, v20
	v_mov_b32_e32 v28, v21
	v_mov_b32_e32 v26, v69
	v_add_f32_e32 v20, 1.0, v20
	v_rcp_f32_e32 v29, v20
	s_nop 0
	v_pk_mul_f32 v[20:21], v[28:29], v[26:27]
	s_nop 0
	v_mul_f32_e32 v20, v20, v21
	v_lshlrev_b32_e32 v21, 16, v47
	v_cvt_pk_bf16_f32 v26, v2, v20
	v_mul_f32_e32 v2, 0xbfb8aa3b, v21
	v_exp_f32_e32 v2, v2
	v_mov_b32_e32 v28, v22
	v_mov_b32_e32 v20, v70
	v_mov_b32_e32 v22, v16
	v_add_f32_e32 v2, 1.0, v2
	v_rcp_f32_e32 v29, v2
	s_nop 0
	v_pk_mul_f32 v[20:21], v[28:29], v[20:21]
	s_nop 0
	v_mul_f32_e32 v2, v20, v21
	v_and_b32_e32 v21, 0xffff0000, v47
	v_mul_f32_e32 v20, 0xbfb8aa3b, v21
	v_exp_f32_e32 v20, v20
	v_mov_b32_e32 v28, v23
	v_add_f32_e32 v20, 1.0, v20
	v_rcp_f32_e32 v29, v20
	v_mov_b32_e32 v20, v71
	v_pk_mul_f32 v[20:21], v[28:29], v[20:21]
	s_nop 0
	v_mul_f32_e32 v20, v20, v21
	v_lshlrev_b32_e32 v21, 16, v40
	v_cvt_pk_bf16_f32 v27, v2, v20
	v_mul_f32_e32 v2, 0xbfb8aa3b, v21
	v_exp_f32_e32 v2, v2
	v_mov_b32_e32 v20, v72
	flat_store_dwordx4 v[98:99], v[24:27] offset:256
; __device__ __forceinline__ size_t pidx(size_t row, int col) { return ((size_t)(col >> 8) * MTOK + row) * PLD + (col & 255); }
; __device__ __forceinline__ float bflo(unsigned v) { return __uint_as_float(v << 16); }
; __device__ __forceinline__ float bfhi(unsigned v) { return __uint_as_float(v & 0xffff0000u); }
; __device__ __forceinline__ float siluf_(float x) { return x * __builtin_amdgcn_rcpf(1.0f + __expf(-x)); }
; #define PG8_WAIT_V(n) asm volatile("s_waitcnt vmcnt(" #n ")" ::: "memory")
; #define PG8_BAR __builtin_amdgcn_s_barrier()
; template <class Epi, class AddrA, class AddrB>
; __device__ __forceinline__ void gemm_phase(const Sched S, const int lda, const int ldb, const int K, const AddrA addrA,
;                                            const AddrB addrB, const Epi E) {
;     ...
;     if (!has_next) break;
;     if (!(Epi::KEEP && cur.br + 1 < S.nbr)) {
; #pragma unroll
;       for (int a = 0; a < 2; ++a)
; #pragma unroll
;         for (int b = 0; b < 2; ++b)
; #pragma unroll
;           for (int m = 0; m < 4; ++m)
; #pragma unroll
;             for (int n = 0; n < 2; ++n) acc[a][b][m][n] = (f32x4){0.f, 0.f, 0.f, 0.f};
;     }
;     cur = nxt; cA = nA; cB = nB; ++ui;
;   }
;   PG8_WAIT_V(0);
;   if (wr == 0) PG8_BAR;
;   PG8_BAR;
;   __device__ __forceinline__ void operator()(EPI_ARGS) const {
;     ...
;       for (int ai = 0; ai < 2; ++ai) {
;         u32x4 z[4];
; #pragma unroll
;         for (int m = 0; m < 4; ++m) z[m] = *(const u32x4*)(proj + pidx(row0 + ai * HALF + m * 16, PZ + c));
;         __builtin_amdgcn_sched_barrier(0);
; #pragma unroll
;         for (int m = 0; m < 4; ++m) {
;           const size_t row = row0 + ai * HALF + m * 16;
;           const f32x4 v0 = acc[ai][bj][m][0], v1 = acc[ai][bj][m][1];
;           u32x4 o;
;           o.x = pack2(v0[0] * s0[0] * siluf_(bflo(z[m].x)), v0[1] * s0[1] * siluf_(bfhi(z[m].x)));
;           o.y = pack2(v0[2] * s0[2] * siluf_(bflo(z[m].y)), v0[3] * s0[3] * siluf_(bfhi(z[m].y)));
;           o.z = pack2(v1[0] * s1[0] * siluf_(bflo(z[m].z)), v1[1] * s1[1] * siluf_(bfhi(z[m].z)));
;           o.w = pack2(v1[2] * s1[2] * siluf_(bflo(z[m].w)), v1[3] * s1[3] * siluf_(bfhi(z[m].w)));
;           *(u32x4*)(y0 + row * DM + c) = o;
;         }
	v_add_f32_e32 v2, 1.0, v2
	v_rcp_f32_e32 v23, v2
	s_nop 0
	v_pk_mul_f32 v[20:21], v[22:23], v[20:21]
	s_nop 0
	v_mul_f32_e32 v2, v20, v21
	v_and_b32_e32 v21, 0xffff0000, v40
	v_mul_f32_e32 v16, 0xbfb8aa3b, v21
	v_exp_f32_e32 v16, v16
	v_mov_b32_e32 v22, v17
	v_mov_b32_e32 v20, v73
	v_add_f32_e32 v16, 1.0, v16
	v_rcp_f32_e32 v23, v16
	s_nop 0
	v_pk_mul_f32 v[16:17], v[22:23], v[20:21]
	s_nop 0
	v_mul_f32_e32 v16, v16, v17
	v_lshlrev_b32_e32 v21, 16, v41
	v_cvt_pk_bf16_f32 v16, v2, v16
	v_mul_f32_e32 v2, 0xbfb8aa3b, v21
	v_exp_f32_e32 v2, v2
	v_mov_b32_e32 v22, v18
	v_mov_b32_e32 v20, v74
	v_add_f32_e32 v2, 1.0, v2
	v_rcp_f32_e32 v23, v2
	s_nop 0
	v_pk_mul_f32 v[20:21], v[22:23], v[20:21]
	s_nop 0
	v_mul_f32_e32 v2, v20, v21
	v_and_b32_e32 v21, 0xffff0000, v41
	v_mul_f32_e32 v17, 0xbfb8aa3b, v21
	v_exp_f32_e32 v17, v17
	v_mov_b32_e32 v22, v19
	v_mov_b32_e32 v20, v75
	v_add_f32_e32 v17, 1.0, v17
	v_rcp_f32_e32 v23, v17
	s_nop 0
	v_pk_mul_f32 v[18:19], v[22:23], v[20:21]
	s_nop 0
	v_mul_f32_e32 v17, v18, v19
	v_lshlrev_b32_e32 v19, 16, v42
	v_cvt_pk_bf16_f32 v17, v2, v17
	v_mul_f32_e32 v2, 0xbfb8aa3b, v19
	v_exp_f32_e32 v2, v2
	v_mov_b32_e32 v20, v12
	v_mov_b32_e32 v18, v68
	v_add_f32_e32 v2, 1.0, v2
	v_rcp_f32_e32 v21, v2
	s_nop 0
	v_pk_mul_f32 v[18:19], v[20:21], v[18:19]
	s_nop 0
	v_mul_f32_e32 v2, v18, v19
	v_and_b32_e32 v19, 0xffff0000, v42
	v_mul_f32_e32 v12, 0xbfb8aa3b, v19
	v_exp_f32_e32 v12, v12
	v_mov_b32_e32 v20, v13
	v_mov_b32_e32 v18, v69
	v_add_f32_e32 v12, 1.0, v12
	v_rcp_f32_e32 v21, v12
	s_nop 0
	v_pk_mul_f32 v[12:13], v[20:21], v[18:19]
	s_nop 0
	v_mul_f32_e32 v12, v12, v13
	v_lshlrev_b32_e32 v13, 16, v43
	v_cvt_pk_bf16_f32 v18, v2, v12
	v_mul_f32_e32 v2, 0xbfb8aa3b, v13
	v_exp_f32_e32 v2, v2
	v_mov_b32_e32 v20, v14
	v_mov_b32_e32 v12, v70
	v_mov_b32_e32 v14, v8
	v_add_f32_e32 v2, 1.0, v2
	v_rcp_f32_e32 v21, v2
	s_nop 0
	v_pk_mul_f32 v[12:13], v[20:21], v[12:13]
	s_nop 0
	v_mul_f32_e32 v2, v12, v13
	v_and_b32_e32 v13, 0xffff0000, v43
	v_mul_f32_e32 v12, 0xbfb8aa3b, v13
	v_exp_f32_e32 v12, v12
	v_mov_b32_e32 v20, v15
	v_add_f32_e32 v12, 1.0, v12
	v_rcp_f32_e32 v21, v12
	v_mov_b32_e32 v12, v71
	v_pk_mul_f32 v[12:13], v[20:21], v[12:13]
	s_nop 0
	v_mul_f32_e32 v12, v12, v13
	v_lshlrev_b32_e32 v13, 16, v36
	v_cvt_pk_bf16_f32 v19, v2, v12
	v_mul_f32_e32 v2, 0xbfb8aa3b, v13
	v_exp_f32_e32 v2, v2
	v_mov_b32_e32 v12, v72
	flat_store_dwordx4 v[104:105], v[16:19] offset:256
	v_add_f32_e32 v2, 1.0, v2
	v_rcp_f32_e32 v15, v2
	s_nop 0
	v_pk_mul_f32 v[12:13], v[14:15], v[12:13]
	s_nop 0
	v_mul_f32_e32 v2, v12, v13
	v_and_b32_e32 v13, 0xffff0000, v36
	v_mul_f32_e32 v8, 0xbfb8aa3b, v13
	v_exp_f32_e32 v8, v8
	v_mov_b32_e32 v14, v9
	v_mov_b32_e32 v12, v73
	v_add_f32_e32 v8, 1.0, v8
	v_rcp_f32_e32 v15, v8
	s_nop 0
	v_pk_mul_f32 v[8:9], v[14:15], v[12:13]
	s_nop 0
	v_mul_f32_e32 v8, v8, v9
	v_lshlrev_b32_e32 v13, 16, v37
	v_cvt_pk_bf16_f32 v8, v2, v8
	v_mul_f32_e32 v2, 0xbfb8aa3b, v13
	v_exp_f32_e32 v2, v2
	v_mov_b32_e32 v14, v10
	v_mov_b32_e32 v12, v74
	v_add_f32_e32 v2, 1.0, v2
	v_rcp_f32_e32 v15, v2
	s_nop 0
	v_pk_mul_f32 v[12:13], v[14:15], v[12:13]
	s_nop 0
	v_mul_f32_e32 v2, v12, v13
	v_and_b32_e32 v13, 0xffff0000, v37
	v_mul_f32_e32 v9, 0xbfb8aa3b, v13
	v_exp_f32_e32 v9, v9
	v_mov_b32_e32 v14, v11
	v_mov_b32_e32 v12, v75
	v_add_f32_e32 v9, 1.0, v9
	v_rcp_f32_e32 v15, v9
	s_nop 0
	v_pk_mul_f32 v[10:11], v[14:15], v[12:13]
	s_nop 0
	v_mul_f32_e32 v9, v10, v11
	v_lshlrev_b32_e32 v11, 16, v38
	v_cvt_pk_bf16_f32 v9, v2, v9
	v_mul_f32_e32 v2, 0xbfb8aa3b, v11
	v_exp_f32_e32 v2, v2
	v_mov_b32_e32 v12, v4
	v_mov_b32_e32 v10, v68
	v_add_f32_e32 v2, 1.0, v2
	v_rcp_f32_e32 v13, v2
	s_nop 0
	v_pk_mul_f32 v[10:11], v[12:13], v[10:11]
	s_nop 0
	v_mul_f32_e32 v2, v10, v11
	v_and_b32_e32 v11, 0xffff0000, v38
	v_mul_f32_e32 v4, 0xbfb8aa3b, v11
	v_exp_f32_e32 v4, v4
	v_mov_b32_e32 v12, v5
	v_mov_b32_e32 v10, v69
	v_add_f32_e32 v4, 1.0, v4
	v_rcp_f32_e32 v13, v4
	s_nop 0
	v_pk_mul_f32 v[4:5], v[12:13], v[10:11]
	s_nop 0
	v_mul_f32_e32 v4, v4, v5
	v_lshlrev_b32_e32 v5, 16, v39
	v_cvt_pk_bf16_f32 v10, v2, v4
	v_mul_f32_e32 v2, 0xbfb8aa3b, v5
	v_exp_f32_e32 v2, v2
	v_mov_b32_e32 v12, v6
	v_mov_b32_e32 v4, v70
	v_add_f32_e32 v2, 1.0, v2
	v_rcp_f32_e32 v13, v2
	s_nop 0
	v_pk_mul_f32 v[4:5], v[12:13], v[4:5]
	s_nop 0
	v_mul_f32_e32 v2, v4, v5
	v_and_b32_e32 v5, 0xffff0000, v39
	v_mul_f32_e32 v4, 0xbfb8aa3b, v5
	v_exp_f32_e32 v4, v4
	v_mov_b32_e32 v12, v7
	v_add_f32_e32 v4, 1.0, v4
	v_rcp_f32_e32 v13, v4
	v_mov_b32_e32 v4, v71
	v_pk_mul_f32 v[4:5], v[12:13], v[4:5]
	s_nop 0
	v_mul_f32_e32 v4, v4, v5
	v_cvt_pk_bf16_f32 v11, v2, v4
	flat_store_dwordx4 v[92:93], v[8:11] offset:256
	s_cbranch_vccz .LBB0_482
	s_waitcnt vmcnt(0)
	v_readlane_b32 s44, v244, 59
	v_readlane_b32 s40, v243, 18
	s_cmpk_gt_u32 s24, 0xff
	s_mov_b32 s43, 0x800000
	v_readlane_b32 s45, v244, 60
	v_readlane_b32 s46, v244, 61
	v_readlane_b32 s47, v244, 62
	v_readlane_b32 s48, v244, 63
	v_readlane_b32 s49, v243, 0
	v_readlane_b32 s50, v243, 1
	v_readlane_b32 s51, v243, 2
	v_readlane_b32 s41, v243, 19
	s_cbranch_scc1 .LBB0_489
	s_barrier

; #define PG8_WAIT_V(n) asm volatile("s_waitcnt vmcnt(" #n ")" ::: "memory")
; #define PG8_WAIT_L(n) asm volatile("s_waitcnt lgkmcnt(" #n ")" ::: "memory")
; #define PG8_BAR __builtin_amdgcn_s_barrier()
; #define PG8_SCHED __builtin_amdgcn_sched_barrier(0)
; template <class Epi, class AddrA, class AddrB>
; __device__ __forceinline__ void gemm_phase(const Sched S, const int lda, const int ldb, const int K, const AddrA addrA,
;                                            const AddrB addrB, const Epi E) {
;     ...
;       PG8_LDB(B0, 0, 0); PG8_SCHED; PG8_LDA(At, 0, 0); PG8_STAGE(PG8_SA(1, 1), a1 + hstepA, voffA);
;       PG8_WAIT_L(8); PG8_BAR; PG8_WAIT_L(0); PG8_MMA(0, 0, At, B0); PG8_BAR; PG8_SCHED;
;       PG8_LDB(B1, 0, 1); PG8_STAGE(PG8_SB(0, 0), b2, voffB);
;       PG8_BAR; PG8_WAIT_L(0); PG8_MMA(0, 1, At, B1); PG8_BAR;
;       PG8_LDA(At, 0, 1); PG8_STAGE(PG8_SA(0, 0), a2, voffA);
;       PG8_BAR; PG8_WAIT_L(0); PG8_MMA(1, 0, At, B0); PG8_BAR; PG8_SCHED;
;       PG8_STAGE(PG8_SB(0, 1), b2 + hstepB, voffB);
;       PG8_WAIT_V(6); PG8_BAR; PG8_MMA(1, 1, At, B1); PG8_BAR;
;       PG8_LDB(B0, 1, 0); PG8_SCHED; PG8_LDA(At, 1, 0); PG8_STAGE(PG8_SA(0, 1), a2 + hstepA, voffA);
;       PG8_WAIT_L(8); PG8_BAR; PG8_WAIT_L(0); PG8_MMA(0, 0, At, B0); PG8_BAR; PG8_SCHED;
.LBB0_543:
	s_add_i32 s43, 0, 0x10000
	v_add_u32_e32 v0, s43, v167
	ds_read_b128 v[132:135], v0
	ds_read_b128 v[136:139], v0 offset:1024
	ds_read_b128 v[140:143], v0 offset:2048
	ds_read_b128 v[144:147], v0 offset:3072
	v_lshl_add_u64 v[0:1], s[2:3], 0, v[180:181]
	s_add_i32 m0, s28, 0xc000
	ds_read_b128 v[148:151], v188
	ds_read_b128 v[152:155], v188 offset:1024
	ds_read_b128 v[156:159], v188 offset:2048
	ds_read_b128 v[160:163], v188 offset:3072
	ds_read_b128 v[182:185], v188 offset:4096
	ds_read_b128 v[190:193], v188 offset:5120
	ds_read_b128 v[194:197], v188 offset:6144
	ds_read_b128 v[212:215], v188 offset:7168
	global_load_lds_dwordx4 v[0:1], off
	v_lshl_add_u64 v[0:1], s[2:3], 0, v[178:179]
	s_add_i32 m0, s28, 0xe000
	s_nop 0
	global_load_lds_dwordx4 v[0:1], off
	s_waitcnt lgkmcnt(6)
	s_setprio 1
	s_barrier
	v_mfma_f32_16x16x32_bf16 v[128:131], v[132:135], v[148:151], v[128:131]
	v_mfma_f32_16x16x32_bf16 v[128:131], v[136:139], v[152:155], v[128:131]
	s_waitcnt lgkmcnt(0)
	v_mfma_f32_16x16x32_bf16 v[120:123], v[132:135], v[156:159], v[120:123]
	v_mfma_f32_16x16x32_bf16 v[120:123], v[136:139], v[160:163], v[120:123]
	v_mfma_f32_16x16x32_bf16 v[112:115], v[132:135], v[182:185], v[112:115]
	v_mfma_f32_16x16x32_bf16 v[112:115], v[136:139], v[190:193], v[112:115]
	v_mfma_f32_16x16x32_bf16 v[104:107], v[132:135], v[194:197], v[104:107]
	v_mfma_f32_16x16x32_bf16 v[104:107], v[136:139], v[212:215], v[104:107]
	v_mfma_f32_16x16x32_bf16 v[124:127], v[140:143], v[148:151], v[124:127]
	v_mfma_f32_16x16x32_bf16 v[124:127], v[144:147], v[152:155], v[124:127]
	v_mfma_f32_16x16x32_bf16 v[116:119], v[140:143], v[156:159], v[116:119]
	v_mfma_f32_16x16x32_bf16 v[116:119], v[144:147], v[160:163], v[116:119]
	v_mfma_f32_16x16x32_bf16 v[108:111], v[140:143], v[182:185], v[108:111]
	v_mfma_f32_16x16x32_bf16 v[108:111], v[144:147], v[190:193], v[108:111]
	v_mfma_f32_16x16x32_bf16 v[100:103], v[140:143], v[194:197], v[100:103]
	v_mfma_f32_16x16x32_bf16 v[100:103], v[144:147], v[212:215], v[100:103]
	s_barrier
	s_setprio 0
	s_add_u32 s4, s2, 0xfff80080
	s_addc_u32 s5, s3, -1
	s_cmp_eq_u32 s42, 28
	s_cselect_b32 s7, s1, s5
	s_cselect_b32 s6, s9, s4
	s_cselect_b32 s5, s13, s41
	s_cselect_b32 s4, s15, s33
	s_add_i32 s46, 0, 0x14000
	v_add_u32_e32 v0, s46, v167
	s_add_i32 s43, s43, s27
	ds_read_b128 v[216:219], v0
	ds_read_b128 v[220:223], v0 offset:1024
	ds_read_b128 v[224:227], v0 offset:2048
	ds_read_b128 v[228:231], v0 offset:3072
	v_lshl_add_u64 v[0:1], s[4:5], 0, v[172:173]
	s_mov_b32 m0, s43
	v_lshl_add_u64 v[232:233], s[4:5], 0, v[168:169]
	global_load_lds_dwordx4 v[0:1], off
	s_add_i32 m0, s43, 0x2000
	s_nop 0
	global_load_lds_dwordx4 v[232:233], off
	s_mov_b32 m0, s28
	v_lshl_add_u64 v[234:235], s[6:7], 0, v[174:175]
	s_waitcnt vmcnt(10)
	s_waitcnt lgkmcnt(0)
	s_setprio 1
	s_barrier
	v_mfma_f32_16x16x32_bf16 v[96:99], v[216:219], v[148:151], v[96:99]
	v_mfma_f32_16x16x32_bf16 v[96:99], v[220:223], v[152:155], v[96:99]
	s_waitcnt lgkmcnt(0)
	v_mfma_f32_16x16x32_bf16 v[88:91], v[216:219], v[156:159], v[88:91]
	v_mfma_f32_16x16x32_bf16 v[88:91], v[220:223], v[160:163], v[88:91]
	v_mfma_f32_16x16x32_bf16 v[80:83], v[216:219], v[182:185], v[80:83]
	v_mfma_f32_16x16x32_bf16 v[80:83], v[220:223], v[190:193], v[80:83]
	v_mfma_f32_16x16x32_bf16 v[72:75], v[216:219], v[194:197], v[72:75]
	v_mfma_f32_16x16x32_bf16 v[72:75], v[220:223], v[212:215], v[72:75]
	v_mfma_f32_16x16x32_bf16 v[92:95], v[224:227], v[148:151], v[92:95]
	v_mfma_f32_16x16x32_bf16 v[92:95], v[228:231], v[152:155], v[92:95]
	v_mfma_f32_16x16x32_bf16 v[84:87], v[224:227], v[156:159], v[84:87]
	v_mfma_f32_16x16x32_bf16 v[84:87], v[228:231], v[160:163], v[84:87]
	v_mfma_f32_16x16x32_bf16 v[76:79], v[224:227], v[182:185], v[76:79]
	v_mfma_f32_16x16x32_bf16 v[76:79], v[228:231], v[190:193], v[76:79]
	v_mfma_f32_16x16x32_bf16 v[68:71], v[224:227], v[194:197], v[68:71]
	v_mfma_f32_16x16x32_bf16 v[68:71], v[228:231], v[212:215], v[68:71]
	s_barrier
	s_setprio 0
	ds_read_b128 v[148:151], v188 offset:16384
	ds_read_b128 v[152:155], v188 offset:17408
	ds_read_b128 v[156:159], v188 offset:18432
	ds_read_b128 v[160:163], v188 offset:19456
	ds_read_b128 v[182:185], v188 offset:20480
	ds_read_b128 v[190:193], v188 offset:21504
	ds_read_b128 v[194:197], v188 offset:22528
	ds_read_b128 v[212:215], v188 offset:23552
	global_load_lds_dwordx4 v[234:235], off
	v_lshl_add_u64 v[236:237], s[6:7], 0, v[170:171]
	s_mov_b32 m0, s29
	s_nop 0
	global_load_lds_dwordx4 v[236:237], off
	s_add_u32 s44, s4, 0x80000
	s_addc_u32 s45, s5, 0
	s_add_i32 s43, s46, s27
	v_lshl_add_u64 v[246:247], s[44:45], 0, v[172:173]
	s_mov_b32 m0, s43
	s_nop 0
	global_load_lds_dwordx4 v[246:247], off
	v_lshl_add_u64 v[246:247], s[44:45], 0, v[168:169]
	s_add_i32 m0, s43, 0x2000
	s_nop 0
	global_load_lds_dwordx4 v[246:247], off
	s_add_i32 s43, 0, 0x18000
	v_add_u32_e32 v2, s43, v167
	s_waitcnt vmcnt(8)
	s_waitcnt lgkmcnt(0)
	s_setprio 1
	s_barrier
; #define PG8_WAIT_V(n) asm volatile("s_waitcnt vmcnt(" #n ")" ::: "memory")
; #define PG8_WAIT_L(n) asm volatile("s_waitcnt lgkmcnt(" #n ")" ::: "memory")
; #define PG8_BAR __builtin_amdgcn_s_barrier()
; #define PG8_SCHED __builtin_amdgcn_sched_barrier(0)
; template <class Epi, class AddrA, class AddrB>
; __device__ __forceinline__ void gemm_phase(const Sched S, const int lda, const int ldb, const int K, const AddrA addrA,
;                                            const AddrB addrB, const Epi E) {
;     ...
;       PG8_BAR; PG8_WAIT_L(0); PG8_MMA(1, 0, At, B0); PG8_BAR; PG8_SCHED;
;       PG8_STAGE(PG8_SB(0, 1), b2 + hstepB, voffB);
;       PG8_WAIT_V(6); PG8_BAR; PG8_MMA(1, 1, At, B1); PG8_BAR;
;       PG8_LDB(B0, 1, 0); PG8_SCHED; PG8_LDA(At, 1, 0); PG8_STAGE(PG8_SA(0, 1), a2 + hstepA, voffA);
;       PG8_WAIT_L(8); PG8_BAR; PG8_WAIT_L(0); PG8_MMA(0, 0, At, B0); PG8_BAR; PG8_SCHED;
;       PG8_LDB(B1, 1, 1); PG8_STAGE(PG8_SB(1, 0), b3, voffB);
;       PG8_BAR; PG8_WAIT_L(0); PG8_MMA(0, 1, At, B1); PG8_BAR;
;       PG8_LDA(At, 1, 1); PG8_STAGE(PG8_SA(1, 0), a3, voffA);
;       PG8_BAR; PG8_WAIT_L(0); PG8_MMA(1, 0, At, B0); PG8_BAR; PG8_SCHED;
	v_mfma_f32_16x16x32_bf16 v[64:67], v[132:135], v[148:151], v[64:67]
	v_mfma_f32_16x16x32_bf16 v[64:67], v[136:139], v[152:155], v[64:67]
	s_waitcnt lgkmcnt(0)
	v_mfma_f32_16x16x32_bf16 v[56:59], v[132:135], v[156:159], v[56:59]
	v_mfma_f32_16x16x32_bf16 v[56:59], v[136:139], v[160:163], v[56:59]
	v_mfma_f32_16x16x32_bf16 v[48:51], v[132:135], v[182:185], v[48:51]
	v_mfma_f32_16x16x32_bf16 v[48:51], v[136:139], v[190:193], v[48:51]
	v_mfma_f32_16x16x32_bf16 v[40:43], v[132:135], v[194:197], v[40:43]
	v_mfma_f32_16x16x32_bf16 v[40:43], v[136:139], v[212:215], v[40:43]
	v_mfma_f32_16x16x32_bf16 v[60:63], v[140:143], v[148:151], v[60:63]
	v_mfma_f32_16x16x32_bf16 v[60:63], v[144:147], v[152:155], v[60:63]
	v_mfma_f32_16x16x32_bf16 v[52:55], v[140:143], v[156:159], v[52:55]
	v_mfma_f32_16x16x32_bf16 v[52:55], v[144:147], v[160:163], v[52:55]
	v_mfma_f32_16x16x32_bf16 v[44:47], v[140:143], v[182:185], v[44:47]
	v_mfma_f32_16x16x32_bf16 v[44:47], v[144:147], v[190:193], v[44:47]
	v_mfma_f32_16x16x32_bf16 v[36:39], v[140:143], v[194:197], v[36:39]
	v_mfma_f32_16x16x32_bf16 v[36:39], v[144:147], v[212:215], v[36:39]
	v_mfma_f32_16x16x32_bf16 v[32:35], v[216:219], v[148:151], v[32:35]
	v_mfma_f32_16x16x32_bf16 v[32:35], v[220:223], v[152:155], v[32:35]
	v_mfma_f32_16x16x32_bf16 v[24:27], v[216:219], v[156:159], v[24:27]
	v_mfma_f32_16x16x32_bf16 v[24:27], v[220:223], v[160:163], v[24:27]
	v_mfma_f32_16x16x32_bf16 v[16:19], v[216:219], v[182:185], v[16:19]
	v_mfma_f32_16x16x32_bf16 v[16:19], v[220:223], v[190:193], v[16:19]
	v_mfma_f32_16x16x32_bf16 v[8:11], v[216:219], v[194:197], v[8:11]
	v_mfma_f32_16x16x32_bf16 v[8:11], v[220:223], v[212:215], v[8:11]
	v_mfma_f32_16x16x32_bf16 v[28:31], v[224:227], v[148:151], v[28:31]
	v_mfma_f32_16x16x32_bf16 v[28:31], v[228:231], v[152:155], v[28:31]
	v_mfma_f32_16x16x32_bf16 v[20:23], v[224:227], v[156:159], v[20:23]
	v_mfma_f32_16x16x32_bf16 v[20:23], v[228:231], v[160:163], v[20:23]
	v_mfma_f32_16x16x32_bf16 v[12:15], v[224:227], v[182:185], v[12:15]
	v_mfma_f32_16x16x32_bf16 v[12:15], v[228:231], v[190:193], v[12:15]
	v_mfma_f32_16x16x32_bf16 v[4:7], v[224:227], v[194:197], v[4:7]
	v_mfma_f32_16x16x32_bf16 v[4:7], v[228:231], v[212:215], v[4:7]
	s_barrier
	s_setprio 0
	ds_read_b128 v[132:135], v2
	ds_read_b128 v[136:139], v2 offset:1024
	ds_read_b128 v[140:143], v2 offset:2048
	ds_read_b128 v[144:147], v2 offset:3072
	s_add_u32 s6, s6, 0x80000
	s_addc_u32 s7, s7, 0
	s_mov_b32 m0, s30
	v_lshl_add_u64 v[216:217], s[6:7], 0, v[174:175]
	ds_read_b128 v[148:151], v188 offset:32768
	ds_read_b128 v[152:155], v188 offset:33792
	ds_read_b128 v[156:159], v188 offset:34816
	ds_read_b128 v[160:163], v188 offset:35840
	ds_read_b128 v[182:185], v188 offset:36864
	ds_read_b128 v[190:193], v188 offset:37888
	ds_read_b128 v[194:197], v188 offset:38912
	ds_read_b128 v[212:215], v188 offset:39936
	global_load_lds_dwordx4 v[216:217], off
	v_lshl_add_u64 v[216:217], s[6:7], 0, v[170:171]
	s_mov_b32 m0, s31
	s_nop 0
	global_load_lds_dwordx4 v[216:217], off
	s_waitcnt lgkmcnt(6)
	s_setprio 1
	s_barrier
	v_mfma_f32_16x16x32_bf16 v[128:131], v[132:135], v[148:151], v[128:131]
	v_mfma_f32_16x16x32_bf16 v[128:131], v[136:139], v[152:155], v[128:131]
	s_waitcnt lgkmcnt(0)
	v_mfma_f32_16x16x32_bf16 v[120:123], v[132:135], v[156:159], v[120:123]
	v_mfma_f32_16x16x32_bf16 v[120:123], v[136:139], v[160:163], v[120:123]
	v_mfma_f32_16x16x32_bf16 v[112:115], v[132:135], v[182:185], v[112:115]
	v_mfma_f32_16x16x32_bf16 v[112:115], v[136:139], v[190:193], v[112:115]
	v_mfma_f32_16x16x32_bf16 v[104:107], v[132:135], v[194:197], v[104:107]
	v_mfma_f32_16x16x32_bf16 v[104:107], v[136:139], v[212:215], v[104:107]
	v_mfma_f32_16x16x32_bf16 v[124:127], v[140:143], v[148:151], v[124:127]
	v_mfma_f32_16x16x32_bf16 v[124:127], v[144:147], v[152:155], v[124:127]
	v_mfma_f32_16x16x32_bf16 v[116:119], v[140:143], v[156:159], v[116:119]
	v_mfma_f32_16x16x32_bf16 v[116:119], v[144:147], v[160:163], v[116:119]
	v_mfma_f32_16x16x32_bf16 v[108:111], v[140:143], v[182:185], v[108:111]
	v_mfma_f32_16x16x32_bf16 v[108:111], v[144:147], v[190:193], v[108:111]
	v_mfma_f32_16x16x32_bf16 v[100:103], v[140:143], v[194:197], v[100:103]
	v_mfma_f32_16x16x32_bf16 v[100:103], v[144:147], v[212:215], v[100:103]
	s_barrier
	s_setprio 0
	s_add_i32 s6, 0, 0x1c000
	s_add_i32 s7, s43, s27
	v_add_u32_e32 v2, s6, v167
	v_lshl_add_u64 v[0:1], v[0:1], 0, s[52:53]
	s_mov_b32 m0, s7
	ds_read_b128 v[216:219], v2
	ds_read_b128 v[220:223], v2 offset:1024
	ds_read_b128 v[224:227], v2 offset:2048
	ds_read_b128 v[228:231], v2 offset:3072
	global_load_lds_dwordx4 v[0:1], off
	v_lshl_add_u64 v[0:1], v[232:233], 0, s[52:53]
	s_add_i32 m0, s7, 0x2000
	s_nop 0
	global_load_lds_dwordx4 v[0:1], off
	s_mov_b32 m0, s38
	v_lshl_add_u64 v[0:1], v[234:235], 0, s[52:53]
	s_waitcnt vmcnt(10)
	s_waitcnt lgkmcnt(0)
	s_setprio 1
	s_barrier
	v_mfma_f32_16x16x32_bf16 v[96:99], v[216:219], v[148:151], v[96:99]
	v_mfma_f32_16x16x32_bf16 v[96:99], v[220:223], v[152:155], v[96:99]
	s_waitcnt lgkmcnt(0)
	v_mfma_f32_16x16x32_bf16 v[88:91], v[216:219], v[156:159], v[88:91]
	v_mfma_f32_16x16x32_bf16 v[88:91], v[220:223], v[160:163], v[88:91]
	v_mfma_f32_16x16x32_bf16 v[80:83], v[216:219], v[182:185], v[80:83]
	v_mfma_f32_16x16x32_bf16 v[80:83], v[220:223], v[190:193], v[80:83]
	v_mfma_f32_16x16x32_bf16 v[72:75], v[216:219], v[194:197], v[72:75]
	v_mfma_f32_16x16x32_bf16 v[72:75], v[220:223], v[212:215], v[72:75]
	v_mfma_f32_16x16x32_bf16 v[92:95], v[224:227], v[148:151], v[92:95]
	v_mfma_f32_16x16x32_bf16 v[92:95], v[228:231], v[152:155], v[92:95]
	v_mfma_f32_16x16x32_bf16 v[84:87], v[224:227], v[156:159], v[84:87]
	v_mfma_f32_16x16x32_bf16 v[84:87], v[228:231], v[160:163], v[84:87]
	v_mfma_f32_16x16x32_bf16 v[76:79], v[224:227], v[182:185], v[76:79]
	v_mfma_f32_16x16x32_bf16 v[76:79], v[228:231], v[190:193], v[76:79]
	v_mfma_f32_16x16x32_bf16 v[68:71], v[224:227], v[194:197], v[68:71]
	v_mfma_f32_16x16x32_bf16 v[68:71], v[228:231], v[212:215], v[68:71]
	s_barrier
; #define PG8_WAIT_V(n) asm volatile("s_waitcnt vmcnt(" #n ")" ::: "memory")
; #define PG8_WAIT_L(n) asm volatile("s_waitcnt lgkmcnt(" #n ")" ::: "memory")
; #define PG8_BAR __builtin_amdgcn_s_barrier()
; #define PG8_SCHED __builtin_amdgcn_sched_barrier(0)
; template <class Epi, class AddrA, class AddrB>
; __device__ __forceinline__ void gemm_phase(const Sched S, const int lda, const int ldb, const int K, const AddrA addrA,
;                                            const AddrB addrB, const Epi E) {
;     ...
;       PG8_LDB(B1, 1, 1); PG8_STAGE(PG8_SB(1, 0), b3, voffB);
;       PG8_BAR; PG8_WAIT_L(0); PG8_MMA(0, 1, At, B1); PG8_BAR;
;       PG8_LDA(At, 1, 1); PG8_STAGE(PG8_SA(1, 0), a3, voffA);
;       PG8_BAR; PG8_WAIT_L(0); PG8_MMA(1, 0, At, B0); PG8_BAR; PG8_SCHED;
;       PG8_STAGE(PG8_SB(1, 1), b3 + hstepB, voffB);
;       PG8_WAIT_V(6); PG8_BAR; PG8_MMA(1, 1, At, B1); PG8_BAR;
;   __device__ __forceinline__ void operator()(EPI_ARGS) const {
;     const int col0 = u.pn * 256 + wc * 32 + 8 * fq;
;     const int br = u.br, brn = br < 2 ? br + 1 : 2;
;     const unsigned loff0 = (unsigned)((wr * 64 + fr) * PLD + wc * 32 + 8 * fq);
;     const bf16_t* pc = proj + ((size_t)((GT + br * DM) / 256 + u.pn) * MTOK + (size_t)u.pm * 256) * PLD;
;     const bf16_t* pn_ = proj + ((size_t)((GT + brn * DM) / 256 + u.pn) * MTOK + (size_t)u.pm * 256) * PLD;
;     bf16_t* mrow = merged + ((size_t)u.pm * 256 + wr * 64 + fr) * DM + col0;
; #pragma unroll
;     for (int bj = 0; bj < 2; ++bj) {
;       const int c = col0 + bj * HALF;
;       float gc[8], gn[8];
;       {
;         const f32x4 a0 = *(const f32x4*)(bg + br * DM + c), a1 = *(const f32x4*)(bg + br * DM + c + 4);
;         const f32x4 b0 = *(const f32x4*)(bg + brn * DM + c), b1 = *(const f32x4*)(bg + brn * DM + c + 4);
; #pragma unroll
;         for (int k = 0; k < 4; ++k) { gc[k] = a0[k]; gc[4 + k] = a1[k]; gn[k] = b0[k]; gn[4 + k] = b1[k]; }
;       }
; #pragma unroll
;       for (int ai = 0; ai < 2; ++ai) {
;         unsigned loff = loff0;
;         asm volatile("" : "+v"(loff));
;         u32x4 zc[4], zn[4];
; #pragma unroll
;         for (int m = 0; m < 4; ++m) {
;           const unsigned o = loff + (unsigned)((ai * HALF + m * 16) * PLD + bj * HALF);
;           zc[m] = *(const u32x4*)(pc + o);
;           zn[m] = *(const u32x4*)(pn_ + o);
;         }
	s_setprio 0
	ds_read_b128 v[148:151], v188 offset:49152
	ds_read_b128 v[152:155], v188 offset:50176
	ds_read_b128 v[156:159], v188 offset:51200
	ds_read_b128 v[160:163], v188 offset:52224
	ds_read_b128 v[182:185], v188 offset:53248
	ds_read_b128 v[190:193], v188 offset:54272
	ds_read_b128 v[194:197], v188 offset:55296
	ds_read_b128 v[212:215], v188 offset:56320
	global_load_lds_dwordx4 v[0:1], off
	v_lshl_add_u64 v[0:1], v[236:237], 0, s[52:53]
	s_mov_b32 m0, s39
	s_nop 0
	global_load_lds_dwordx4 v[0:1], off
	s_add_u32 s4, s4, 0x80080
	s_addc_u32 s5, s5, 0
	s_add_i32 s6, s6, s27
	v_lshl_add_u64 v[0:1], s[4:5], 0, v[172:173]
	s_mov_b32 m0, s6
	s_nop 0
	global_load_lds_dwordx4 v[0:1], off
	v_lshl_add_u64 v[0:1], s[4:5], 0, v[168:169]
	s_add_i32 m0, s6, 0x2000
	s_nop 0
	global_load_lds_dwordx4 v[0:1], off
	s_add_i32 s42, s42, 2
	s_add_u32 s33, s33, 0x100
	s_addc_u32 s41, s41, 0
	s_add_u32 s2, s2, 0x100
	s_addc_u32 s3, s3, 0
	s_waitcnt vmcnt(8)
	s_waitcnt lgkmcnt(0)
	s_setprio 1
	s_barrier
	v_mfma_f32_16x16x32_bf16 v[64:67], v[132:135], v[148:151], v[64:67]
	v_mfma_f32_16x16x32_bf16 v[64:67], v[136:139], v[152:155], v[64:67]
	s_waitcnt lgkmcnt(0)
	v_mfma_f32_16x16x32_bf16 v[56:59], v[132:135], v[156:159], v[56:59]
	v_mfma_f32_16x16x32_bf16 v[56:59], v[136:139], v[160:163], v[56:59]
	v_mfma_f32_16x16x32_bf16 v[48:51], v[132:135], v[182:185], v[48:51]
	v_mfma_f32_16x16x32_bf16 v[48:51], v[136:139], v[190:193], v[48:51]
	v_mfma_f32_16x16x32_bf16 v[40:43], v[132:135], v[194:197], v[40:43]
	v_mfma_f32_16x16x32_bf16 v[40:43], v[136:139], v[212:215], v[40:43]
	v_mfma_f32_16x16x32_bf16 v[60:63], v[140:143], v[148:151], v[60:63]
	v_mfma_f32_16x16x32_bf16 v[60:63], v[144:147], v[152:155], v[60:63]
	v_mfma_f32_16x16x32_bf16 v[52:55], v[140:143], v[156:159], v[52:55]
	v_mfma_f32_16x16x32_bf16 v[52:55], v[144:147], v[160:163], v[52:55]
	v_mfma_f32_16x16x32_bf16 v[44:47], v[140:143], v[182:185], v[44:47]
	v_mfma_f32_16x16x32_bf16 v[44:47], v[144:147], v[190:193], v[44:47]
	v_mfma_f32_16x16x32_bf16 v[36:39], v[140:143], v[194:197], v[36:39]
	v_mfma_f32_16x16x32_bf16 v[36:39], v[144:147], v[212:215], v[36:39]
	v_mfma_f32_16x16x32_bf16 v[32:35], v[216:219], v[148:151], v[32:35]
	v_mfma_f32_16x16x32_bf16 v[32:35], v[220:223], v[152:155], v[32:35]
	v_mfma_f32_16x16x32_bf16 v[24:27], v[216:219], v[156:159], v[24:27]
	v_mfma_f32_16x16x32_bf16 v[24:27], v[220:223], v[160:163], v[24:27]
	v_mfma_f32_16x16x32_bf16 v[16:19], v[216:219], v[182:185], v[16:19]
	v_mfma_f32_16x16x32_bf16 v[16:19], v[220:223], v[190:193], v[16:19]
	v_mfma_f32_16x16x32_bf16 v[8:11], v[216:219], v[194:197], v[8:11]
	v_mfma_f32_16x16x32_bf16 v[8:11], v[220:223], v[212:215], v[8:11]
	v_mfma_f32_16x16x32_bf16 v[28:31], v[224:227], v[148:151], v[28:31]
	v_mfma_f32_16x16x32_bf16 v[28:31], v[228:231], v[152:155], v[28:31]
	v_mfma_f32_16x16x32_bf16 v[20:23], v[224:227], v[156:159], v[20:23]
	v_mfma_f32_16x16x32_bf16 v[20:23], v[228:231], v[160:163], v[20:23]
	v_mfma_f32_16x16x32_bf16 v[12:15], v[224:227], v[182:185], v[12:15]
	v_mfma_f32_16x16x32_bf16 v[12:15], v[228:231], v[190:193], v[12:15]
	v_mfma_f32_16x16x32_bf16 v[4:7], v[224:227], v[194:197], v[4:7]
	v_mfma_f32_16x16x32_bf16 v[4:7], v[228:231], v[212:215], v[4:7]
	s_barrier
	s_setprio 0
	s_cmp_gt_u32 s42, 29
	s_cbranch_scc0 .LBB0_543
	s_cmp_gt_i32 s10, 1
	s_cselect_b64 s[6:7], -1, 0
	s_lshl_b32 s42, s10, 11
	s_add_i32 s2, s42, 0x4c00
	s_ashr_i32 s2, s2, 8
	s_add_i32 s2, s2, s11
	s_ashr_i32 s3, s2, 31
	s_min_i32 s1, s10, 1
	s_ashr_i32 s9, s8, 31
	s_lshl_b64 s[2:3], s[2:3], 23
	s_add_u32 s2, s34, s2
	s_addc_u32 s3, s35, s3
	s_lshl_b64 s[4:5], s[8:9], 17
	s_add_u32 s2, s2, s4
	s_addc_u32 s3, s3, s5
	s_lshl_b32 s1, s1, 11
	s_add_i32 s44, s1, 0x800
	s_addk_i32 s1, 0x5400
	s_ashr_i32 s1, s1, 8
	s_add_i32 s46, s1, s11
	s_ashr_i32 s47, s46, 31
	s_lshl_b64 s[46:47], s[46:47], 23
	s_add_u32 s1, s34, s46
	v_lshl_or_b32 v132, s11, 8, v187
	s_addc_u32 s11, s35, s47
	s_add_u32 s4, s1, s4
	s_addc_u32 s5, s11, s5
	s_ashr_i32 s43, s42, 31
	s_lshl_b64 s[8:9], s[8:9], 20
	s_ashr_i32 s45, s44, 31
	s_lshl_b64 s[42:43], s[42:43], 2
	s_add_u32 s42, s36, s42
	s_addc_u32 s43, s37, s43
	s_lshl_b64 s[44:45], s[44:45], 2
	s_add_u32 s44, s36, s44
	v_lshl_add_u64 v[0:1], v[176:177], 0, s[8:9]
	v_ashrrev_i32_e32 v133, 31, v132
	s_addc_u32 s45, s37, s45
	v_lshl_add_u64 v[0:1], v[132:133], 1, v[0:1]
	v_lshlrev_b64 v[132:133], 2, v[132:133]
	v_lshl_add_u64 v[182:183], s[42:43], 0, v[132:133]
	v_lshl_add_u64 v[184:185], s[44:45], 0, v[132:133]
	v_mov_b32_e32 v2, v186
	global_load_dwordx4 v[144:147], v[182:183], off
	global_load_dwordx4 v[136:139], v[182:183], off offset:16
	global_load_dwordx4 v[140:143], v[184:185], off
	global_load_dwordx4 v[132:135], v[184:185], off offset:16
	s_cmp_lt_i32 s10, 2
	v_lshlrev_b64 v[148:149], 1, v[2:3]
	v_lshl_add_u64 v[150:151], s[2:3], 0, v[148:149]
	v_lshl_add_u64 v[148:149], s[4:5], 0, v[148:149]
	flat_load_dwordx4 v[190:193], v[150:151]
	flat_load_dwordx4 v[160:163], v[148:149]
	v_add_u32_e32 v148, 0x1000, v2
	v_mov_b32_e32 v149, v3
	v_lshlrev_b64 v[148:149], 1, v[148:149]
	v_lshl_add_u64 v[150:151], s[2:3], 0, v[148:149]
	v_lshl_add_u64 v[148:149], s[4:5], 0, v[148:149]
	flat_load_dwordx4 v[194:197], v[150:151]
	flat_load_dwordx4 v[156:159], v[148:149]
	v_add_u32_e32 v148, 0x2000, v2
	v_mov_b32_e32 v149, v3
	v_lshlrev_b64 v[148:149], 1, v[148:149]
	v_lshl_add_u64 v[150:151], s[2:3], 0, v[148:149]
	v_lshl_add_u64 v[148:149], s[4:5], 0, v[148:149]
	v_add_u32_e32 v2, 0x3000, v2
	flat_load_dwordx4 v[234:237], v[150:151]
	flat_load_dwordx4 v[152:155], v[148:149]
	v_lshlrev_b64 v[148:149], 1, v[2:3]
	v_lshl_add_u64 v[150:151], s[2:3], 0, v[148:149]
	v_lshl_add_u64 v[148:149], s[4:5], 0, v[148:149]
	flat_load_dwordx4 v[238:241], v[150:151]
	s_nop 0
	flat_load_dwordx4 v[148:151], v[148:149]
	s_waitcnt vmcnt(0) lgkmcnt(0)
; __device__ __forceinline__ float sigmoidf_(float x) { return __builtin_amdgcn_rcpf(1.0f + __expf(-x)); }
;   __device__ __forceinline__ void operator()(EPI_ARGS) const {
;     ...
;         __builtin_amdgcn_sched_barrier(0);
;         if (br < 2) {
; #pragma unroll
;           for (int m = 0; m < 4; ++m) {
;             float xc[8], xn[8];
;             unpack8(zc[m], xc);
;             unpack8(zn[m], xn);
; #pragma unroll
;             for (int k = 0; k < 8; ++k) {
;               const float ec = __expf(-fmaxf(xc[k] + gc[k], -40.f)), en = __expf(-fmaxf(xn[k] + gn[k], -40.f));
;               const float f = (1.0f + en) * __builtin_amdgcn_rcpf(1.0f + ec);
;               acc[ai][bj][m][k >> 2][k & 3] *= f;
;             }
;           }
;         } else {
; #pragma unroll
;           for (int m = 0; m < 4; ++m) {
;             float xc[8], y[8];
;             unpack8(zc[m], xc);
; #pragma unroll
;             for (int k = 0; k < 8; ++k) y[k] = acc[ai][bj][m][k >> 2][k & 3] * sigmoidf_(fmaxf(xc[k] + gc[k], -40.f));
;             u32x4 o;
;             o.x = pack2(y[0], y[1]); o.y = pack2(y[2], y[3]); o.z = pack2(y[4], y[5]); o.w = pack2(y[6], y[7]);
;             *(u32x4*)(mrow + (size_t)(ai * HALF + m * 16) * DM + bj * HALF) = o;
	v_lshlrev_b32_e32 v2, 16, v190
	v_and_b32_e32 v189, 0xffff0000, v190
	v_lshlrev_b32_e32 v190, 16, v191
	v_and_b32_e32 v191, 0xffff0000, v191
	v_lshlrev_b32_e32 v212, 16, v192
	v_and_b32_e32 v192, 0xffff0000, v192
	v_lshlrev_b32_e32 v213, 16, v193
	v_and_b32_e32 v193, 0xffff0000, v193
	v_add_f32_e32 v2, v144, v2
	v_add_f32_e32 v189, v145, v189
	v_add_f32_e32 v190, v146, v190
	v_add_f32_e32 v191, v147, v191
	v_add_f32_e32 v212, v136, v212
	v_add_f32_e32 v192, v137, v192
	v_add_f32_e32 v213, v138, v213
	v_add_f32_e32 v193, v139, v193
	s_mov_b64 s[8:9], -1
	v_max_f32_e32 v233, 0xc2200000, v2
	v_max_f32_e32 v232, 0xc2200000, v189
	v_max_f32_e32 v231, 0xc2200000, v190
	v_max_f32_e32 v230, 0xc2200000, v191
	v_max_f32_e32 v229, 0xc2200000, v212
	v_max_f32_e32 v228, 0xc2200000, v192
	v_max_f32_e32 v227, 0xc2200000, v213
	v_max_f32_e32 v226, 0xc2200000, v193
	v_lshlrev_b32_e32 v225, 16, v194
	v_and_b32_e32 v224, 0xffff0000, v194
	v_lshlrev_b32_e32 v223, 16, v195
	v_and_b32_e32 v222, 0xffff0000, v195
	v_lshlrev_b32_e32 v221, 16, v196
	v_and_b32_e32 v220, 0xffff0000, v196
	v_lshlrev_b32_e32 v219, 16, v197
	v_and_b32_e32 v218, 0xffff0000, v197
	v_lshlrev_b32_e32 v217, 16, v234
	v_and_b32_e32 v216, 0xffff0000, v234
	v_lshlrev_b32_e32 v215, 16, v235
	v_and_b32_e32 v214, 0xffff0000, v235
	v_lshlrev_b32_e32 v213, 16, v236
	v_and_b32_e32 v212, 0xffff0000, v236
	v_lshlrev_b32_e32 v197, 16, v237
	v_and_b32_e32 v196, 0xffff0000, v237
	v_lshlrev_b32_e32 v195, 16, v238
	v_and_b32_e32 v194, 0xffff0000, v238
	v_lshlrev_b32_e32 v193, 16, v239
	v_and_b32_e32 v192, 0xffff0000, v239
	v_lshlrev_b32_e32 v191, 16, v240
	v_and_b32_e32 v190, 0xffff0000, v240
	v_lshlrev_b32_e32 v189, 16, v241
	v_and_b32_e32 v2, 0xffff0000, v241
	s_cbranch_scc1 .LBB0_546
	v_mul_f32_e32 v234, 0xbfb8aa3b, v233
	v_mul_f32_e32 v235, 0xbfb8aa3b, v232
	v_mul_f32_e32 v236, 0xbfb8aa3b, v231
	v_exp_f32_e32 v234, v234
	v_exp_f32_e32 v235, v235
	v_exp_f32_e32 v236, v236
	v_mul_f32_e32 v237, 0xbfb8aa3b, v230
	v_exp_f32_e32 v237, v237
	v_mul_f32_e32 v238, 0xbfb8aa3b, v229
	v_mul_f32_e32 v239, 0xbfb8aa3b, v228
	v_add_f32_e32 v234, 1.0, v234
	v_add_f32_e32 v235, 1.0, v235
	v_add_f32_e32 v236, 1.0, v236
	v_exp_f32_e32 v238, v238
	v_exp_f32_e32 v239, v239
	v_mul_f32_e32 v240, 0xbfb8aa3b, v227
	v_mul_f32_e32 v241, 0xbfb8aa3b, v226
	v_rcp_f32_e32 v234, v234
	v_rcp_f32_e32 v235, v235
	v_rcp_f32_e32 v236, v236
	v_add_f32_e32 v237, 1.0, v237
	v_exp_f32_e32 v240, v240
	v_exp_f32_e32 v241, v241
	v_rcp_f32_e32 v237, v237
	v_add_f32_e32 v238, 1.0, v238
	v_add_f32_e32 v239, 1.0, v239
	v_mul_f32_e32 v234, v128, v234
	v_mul_f32_e32 v235, v129, v235
	v_mul_f32_e32 v236, v130, v236
	v_rcp_f32_e32 v238, v238
	v_rcp_f32_e32 v239, v239
	v_add_f32_e32 v240, 1.0, v240
	v_add_f32_e32 v241, 1.0, v241
	v_mul_f32_e32 v237, v131, v237
	v_rcp_f32_e32 v240, v240
	v_rcp_f32_e32 v241, v241
	v_cvt_pk_bf16_f32 v234, v234, v235
	v_cvt_pk_bf16_f32 v235, v236, v237
	v_add_f32_e32 v236, v144, v225
	v_max_f32_e32 v236, 0xc2200000, v236
	v_mul_f32_e32 v236, 0xbfb8aa3b, v236
	v_mul_f32_e32 v238, v124, v238
	v_mul_f32_e32 v239, v125, v239
	v_exp_f32_e32 v242, v236
	v_cvt_pk_bf16_f32 v236, v238, v239
	v_mul_f32_e32 v240, v126, v240
	v_mul_f32_e32 v241, v127, v241
	v_cvt_pk_bf16_f32 v237, v240, v241
	flat_store_dwordx4 v[0:1], v[234:237]
	v_add_f32_e32 v238, v136, v221
	v_max_f32_e32 v238, 0xc2200000, v238
	v_add_f32_e32 v235, v145, v224
	v_add_f32_e32 v236, v146, v223
	v_max_f32_e32 v235, 0xc2200000, v235
	v_max_f32_e32 v236, 0xc2200000, v236
	v_add_f32_e32 v237, v147, v222
	v_add_f32_e32 v239, v137, v220
	v_mul_f32_e32 v235, 0xbfb8aa3b, v235
	v_mul_f32_e32 v236, 0xbfb8aa3b, v236
	v_max_f32_e32 v237, 0xc2200000, v237
	v_mul_f32_e32 v238, 0xbfb8aa3b, v238
	v_max_f32_e32 v239, 0xc2200000, v239
	v_exp_f32_e32 v235, v235
	v_exp_f32_e32 v236, v236
	v_mul_f32_e32 v237, 0xbfb8aa3b, v237
	v_exp_f32_e32 v238, v238
	v_mul_f32_e32 v239, 0xbfb8aa3b, v239
	v_add_f32_e32 v240, v138, v219
	v_exp_f32_e32 v237, v237
	v_exp_f32_e32 v239, v239
	v_max_f32_e32 v240, 0xc2200000, v240
	v_add_f32_e32 v241, v139, v218
	v_mul_f32_e32 v240, 0xbfb8aa3b, v240
	v_max_f32_e32 v241, 0xc2200000, v241
	v_exp_f32_e32 v240, v240
	v_mul_f32_e32 v241, 0xbfb8aa3b, v241
	v_add_f32_e32 v234, 1.0, v242
	v_add_f32_e32 v235, 1.0, v235
	v_add_f32_e32 v236, 1.0, v236
	v_add_f32_e32 v238, 1.0, v238
	v_exp_f32_e32 v241, v241
	v_rcp_f32_e32 v234, v234
	v_rcp_f32_e32 v235, v235
	v_rcp_f32_e32 v236, v236
	v_add_f32_e32 v237, 1.0, v237
	v_rcp_f32_e32 v238, v238
	v_add_f32_e32 v239, 1.0, v239
	v_rcp_f32_e32 v237, v237
	v_rcp_f32_e32 v239, v239
	v_add_f32_e32 v240, 1.0, v240
	v_rcp_f32_e32 v240, v240
	v_add_f32_e32 v241, 1.0, v241
	v_mul_f32_e32 v234, v120, v234
; __device__ __forceinline__ float sigmoidf_(float x) { return __builtin_amdgcn_rcpf(1.0f + __expf(-x)); }
;   __device__ __forceinline__ void operator()(EPI_ARGS) const {
;     ...
;         } else {
; #pragma unroll
;           for (int m = 0; m < 4; ++m) {
;             float xc[8], y[8];
;             unpack8(zc[m], xc);
; #pragma unroll
;             for (int k = 0; k < 8; ++k) y[k] = acc[ai][bj][m][k >> 2][k & 3] * sigmoidf_(fmaxf(xc[k] + gc[k], -40.f));
;             u32x4 o;
;             o.x = pack2(y[0], y[1]); o.y = pack2(y[2], y[3]); o.z = pack2(y[4], y[5]); o.w = pack2(y[6], y[7]);
;             *(u32x4*)(mrow + (size_t)(ai * HALF + m * 16) * DM + bj * HALF) = o;
	v_mul_f32_e32 v235, v121, v235
	v_mul_f32_e32 v236, v122, v236
	v_rcp_f32_e32 v241, v241
	v_mul_f32_e32 v238, v116, v238
	v_mul_f32_e32 v237, v123, v237
	v_mul_f32_e32 v239, v117, v239
	v_cvt_pk_bf16_f32 v234, v234, v235
	v_cvt_pk_bf16_f32 v235, v236, v237
	v_cvt_pk_bf16_f32 v236, v238, v239
	v_add_f32_e32 v238, v144, v217
	v_max_f32_e32 v238, 0xc2200000, v238
	v_mul_f32_e32 v240, v118, v240
	v_mul_f32_e32 v238, 0xbfb8aa3b, v238
	v_mul_f32_e32 v241, v119, v241
	v_cvt_pk_bf16_f32 v237, v240, v241
	v_exp_f32_e32 v240, v238
	v_add_co_u32_e32 v238, vcc, s67, v0
	v_add_f32_e32 v241, v139, v196
	s_nop 0
	v_addc_co_u32_e32 v239, vcc, 0, v1, vcc
	flat_store_dwordx4 v[238:239], v[234:237]
	v_add_f32_e32 v238, v136, v213
	v_max_f32_e32 v238, 0xc2200000, v238
	v_add_f32_e32 v235, v145, v216
	v_add_f32_e32 v236, v146, v215
	v_max_f32_e32 v235, 0xc2200000, v235
	v_max_f32_e32 v236, 0xc2200000, v236
	v_add_f32_e32 v237, v147, v214
	v_add_f32_e32 v239, v137, v212
	v_mul_f32_e32 v235, 0xbfb8aa3b, v235
	v_mul_f32_e32 v236, 0xbfb8aa3b, v236
	v_max_f32_e32 v237, 0xc2200000, v237
	v_mul_f32_e32 v238, 0xbfb8aa3b, v238
	v_max_f32_e32 v239, 0xc2200000, v239
	v_add_f32_e32 v234, 1.0, v240
	v_exp_f32_e32 v235, v235
	v_exp_f32_e32 v236, v236
	v_mul_f32_e32 v237, 0xbfb8aa3b, v237
	v_exp_f32_e32 v238, v238
	v_mul_f32_e32 v239, 0xbfb8aa3b, v239
	v_add_f32_e32 v240, v138, v197
	v_exp_f32_e32 v237, v237
	v_exp_f32_e32 v239, v239
	v_max_f32_e32 v240, 0xc2200000, v240
	v_mul_f32_e32 v240, 0xbfb8aa3b, v240
	v_max_f32_e32 v241, 0xc2200000, v241
	v_exp_f32_e32 v240, v240
	v_mul_f32_e32 v241, 0xbfb8aa3b, v241
	v_add_f32_e32 v235, 1.0, v235
	v_add_f32_e32 v236, 1.0, v236
	v_add_f32_e32 v238, 1.0, v238
	v_exp_f32_e32 v241, v241
	v_rcp_f32_e32 v234, v234
	v_rcp_f32_e32 v235, v235
	v_rcp_f32_e32 v236, v236
	v_add_f32_e32 v237, 1.0, v237
	v_rcp_f32_e32 v238, v238
	v_add_f32_e32 v239, 1.0, v239
	v_rcp_f32_e32 v237, v237
	v_rcp_f32_e32 v239, v239
	v_add_f32_e32 v240, 1.0, v240
	v_rcp_f32_e32 v240, v240
	v_add_f32_e32 v241, 1.0, v241
	v_mul_f32_e32 v234, v112, v234
	v_mul_f32_e32 v235, v113, v235
	v_mul_f32_e32 v236, v114, v236
	v_rcp_f32_e32 v241, v241
	v_mul_f32_e32 v238, v108, v238
	v_mul_f32_e32 v237, v115, v237
	v_mul_f32_e32 v239, v109, v239
	v_cvt_pk_bf16_f32 v234, v234, v235
	v_cvt_pk_bf16_f32 v235, v236, v237
	v_cvt_pk_bf16_f32 v236, v238, v239
	v_add_f32_e32 v238, v144, v195
	v_max_f32_e32 v238, 0xc2200000, v238
	v_mul_f32_e32 v240, v110, v240
	v_mul_f32_e32 v238, 0xbfb8aa3b, v238
	s_mov_b32 s1, 0x20000
	v_mul_f32_e32 v241, v111, v241
	v_cvt_pk_bf16_f32 v237, v240, v241
	v_exp_f32_e32 v240, v238
	v_add_co_u32_e32 v238, vcc, s1, v0
	v_add_f32_e32 v241, v139, v2
	s_nop 0
	v_addc_co_u32_e32 v239, vcc, 0, v1, vcc
	flat_store_dwordx4 v[238:239], v[234:237]
	v_add_f32_e32 v238, v136, v191
	v_max_f32_e32 v238, 0xc2200000, v238
	v_add_f32_e32 v235, v145, v194
	v_add_f32_e32 v236, v146, v193
	v_max_f32_e32 v235, 0xc2200000, v235
	v_max_f32_e32 v236, 0xc2200000, v236
	v_add_f32_e32 v237, v147, v192
	v_add_f32_e32 v239, v137, v190
	v_mul_f32_e32 v235, 0xbfb8aa3b, v235
	v_mul_f32_e32 v236, 0xbfb8aa3b, v236
	v_max_f32_e32 v237, 0xc2200000, v237
	v_mul_f32_e32 v238, 0xbfb8aa3b, v238
	v_max_f32_e32 v239, 0xc2200000, v239
	v_add_f32_e32 v234, 1.0, v240
	v_exp_f32_e32 v235, v235
	v_exp_f32_e32 v236, v236
	v_mul_f32_e32 v237, 0xbfb8aa3b, v237
	v_exp_f32_e32 v238, v238
	v_mul_f32_e32 v239, 0xbfb8aa3b, v239
	v_add_f32_e32 v240, v138, v189
	v_exp_f32_e32 v237, v237
	v_exp_f32_e32 v239, v239
	v_max_f32_e32 v240, 0xc2200000, v240
	v_max_f32_e32 v241, 0xc2200000, v241
	v_mul_f32_e32 v240, 0xbfb8aa3b, v240
	v_mul_f32_e32 v241, 0xbfb8aa3b, v241
	v_exp_f32_e32 v240, v240
	v_exp_f32_e32 v241, v241
	v_add_f32_e32 v235, 1.0, v235
	v_add_f32_e32 v236, 1.0, v236
	v_add_f32_e32 v238, 1.0, v238
	v_rcp_f32_e32 v234, v234
	v_rcp_f32_e32 v235, v235
	v_rcp_f32_e32 v236, v236
	v_add_f32_e32 v237, 1.0, v237
	v_rcp_f32_e32 v238, v238
	v_add_f32_e32 v239, 1.0, v239
	v_rcp_f32_e32 v237, v237
	v_rcp_f32_e32 v239, v239
	v_add_f32_e32 v240, 1.0, v240
	v_add_f32_e32 v241, 1.0, v241
	v_rcp_f32_e32 v240, v240
	v_rcp_f32_e32 v241, v241
	v_mul_f32_e32 v234, v104, v234
	v_mul_f32_e32 v235, v105, v235
	v_mul_f32_e32 v236, v106, v236
	v_mul_f32_e32 v238, v100, v238
	v_mul_f32_e32 v237, v107, v237
	v_mul_f32_e32 v239, v101, v239
	v_cvt_pk_bf16_f32 v234, v234, v235
	v_cvt_pk_bf16_f32 v235, v236, v237
	v_cvt_pk_bf16_f32 v236, v238, v239
	v_add_co_u32_e32 v238, vcc, 0x30000, v0
	s_mov_b64 s[8:9], 0
	s_nop 0
	v_addc_co_u32_e32 v239, vcc, 0, v1, vcc
	v_mul_f32_e32 v240, v102, v240
	v_mul_f32_e32 v241, v103, v241
	v_cvt_pk_bf16_f32 v237, v240, v241
	flat_store_dwordx4 v[238:239], v[234:237]

; #define PG8_WAIT_V(n) asm volatile("s_waitcnt vmcnt(" #n ")" ::: "memory")
; #define PG8_WAIT_L(n) asm volatile("s_waitcnt lgkmcnt(" #n ")" ::: "memory")
; #define PG8_BAR __builtin_amdgcn_s_barrier()
; #define PG8_SCHED __builtin_amdgcn_sched_barrier(0)
; template <class Epi, class AddrA, class AddrB>
; __device__ __forceinline__ void gemm_phase(const Sched S, const int lda, const int ldb, const int K, const AddrA addrA,
;                                            const AddrB addrB, const Epi E) {
;     ...
;     for (int t = 0; t < nt; t += 2) {
;       const bool last = (t == nt - 2);
;       const char* a1 = cA + (size_t)(t + 1) * kstep;
;       const char* a2 = last ? nA : cA + (size_t)(t + 2) * kstep;
;       const char* b2 = last ? nB : cB + (size_t)(t + 2) * kstep;
;       const char* a3 = a2 + kstep;
;       const char* b3 = b2 + kstep;
;       PG8_LDB(B0, 0, 0); PG8_SCHED; PG8_LDA(At, 0, 0); PG8_STAGE(PG8_SA(1, 1), a1 + hstepA, voffA);
;       PG8_WAIT_L(8); PG8_BAR; PG8_WAIT_L(0); PG8_MMA(0, 0, At, B0); PG8_BAR; PG8_SCHED;
;       PG8_LDB(B1, 0, 1); PG8_STAGE(PG8_SB(0, 0), b2, voffB);
;       PG8_BAR; PG8_WAIT_L(0); PG8_MMA(0, 1, At, B1); PG8_BAR;
;       PG8_LDA(At, 0, 1); PG8_STAGE(PG8_SA(0, 0), a2, voffA);
;       PG8_BAR; PG8_WAIT_L(0); PG8_MMA(1, 0, At, B0); PG8_BAR; PG8_SCHED;
;       PG8_STAGE(PG8_SB(0, 1), b2 + hstepB, voffB);
;       PG8_WAIT_V(6); PG8_BAR; PG8_MMA(1, 1, At, B1); PG8_BAR;
.LBB0_618:
	s_ashr_i32 s3, s2, 31
	s_lshl_b64 s[8:9], s[2:3], 20
	s_add_u32 s8, s23, s8
	s_addc_u32 s9, s24, s9
	s_and_b64 s[10:11], s[18:19], exec
	s_cselect_b32 s3, s9, s17
	s_cselect_b32 s13, s8, s16
	s_ashr_i32 s5, s4, 31
	s_lshl_b64 s[10:11], s[4:5], 20
	s_add_u32 s10, s21, s10
	s_addc_u32 s11, s22, s11
	s_and_b64 s[18:19], s[18:19], exec
	s_cselect_b32 s5, s11, s15
	s_cselect_b32 s35, s10, s14
	s_add_u32 s36, s14, 0x100
	s_addc_u32 s37, s15, 0
	s_add_u32 s14, s16, 0x80080
	s_addc_u32 s15, s17, 0
	s_mov_b32 s38, -2
	s_add_i32 s39, 0, 0x10000
	v_add_u32_e32 v142, s39, v144
	ds_read_b128 v[148:151], v142
	ds_read_b128 v[152:155], v142 offset:1024
	ds_read_b128 v[156:159], v142 offset:2048
	ds_read_b128 v[160:163], v142 offset:3072
	v_lshl_add_u64 v[142:143], s[14:15], 0, v[140:141]
	s_add_i32 m0, s26, 0xc000
	ds_read_b128 v[168:171], v146
	ds_read_b128 v[172:175], v146 offset:1024
	ds_read_b128 v[176:179], v146 offset:2048
	ds_read_b128 v[180:183], v146 offset:3072
	ds_read_b128 v[184:187], v146 offset:4096
	ds_read_b128 v[188:191], v146 offset:5120
	ds_read_b128 v[192:195], v146 offset:6144
	ds_read_b128 v[212:215], v146 offset:7168
	global_load_lds_dwordx4 v[142:143], off
	v_lshl_add_u64 v[142:143], s[14:15], 0, v[138:139]
	s_add_i32 m0, s26, 0xe000
	s_nop 0
	global_load_lds_dwordx4 v[142:143], off
	s_waitcnt lgkmcnt(6)
	s_setprio 1
	s_barrier
	v_mfma_f32_16x16x32_bf16 v[128:131], v[148:151], v[168:171], 0
	v_mfma_f32_16x16x32_bf16 v[128:131], v[152:155], v[172:175], v[128:131]
	s_waitcnt lgkmcnt(0)
	v_mfma_f32_16x16x32_bf16 v[120:123], v[148:151], v[176:179], 0
	v_mfma_f32_16x16x32_bf16 v[120:123], v[152:155], v[180:183], v[120:123]
	v_mfma_f32_16x16x32_bf16 v[112:115], v[148:151], v[184:187], 0
	v_mfma_f32_16x16x32_bf16 v[112:115], v[152:155], v[188:191], v[112:115]
	v_mfma_f32_16x16x32_bf16 v[104:107], v[148:151], v[192:195], 0
	v_mfma_f32_16x16x32_bf16 v[104:107], v[152:155], v[212:215], v[104:107]
	v_mfma_f32_16x16x32_bf16 v[124:127], v[156:159], v[168:171], 0
	v_mfma_f32_16x16x32_bf16 v[124:127], v[160:163], v[172:175], v[124:127]
	v_mfma_f32_16x16x32_bf16 v[116:119], v[156:159], v[176:179], 0
	v_mfma_f32_16x16x32_bf16 v[116:119], v[160:163], v[180:183], v[116:119]
	v_mfma_f32_16x16x32_bf16 v[108:111], v[156:159], v[184:187], 0
	v_mfma_f32_16x16x32_bf16 v[108:111], v[160:163], v[188:191], v[108:111]
	v_mfma_f32_16x16x32_bf16 v[100:103], v[156:159], v[192:195], 0
	v_mfma_f32_16x16x32_bf16 v[100:103], v[160:163], v[212:215], v[100:103]
	s_barrier
	s_setprio 0
	s_add_u32 s16, s14, 0xfff80080
	s_addc_u32 s17, s15, -1
	s_cmp_eq_u32 s38, 28
	s_cselect_b32 s19, s3, s17
	s_cselect_b32 s18, s13, s16
	s_cselect_b32 s17, s5, s37
	s_cselect_b32 s16, s35, s36
	s_add_i32 s42, 0, 0x14000
	v_add_u32_e32 v142, s42, v144
	s_add_i32 s39, s39, s25
	ds_read_b128 v[216:219], v142
	ds_read_b128 v[220:223], v142 offset:1024
	ds_read_b128 v[224:227], v142 offset:2048
	ds_read_b128 v[228:231], v142 offset:3072
	v_lshl_add_u64 v[142:143], s[16:17], 0, v[2:3]
	s_mov_b32 m0, s39
	v_lshl_add_u64 v[196:197], s[16:17], 0, v[0:1]
	global_load_lds_dwordx4 v[142:143], off
	s_add_i32 m0, s39, 0x2000
	s_nop 0
	global_load_lds_dwordx4 v[196:197], off
	s_mov_b32 m0, s26
	v_lshl_add_u64 v[232:233], s[18:19], 0, v[134:135]
	s_waitcnt vmcnt(10)
	s_waitcnt lgkmcnt(0)
	s_setprio 1
	s_barrier
	v_mfma_f32_16x16x32_bf16 v[96:99], v[216:219], v[168:171], 0
	v_mfma_f32_16x16x32_bf16 v[96:99], v[220:223], v[172:175], v[96:99]
	s_waitcnt lgkmcnt(0)
	v_mfma_f32_16x16x32_bf16 v[88:91], v[216:219], v[176:179], 0
	v_mfma_f32_16x16x32_bf16 v[88:91], v[220:223], v[180:183], v[88:91]
	v_mfma_f32_16x16x32_bf16 v[80:83], v[216:219], v[184:187], 0
	v_mfma_f32_16x16x32_bf16 v[80:83], v[220:223], v[188:191], v[80:83]
	v_mfma_f32_16x16x32_bf16 v[72:75], v[216:219], v[192:195], 0
	v_mfma_f32_16x16x32_bf16 v[72:75], v[220:223], v[212:215], v[72:75]
	v_mfma_f32_16x16x32_bf16 v[92:95], v[224:227], v[168:171], 0
	v_mfma_f32_16x16x32_bf16 v[92:95], v[228:231], v[172:175], v[92:95]
	v_mfma_f32_16x16x32_bf16 v[84:87], v[224:227], v[176:179], 0
	v_mfma_f32_16x16x32_bf16 v[84:87], v[228:231], v[180:183], v[84:87]
	v_mfma_f32_16x16x32_bf16 v[76:79], v[224:227], v[184:187], 0
	v_mfma_f32_16x16x32_bf16 v[76:79], v[228:231], v[188:191], v[76:79]
	v_mfma_f32_16x16x32_bf16 v[68:71], v[224:227], v[192:195], 0
	v_mfma_f32_16x16x32_bf16 v[68:71], v[228:231], v[212:215], v[68:71]
	s_barrier
	s_setprio 0
	ds_read_b128 v[168:171], v146 offset:16384
	ds_read_b128 v[172:175], v146 offset:17408
	ds_read_b128 v[176:179], v146 offset:18432
	ds_read_b128 v[180:183], v146 offset:19456
	ds_read_b128 v[184:187], v146 offset:20480
	ds_read_b128 v[188:191], v146 offset:21504
	ds_read_b128 v[192:195], v146 offset:22528
	ds_read_b128 v[212:215], v146 offset:23552
	global_load_lds_dwordx4 v[232:233], off
	v_lshl_add_u64 v[234:235], s[18:19], 0, v[132:133]
	s_mov_b32 m0, s27
	s_nop 0
	global_load_lds_dwordx4 v[234:235], off
	s_add_u32 s40, s16, 0x80000
	s_addc_u32 s41, s17, 0
	s_add_i32 s39, s42, s25
	v_lshl_add_u64 v[246:247], s[40:41], 0, v[2:3]
	s_mov_b32 m0, s39
	s_nop 0
	global_load_lds_dwordx4 v[246:247], off
	v_lshl_add_u64 v[246:247], s[40:41], 0, v[0:1]
	s_add_i32 m0, s39, 0x2000
	s_nop 0
	global_load_lds_dwordx4 v[246:247], off
	s_add_i32 s39, 0, 0x18000
	v_add_u32_e32 v147, s39, v144
	s_waitcnt vmcnt(8)
	s_waitcnt lgkmcnt(0)
	s_setprio 1
	s_barrier
; #define PG8_WAIT_V(n) asm volatile("s_waitcnt vmcnt(" #n ")" ::: "memory")
; #define PG8_WAIT_L(n) asm volatile("s_waitcnt lgkmcnt(" #n ")" ::: "memory")
; #define PG8_BAR __builtin_amdgcn_s_barrier()
; #define PG8_SCHED __builtin_amdgcn_sched_barrier(0)
; template <class Epi, class AddrA, class AddrB>
; __device__ __forceinline__ void gemm_phase(const Sched S, const int lda, const int ldb, const int K, const AddrA addrA,
;                                            const AddrB addrB, const Epi E) {
;     ...
;     for (int t = 0; t < nt; t += 2) {
;       const bool last = (t == nt - 2);
;       const char* a1 = cA + (size_t)(t + 1) * kstep;
;       const char* a2 = last ? nA : cA + (size_t)(t + 2) * kstep;
;       const char* b2 = last ? nB : cB + (size_t)(t + 2) * kstep;
;       const char* a3 = a2 + kstep;
;       const char* b3 = b2 + kstep;
;       PG8_LDB(B0, 0, 0); PG8_SCHED; PG8_LDA(At, 0, 0); PG8_STAGE(PG8_SA(1, 1), a1 + hstepA, voffA);
;       PG8_WAIT_L(8); PG8_BAR; PG8_WAIT_L(0); PG8_MMA(0, 0, At, B0); PG8_BAR; PG8_SCHED;
;       PG8_LDB(B1, 0, 1); PG8_STAGE(PG8_SB(0, 0), b2, voffB);
;       PG8_BAR; PG8_WAIT_L(0); PG8_MMA(0, 1, At, B1); PG8_BAR;
;       PG8_LDA(At, 0, 1); PG8_STAGE(PG8_SA(0, 0), a2, voffA);
;       PG8_BAR; PG8_WAIT_L(0); PG8_MMA(1, 0, At, B0); PG8_BAR; PG8_SCHED;
;       PG8_STAGE(PG8_SB(0, 1), b2 + hstepB, voffB);
;       PG8_WAIT_V(6); PG8_BAR; PG8_MMA(1, 1, At, B1); PG8_BAR;
;       PG8_LDB(B0, 1, 0); PG8_SCHED; PG8_LDA(At, 1, 0); PG8_STAGE(PG8_SA(0, 1), a2 + hstepA, voffA);
;       PG8_WAIT_L(8); PG8_BAR; PG8_WAIT_L(0); PG8_MMA(0, 0, At, B0); PG8_BAR; PG8_SCHED;
;       PG8_LDB(B1, 1, 1); PG8_STAGE(PG8_SB(1, 0), b3, voffB);
;       PG8_BAR; PG8_WAIT_L(0); PG8_MMA(0, 1, At, B1); PG8_BAR;
;       PG8_LDA(At, 1, 1); PG8_STAGE(PG8_SA(1, 0), a3, voffA);
;       PG8_BAR; PG8_WAIT_L(0); PG8_MMA(1, 0, At, B0); PG8_BAR; PG8_SCHED;
;       PG8_STAGE(PG8_SB(1, 1), b3 + hstepB, voffB);
;       PG8_WAIT_V(6); PG8_BAR; PG8_MMA(1, 1, At, B1); PG8_BAR;
	v_mfma_f32_16x16x32_bf16 v[64:67], v[148:151], v[168:171], 0
	v_mfma_f32_16x16x32_bf16 v[64:67], v[152:155], v[172:175], v[64:67]
	s_waitcnt lgkmcnt(0)
	v_mfma_f32_16x16x32_bf16 v[56:59], v[148:151], v[176:179], 0
	v_mfma_f32_16x16x32_bf16 v[56:59], v[152:155], v[180:183], v[56:59]
	v_mfma_f32_16x16x32_bf16 v[48:51], v[148:151], v[184:187], 0
	v_mfma_f32_16x16x32_bf16 v[48:51], v[152:155], v[188:191], v[48:51]
	v_mfma_f32_16x16x32_bf16 v[40:43], v[148:151], v[192:195], 0
	v_mfma_f32_16x16x32_bf16 v[40:43], v[152:155], v[212:215], v[40:43]
	v_mfma_f32_16x16x32_bf16 v[60:63], v[156:159], v[168:171], 0
	v_mfma_f32_16x16x32_bf16 v[60:63], v[160:163], v[172:175], v[60:63]
	v_mfma_f32_16x16x32_bf16 v[52:55], v[156:159], v[176:179], 0
	v_mfma_f32_16x16x32_bf16 v[52:55], v[160:163], v[180:183], v[52:55]
	v_mfma_f32_16x16x32_bf16 v[44:47], v[156:159], v[184:187], 0
	v_mfma_f32_16x16x32_bf16 v[44:47], v[160:163], v[188:191], v[44:47]
	v_mfma_f32_16x16x32_bf16 v[36:39], v[156:159], v[192:195], 0
	v_mfma_f32_16x16x32_bf16 v[36:39], v[160:163], v[212:215], v[36:39]
	v_mfma_f32_16x16x32_bf16 v[32:35], v[216:219], v[168:171], 0
	v_mfma_f32_16x16x32_bf16 v[32:35], v[220:223], v[172:175], v[32:35]
	v_mfma_f32_16x16x32_bf16 v[24:27], v[216:219], v[176:179], 0
	v_mfma_f32_16x16x32_bf16 v[24:27], v[220:223], v[180:183], v[24:27]
	v_mfma_f32_16x16x32_bf16 v[16:19], v[216:219], v[184:187], 0
	v_mfma_f32_16x16x32_bf16 v[16:19], v[220:223], v[188:191], v[16:19]
	v_mfma_f32_16x16x32_bf16 v[8:11], v[216:219], v[192:195], 0
	v_mfma_f32_16x16x32_bf16 v[8:11], v[220:223], v[212:215], v[8:11]
	v_mfma_f32_16x16x32_bf16 v[28:31], v[224:227], v[168:171], 0
	v_mfma_f32_16x16x32_bf16 v[28:31], v[228:231], v[172:175], v[28:31]
	v_mfma_f32_16x16x32_bf16 v[20:23], v[224:227], v[176:179], 0
	v_mfma_f32_16x16x32_bf16 v[20:23], v[228:231], v[180:183], v[20:23]
	v_mfma_f32_16x16x32_bf16 v[12:15], v[224:227], v[184:187], 0
	v_mfma_f32_16x16x32_bf16 v[12:15], v[228:231], v[188:191], v[12:15]
	v_mfma_f32_16x16x32_bf16 v[4:7], v[224:227], v[192:195], 0
	v_mfma_f32_16x16x32_bf16 v[4:7], v[228:231], v[212:215], v[4:7]
	s_barrier
	s_setprio 0
	ds_read_b128 v[148:151], v147
	ds_read_b128 v[152:155], v147 offset:1024
	ds_read_b128 v[156:159], v147 offset:2048
	ds_read_b128 v[160:163], v147 offset:3072
	s_add_u32 s18, s18, 0x80000
	s_addc_u32 s19, s19, 0
	s_mov_b32 m0, s28
	v_lshl_add_u64 v[216:217], s[18:19], 0, v[134:135]
	ds_read_b128 v[168:171], v146 offset:32768
	ds_read_b128 v[172:175], v146 offset:33792
	ds_read_b128 v[176:179], v146 offset:34816
	ds_read_b128 v[180:183], v146 offset:35840
	ds_read_b128 v[184:187], v146 offset:36864
	ds_read_b128 v[188:191], v146 offset:37888
	ds_read_b128 v[192:195], v146 offset:38912
	ds_read_b128 v[212:215], v146 offset:39936
	global_load_lds_dwordx4 v[216:217], off
	v_lshl_add_u64 v[216:217], s[18:19], 0, v[132:133]
	s_mov_b32 m0, s29
	s_nop 0
	global_load_lds_dwordx4 v[216:217], off
	s_waitcnt lgkmcnt(6)
	s_setprio 1
	s_barrier
	v_mfma_f32_16x16x32_bf16 v[128:131], v[148:151], v[168:171], v[128:131]
	v_mfma_f32_16x16x32_bf16 v[128:131], v[152:155], v[172:175], v[128:131]
	s_waitcnt lgkmcnt(0)
	v_mfma_f32_16x16x32_bf16 v[120:123], v[148:151], v[176:179], v[120:123]
	v_mfma_f32_16x16x32_bf16 v[120:123], v[152:155], v[180:183], v[120:123]
	v_mfma_f32_16x16x32_bf16 v[112:115], v[148:151], v[184:187], v[112:115]
	v_mfma_f32_16x16x32_bf16 v[112:115], v[152:155], v[188:191], v[112:115]
	v_mfma_f32_16x16x32_bf16 v[104:107], v[148:151], v[192:195], v[104:107]
	v_mfma_f32_16x16x32_bf16 v[104:107], v[152:155], v[212:215], v[104:107]
	v_mfma_f32_16x16x32_bf16 v[124:127], v[156:159], v[168:171], v[124:127]
	v_mfma_f32_16x16x32_bf16 v[124:127], v[160:163], v[172:175], v[124:127]
	v_mfma_f32_16x16x32_bf16 v[116:119], v[156:159], v[176:179], v[116:119]
	v_mfma_f32_16x16x32_bf16 v[116:119], v[160:163], v[180:183], v[116:119]
	v_mfma_f32_16x16x32_bf16 v[108:111], v[156:159], v[184:187], v[108:111]
	v_mfma_f32_16x16x32_bf16 v[108:111], v[160:163], v[188:191], v[108:111]
	v_mfma_f32_16x16x32_bf16 v[100:103], v[156:159], v[192:195], v[100:103]
	v_mfma_f32_16x16x32_bf16 v[100:103], v[160:163], v[212:215], v[100:103]
	s_barrier
	s_setprio 0
	s_add_i32 s18, 0, 0x1c000
	s_add_i32 s19, s39, s25
	v_add_u32_e32 v147, s18, v144
	v_lshl_add_u64 v[142:143], v[142:143], 0, s[52:53]
	s_mov_b32 m0, s19
	ds_read_b128 v[216:219], v147
	ds_read_b128 v[220:223], v147 offset:1024
	ds_read_b128 v[224:227], v147 offset:2048
	ds_read_b128 v[228:231], v147 offset:3072
	global_load_lds_dwordx4 v[142:143], off
	v_lshl_add_u64 v[142:143], v[196:197], 0, s[52:53]
	s_add_i32 m0, s19, 0x2000
	s_nop 0
	global_load_lds_dwordx4 v[142:143], off
	s_mov_b32 m0, s30
	v_lshl_add_u64 v[142:143], v[232:233], 0, s[52:53]
	s_waitcnt vmcnt(10)
	s_waitcnt lgkmcnt(0)
	s_setprio 1
	s_barrier
	v_mfma_f32_16x16x32_bf16 v[96:99], v[216:219], v[168:171], v[96:99]
	v_mfma_f32_16x16x32_bf16 v[96:99], v[220:223], v[172:175], v[96:99]
	s_waitcnt lgkmcnt(0)
	v_mfma_f32_16x16x32_bf16 v[88:91], v[216:219], v[176:179], v[88:91]
	v_mfma_f32_16x16x32_bf16 v[88:91], v[220:223], v[180:183], v[88:91]
	v_mfma_f32_16x16x32_bf16 v[80:83], v[216:219], v[184:187], v[80:83]
	v_mfma_f32_16x16x32_bf16 v[80:83], v[220:223], v[188:191], v[80:83]
	v_mfma_f32_16x16x32_bf16 v[72:75], v[216:219], v[192:195], v[72:75]
	v_mfma_f32_16x16x32_bf16 v[72:75], v[220:223], v[212:215], v[72:75]
	v_mfma_f32_16x16x32_bf16 v[92:95], v[224:227], v[168:171], v[92:95]
	v_mfma_f32_16x16x32_bf16 v[92:95], v[228:231], v[172:175], v[92:95]
	v_mfma_f32_16x16x32_bf16 v[84:87], v[224:227], v[176:179], v[84:87]
	v_mfma_f32_16x16x32_bf16 v[84:87], v[228:231], v[180:183], v[84:87]
	v_mfma_f32_16x16x32_bf16 v[76:79], v[224:227], v[184:187], v[76:79]
	v_mfma_f32_16x16x32_bf16 v[76:79], v[228:231], v[188:191], v[76:79]
	v_mfma_f32_16x16x32_bf16 v[68:71], v[224:227], v[192:195], v[68:71]
	v_mfma_f32_16x16x32_bf16 v[68:71], v[228:231], v[212:215], v[68:71]
	s_barrier
; #define PG8_WAIT_V(n) asm volatile("s_waitcnt vmcnt(" #n ")" ::: "memory")
; #define PG8_WAIT_L(n) asm volatile("s_waitcnt lgkmcnt(" #n ")" ::: "memory")
; #define PG8_BAR __builtin_amdgcn_s_barrier()
; #define PG8_SCHED __builtin_amdgcn_sched_barrier(0)
; template <class Epi, class AddrA, class AddrB>
; __device__ __forceinline__ void gemm_phase(const Sched S, const int lda, const int ldb, const int K, const AddrA addrA,
;                                            const AddrB addrB, const Epi E) {
;     ...
;       PG8_LDB(B0, 0, 0); PG8_SCHED; PG8_LDA(At, 0, 0); PG8_STAGE(PG8_SA(1, 1), a1 + hstepA, voffA);
;       PG8_WAIT_L(8); PG8_BAR; PG8_WAIT_L(0); PG8_MMA(0, 0, At, B0); PG8_BAR; PG8_SCHED;
;       PG8_LDB(B1, 0, 1); PG8_STAGE(PG8_SB(0, 0), b2, voffB);
;       PG8_BAR; PG8_WAIT_L(0); PG8_MMA(0, 1, At, B1); PG8_BAR;
;       PG8_LDA(At, 0, 1); PG8_STAGE(PG8_SA(0, 0), a2, voffA);
;       PG8_BAR; PG8_WAIT_L(0); PG8_MMA(1, 0, At, B0); PG8_BAR; PG8_SCHED;
;       PG8_STAGE(PG8_SB(0, 1), b2 + hstepB, voffB);
;       PG8_WAIT_V(6); PG8_BAR; PG8_MMA(1, 1, At, B1); PG8_BAR;
;       PG8_LDB(B0, 1, 0); PG8_SCHED; PG8_LDA(At, 1, 0); PG8_STAGE(PG8_SA(0, 1), a2 + hstepA, voffA);
;       PG8_WAIT_L(8); PG8_BAR; PG8_WAIT_L(0); PG8_MMA(0, 0, At, B0); PG8_BAR; PG8_SCHED;
;       PG8_LDB(B1, 1, 1); PG8_STAGE(PG8_SB(1, 0), b3, voffB);
;       PG8_BAR; PG8_WAIT_L(0); PG8_MMA(0, 1, At, B1); PG8_BAR;
;       PG8_LDA(At, 1, 1); PG8_STAGE(PG8_SA(1, 0), a3, voffA);
;       PG8_BAR; PG8_WAIT_L(0); PG8_MMA(1, 0, At, B0); PG8_BAR; PG8_SCHED;
;       PG8_STAGE(PG8_SB(1, 1), b3 + hstepB, voffB);
;       PG8_WAIT_V(6); PG8_BAR; PG8_MMA(1, 1, At, B1); PG8_BAR;
	s_setprio 0
	ds_read_b128 v[168:171], v146 offset:49152
	ds_read_b128 v[172:175], v146 offset:50176
	ds_read_b128 v[176:179], v146 offset:51200
	ds_read_b128 v[180:183], v146 offset:52224
	ds_read_b128 v[184:187], v146 offset:53248
	ds_read_b128 v[188:191], v146 offset:54272
	ds_read_b128 v[192:195], v146 offset:55296
	ds_read_b128 v[212:215], v146 offset:56320
	global_load_lds_dwordx4 v[142:143], off
	v_lshl_add_u64 v[142:143], v[234:235], 0, s[52:53]
	s_mov_b32 m0, s31
	s_nop 0
	global_load_lds_dwordx4 v[142:143], off
	s_add_u32 s16, s16, 0x80080
	s_addc_u32 s17, s17, 0
	s_add_i32 s18, s18, s25
	v_lshl_add_u64 v[142:143], s[16:17], 0, v[2:3]
	s_mov_b32 m0, s18
	s_nop 0
	global_load_lds_dwordx4 v[142:143], off
	v_lshl_add_u64 v[142:143], s[16:17], 0, v[0:1]
	s_add_i32 m0, s18, 0x2000
	s_nop 0
	global_load_lds_dwordx4 v[142:143], off
	s_add_i32 s38, s38, 2
	s_add_u32 s36, s36, 0x100
	s_addc_u32 s37, s37, 0
	s_add_u32 s14, s14, 0x100
	s_addc_u32 s15, s15, 0
	s_waitcnt vmcnt(8)
	s_waitcnt lgkmcnt(0)
	s_setprio 1
	s_barrier
	v_mfma_f32_16x16x32_bf16 v[64:67], v[148:151], v[168:171], v[64:67]
	v_mfma_f32_16x16x32_bf16 v[64:67], v[152:155], v[172:175], v[64:67]
	s_waitcnt lgkmcnt(0)
	v_mfma_f32_16x16x32_bf16 v[56:59], v[148:151], v[176:179], v[56:59]
	v_mfma_f32_16x16x32_bf16 v[56:59], v[152:155], v[180:183], v[56:59]
	v_mfma_f32_16x16x32_bf16 v[48:51], v[148:151], v[184:187], v[48:51]
	v_mfma_f32_16x16x32_bf16 v[48:51], v[152:155], v[188:191], v[48:51]
	v_mfma_f32_16x16x32_bf16 v[40:43], v[148:151], v[192:195], v[40:43]
	v_mfma_f32_16x16x32_bf16 v[40:43], v[152:155], v[212:215], v[40:43]
	v_mfma_f32_16x16x32_bf16 v[60:63], v[156:159], v[168:171], v[60:63]
	v_mfma_f32_16x16x32_bf16 v[60:63], v[160:163], v[172:175], v[60:63]
	v_mfma_f32_16x16x32_bf16 v[52:55], v[156:159], v[176:179], v[52:55]
	v_mfma_f32_16x16x32_bf16 v[52:55], v[160:163], v[180:183], v[52:55]
	v_mfma_f32_16x16x32_bf16 v[44:47], v[156:159], v[184:187], v[44:47]
	v_mfma_f32_16x16x32_bf16 v[44:47], v[160:163], v[188:191], v[44:47]
	v_mfma_f32_16x16x32_bf16 v[36:39], v[156:159], v[192:195], v[36:39]
	v_mfma_f32_16x16x32_bf16 v[36:39], v[160:163], v[212:215], v[36:39]
	v_mfma_f32_16x16x32_bf16 v[32:35], v[216:219], v[168:171], v[32:35]
	v_mfma_f32_16x16x32_bf16 v[32:35], v[220:223], v[172:175], v[32:35]
	v_mfma_f32_16x16x32_bf16 v[24:27], v[216:219], v[176:179], v[24:27]
	v_mfma_f32_16x16x32_bf16 v[24:27], v[220:223], v[180:183], v[24:27]
	v_mfma_f32_16x16x32_bf16 v[16:19], v[216:219], v[184:187], v[16:19]
	v_mfma_f32_16x16x32_bf16 v[16:19], v[220:223], v[188:191], v[16:19]
	v_mfma_f32_16x16x32_bf16 v[8:11], v[216:219], v[192:195], v[8:11]
	v_mfma_f32_16x16x32_bf16 v[8:11], v[220:223], v[212:215], v[8:11]
	v_mfma_f32_16x16x32_bf16 v[28:31], v[224:227], v[168:171], v[28:31]
	v_mfma_f32_16x16x32_bf16 v[28:31], v[228:231], v[172:175], v[28:31]
	v_mfma_f32_16x16x32_bf16 v[20:23], v[224:227], v[176:179], v[20:23]
	v_mfma_f32_16x16x32_bf16 v[20:23], v[228:231], v[180:183], v[20:23]
	v_mfma_f32_16x16x32_bf16 v[12:15], v[224:227], v[184:187], v[12:15]
	v_mfma_f32_16x16x32_bf16 v[12:15], v[228:231], v[188:191], v[12:15]
	v_mfma_f32_16x16x32_bf16 v[4:7], v[224:227], v[192:195], v[4:7]
	v_mfma_f32_16x16x32_bf16 v[4:7], v[228:231], v[212:215], v[4:7]
	s_barrier
	s_setprio 0
	s_cmp_gt_u32 s38, 29
.LBB0_619:
	s_add_i32 s39, 0, 0x10000
	v_add_u32_e32 v142, s39, v144
	ds_read_b128 v[148:151], v142
	ds_read_b128 v[152:155], v142 offset:1024
	ds_read_b128 v[156:159], v142 offset:2048
	ds_read_b128 v[160:163], v142 offset:3072
	v_lshl_add_u64 v[142:143], s[14:15], 0, v[140:141]
	s_add_i32 m0, s26, 0xc000
	ds_read_b128 v[168:171], v146
	ds_read_b128 v[172:175], v146 offset:1024
	ds_read_b128 v[176:179], v146 offset:2048
	ds_read_b128 v[180:183], v146 offset:3072
	ds_read_b128 v[184:187], v146 offset:4096
	ds_read_b128 v[188:191], v146 offset:5120
	ds_read_b128 v[192:195], v146 offset:6144
	ds_read_b128 v[212:215], v146 offset:7168
	global_load_lds_dwordx4 v[142:143], off
	v_lshl_add_u64 v[142:143], s[14:15], 0, v[138:139]
	s_add_i32 m0, s26, 0xe000
	s_nop 0
	global_load_lds_dwordx4 v[142:143], off
	s_waitcnt lgkmcnt(6)
	s_setprio 1
	s_barrier
	v_mfma_f32_16x16x32_bf16 v[128:131], v[148:151], v[168:171], v[128:131]
	v_mfma_f32_16x16x32_bf16 v[128:131], v[152:155], v[172:175], v[128:131]
	s_waitcnt lgkmcnt(0)
	v_mfma_f32_16x16x32_bf16 v[120:123], v[148:151], v[176:179], v[120:123]
	v_mfma_f32_16x16x32_bf16 v[120:123], v[152:155], v[180:183], v[120:123]
	v_mfma_f32_16x16x32_bf16 v[112:115], v[148:151], v[184:187], v[112:115]
	v_mfma_f32_16x16x32_bf16 v[112:115], v[152:155], v[188:191], v[112:115]
	v_mfma_f32_16x16x32_bf16 v[104:107], v[148:151], v[192:195], v[104:107]
	v_mfma_f32_16x16x32_bf16 v[104:107], v[152:155], v[212:215], v[104:107]
	v_mfma_f32_16x16x32_bf16 v[124:127], v[156:159], v[168:171], v[124:127]
	v_mfma_f32_16x16x32_bf16 v[124:127], v[160:163], v[172:175], v[124:127]
	v_mfma_f32_16x16x32_bf16 v[116:119], v[156:159], v[176:179], v[116:119]
	v_mfma_f32_16x16x32_bf16 v[116:119], v[160:163], v[180:183], v[116:119]
	v_mfma_f32_16x16x32_bf16 v[108:111], v[156:159], v[184:187], v[108:111]
	v_mfma_f32_16x16x32_bf16 v[108:111], v[160:163], v[188:191], v[108:111]
	v_mfma_f32_16x16x32_bf16 v[100:103], v[156:159], v[192:195], v[100:103]
	v_mfma_f32_16x16x32_bf16 v[100:103], v[160:163], v[212:215], v[100:103]
	s_barrier
; #define PG8_WAIT_V(n) asm volatile("s_waitcnt vmcnt(" #n ")" ::: "memory")
; #define PG8_WAIT_L(n) asm volatile("s_waitcnt lgkmcnt(" #n ")" ::: "memory")
; #define PG8_BAR __builtin_amdgcn_s_barrier()
; #define PG8_SCHED __builtin_amdgcn_sched_barrier(0)
; template <class Epi, class AddrA, class AddrB>
; __device__ __forceinline__ void gemm_phase(const Sched S, const int lda, const int ldb, const int K, const AddrA addrA,
;                                            const AddrB addrB, const Epi E) {
;     ...
;     for (int t = 0; t < nt; t += 2) {
;       const bool last = (t == nt - 2);
;       const char* a1 = cA + (size_t)(t + 1) * kstep;
;       const char* a2 = last ? nA : cA + (size_t)(t + 2) * kstep;
;       const char* b2 = last ? nB : cB + (size_t)(t + 2) * kstep;
;       const char* a3 = a2 + kstep;
;       const char* b3 = b2 + kstep;
;       PG8_LDB(B0, 0, 0); PG8_SCHED; PG8_LDA(At, 0, 0); PG8_STAGE(PG8_SA(1, 1), a1 + hstepA, voffA);
;       PG8_WAIT_L(8); PG8_BAR; PG8_WAIT_L(0); PG8_MMA(0, 0, At, B0); PG8_BAR; PG8_SCHED;
;       PG8_LDB(B1, 0, 1); PG8_STAGE(PG8_SB(0, 0), b2, voffB);
;       PG8_BAR; PG8_WAIT_L(0); PG8_MMA(0, 1, At, B1); PG8_BAR;
;       PG8_LDA(At, 0, 1); PG8_STAGE(PG8_SA(0, 0), a2, voffA);
;       PG8_BAR; PG8_WAIT_L(0); PG8_MMA(1, 0, At, B0); PG8_BAR; PG8_SCHED;
;       PG8_STAGE(PG8_SB(0, 1), b2 + hstepB, voffB);
;       PG8_WAIT_V(6); PG8_BAR; PG8_MMA(1, 1, At, B1); PG8_BAR;
;       PG8_LDB(B0, 1, 0); PG8_SCHED; PG8_LDA(At, 1, 0); PG8_STAGE(PG8_SA(0, 1), a2 + hstepA, voffA);
;       PG8_WAIT_L(8); PG8_BAR; PG8_WAIT_L(0); PG8_MMA(0, 0, At, B0); PG8_BAR; PG8_SCHED;
;       PG8_LDB(B1, 1, 1); PG8_STAGE(PG8_SB(1, 0), b3, voffB);
;       PG8_BAR; PG8_WAIT_L(0); PG8_MMA(0, 1, At, B1); PG8_BAR;
;       PG8_LDA(At, 1, 1); PG8_STAGE(PG8_SA(1, 0), a3, voffA);
;       PG8_BAR; PG8_WAIT_L(0); PG8_MMA(1, 0, At, B0); PG8_BAR; PG8_SCHED;
;       PG8_STAGE(PG8_SB(1, 1), b3 + hstepB, voffB);
;       PG8_WAIT_V(6); PG8_BAR; PG8_MMA(1, 1, At, B1); PG8_BAR;
	s_setprio 0
	s_add_u32 s16, s14, 0xfff80080
	s_addc_u32 s17, s15, -1
	s_cmp_eq_u32 s38, 28
	s_cselect_b32 s19, s3, s17
	s_cselect_b32 s18, s13, s16
	s_cselect_b32 s17, s5, s37
	s_cselect_b32 s16, s35, s36
	s_add_i32 s42, 0, 0x14000
	v_add_u32_e32 v142, s42, v144
	s_add_i32 s39, s39, s25
	ds_read_b128 v[216:219], v142
	ds_read_b128 v[220:223], v142 offset:1024
	ds_read_b128 v[224:227], v142 offset:2048
	ds_read_b128 v[228:231], v142 offset:3072
	v_lshl_add_u64 v[142:143], s[16:17], 0, v[2:3]
	s_mov_b32 m0, s39
	v_lshl_add_u64 v[196:197], s[16:17], 0, v[0:1]
	global_load_lds_dwordx4 v[142:143], off
	s_add_i32 m0, s39, 0x2000
	s_nop 0
	global_load_lds_dwordx4 v[196:197], off
	s_mov_b32 m0, s26
	v_lshl_add_u64 v[232:233], s[18:19], 0, v[134:135]
	s_waitcnt vmcnt(10)
	s_waitcnt lgkmcnt(0)
	s_setprio 1
	s_barrier
	v_mfma_f32_16x16x32_bf16 v[96:99], v[216:219], v[168:171], v[96:99]
	v_mfma_f32_16x16x32_bf16 v[96:99], v[220:223], v[172:175], v[96:99]
	s_waitcnt lgkmcnt(0)
	v_mfma_f32_16x16x32_bf16 v[88:91], v[216:219], v[176:179], v[88:91]
	v_mfma_f32_16x16x32_bf16 v[88:91], v[220:223], v[180:183], v[88:91]
	v_mfma_f32_16x16x32_bf16 v[80:83], v[216:219], v[184:187], v[80:83]
	v_mfma_f32_16x16x32_bf16 v[80:83], v[220:223], v[188:191], v[80:83]
	v_mfma_f32_16x16x32_bf16 v[72:75], v[216:219], v[192:195], v[72:75]
	v_mfma_f32_16x16x32_bf16 v[72:75], v[220:223], v[212:215], v[72:75]
	v_mfma_f32_16x16x32_bf16 v[92:95], v[224:227], v[168:171], v[92:95]
	v_mfma_f32_16x16x32_bf16 v[92:95], v[228:231], v[172:175], v[92:95]
	v_mfma_f32_16x16x32_bf16 v[84:87], v[224:227], v[176:179], v[84:87]
	v_mfma_f32_16x16x32_bf16 v[84:87], v[228:231], v[180:183], v[84:87]
	v_mfma_f32_16x16x32_bf16 v[76:79], v[224:227], v[184:187], v[76:79]
	v_mfma_f32_16x16x32_bf16 v[76:79], v[228:231], v[188:191], v[76:79]
	v_mfma_f32_16x16x32_bf16 v[68:71], v[224:227], v[192:195], v[68:71]
	v_mfma_f32_16x16x32_bf16 v[68:71], v[228:231], v[212:215], v[68:71]
	s_barrier
	s_setprio 0
	ds_read_b128 v[168:171], v146 offset:16384
	ds_read_b128 v[172:175], v146 offset:17408
	ds_read_b128 v[176:179], v146 offset:18432
	ds_read_b128 v[180:183], v146 offset:19456
	ds_read_b128 v[184:187], v146 offset:20480
	ds_read_b128 v[188:191], v146 offset:21504
	ds_read_b128 v[192:195], v146 offset:22528
	ds_read_b128 v[212:215], v146 offset:23552
	global_load_lds_dwordx4 v[232:233], off
	v_lshl_add_u64 v[234:235], s[18:19], 0, v[132:133]
	s_mov_b32 m0, s27
	s_nop 0
	global_load_lds_dwordx4 v[234:235], off
	s_add_u32 s40, s16, 0x80000
	s_addc_u32 s41, s17, 0
	s_add_i32 s39, s42, s25
	v_lshl_add_u64 v[246:247], s[40:41], 0, v[2:3]
	s_mov_b32 m0, s39
	s_nop 0
	global_load_lds_dwordx4 v[246:247], off
	v_lshl_add_u64 v[246:247], s[40:41], 0, v[0:1]
	s_add_i32 m0, s39, 0x2000
	s_nop 0
	global_load_lds_dwordx4 v[246:247], off
	s_add_i32 s39, 0, 0x18000
	v_add_u32_e32 v147, s39, v144
	s_waitcnt vmcnt(8)
	s_waitcnt lgkmcnt(0)
	s_setprio 1
	s_barrier
	v_mfma_f32_16x16x32_bf16 v[64:67], v[148:151], v[168:171], v[64:67]
	v_mfma_f32_16x16x32_bf16 v[64:67], v[152:155], v[172:175], v[64:67]
	s_waitcnt lgkmcnt(0)
	v_mfma_f32_16x16x32_bf16 v[56:59], v[148:151], v[176:179], v[56:59]
	v_mfma_f32_16x16x32_bf16 v[56:59], v[152:155], v[180:183], v[56:59]
	v_mfma_f32_16x16x32_bf16 v[48:51], v[148:151], v[184:187], v[48:51]
	v_mfma_f32_16x16x32_bf16 v[48:51], v[152:155], v[188:191], v[48:51]
	v_mfma_f32_16x16x32_bf16 v[40:43], v[148:151], v[192:195], v[40:43]
	v_mfma_f32_16x16x32_bf16 v[40:43], v[152:155], v[212:215], v[40:43]
	v_mfma_f32_16x16x32_bf16 v[60:63], v[156:159], v[168:171], v[60:63]
	v_mfma_f32_16x16x32_bf16 v[60:63], v[160:163], v[172:175], v[60:63]
	v_mfma_f32_16x16x32_bf16 v[52:55], v[156:159], v[176:179], v[52:55]
	v_mfma_f32_16x16x32_bf16 v[52:55], v[160:163], v[180:183], v[52:55]
	v_mfma_f32_16x16x32_bf16 v[44:47], v[156:159], v[184:187], v[44:47]
	v_mfma_f32_16x16x32_bf16 v[44:47], v[160:163], v[188:191], v[44:47]
	v_mfma_f32_16x16x32_bf16 v[36:39], v[156:159], v[192:195], v[36:39]
	v_mfma_f32_16x16x32_bf16 v[36:39], v[160:163], v[212:215], v[36:39]
	v_mfma_f32_16x16x32_bf16 v[32:35], v[216:219], v[168:171], v[32:35]
	v_mfma_f32_16x16x32_bf16 v[32:35], v[220:223], v[172:175], v[32:35]
	v_mfma_f32_16x16x32_bf16 v[24:27], v[216:219], v[176:179], v[24:27]
	v_mfma_f32_16x16x32_bf16 v[24:27], v[220:223], v[180:183], v[24:27]
	v_mfma_f32_16x16x32_bf16 v[16:19], v[216:219], v[184:187], v[16:19]
	v_mfma_f32_16x16x32_bf16 v[16:19], v[220:223], v[188:191], v[16:19]
	v_mfma_f32_16x16x32_bf16 v[8:11], v[216:219], v[192:195], v[8:11]
	v_mfma_f32_16x16x32_bf16 v[8:11], v[220:223], v[212:215], v[8:11]
	v_mfma_f32_16x16x32_bf16 v[28:31], v[224:227], v[168:171], v[28:31]
	v_mfma_f32_16x16x32_bf16 v[28:31], v[228:231], v[172:175], v[28:31]
	v_mfma_f32_16x16x32_bf16 v[20:23], v[224:227], v[176:179], v[20:23]
	v_mfma_f32_16x16x32_bf16 v[20:23], v[228:231], v[180:183], v[20:23]
	v_mfma_f32_16x16x32_bf16 v[12:15], v[224:227], v[184:187], v[12:15]
	v_mfma_f32_16x16x32_bf16 v[12:15], v[228:231], v[188:191], v[12:15]
	v_mfma_f32_16x16x32_bf16 v[4:7], v[224:227], v[192:195], v[4:7]
	v_mfma_f32_16x16x32_bf16 v[4:7], v[228:231], v[212:215], v[4:7]
	s_barrier
	s_setprio 0
	ds_read_b128 v[148:151], v147
	ds_read_b128 v[152:155], v147 offset:1024
	ds_read_b128 v[156:159], v147 offset:2048
	ds_read_b128 v[160:163], v147 offset:3072
	s_add_u32 s18, s18, 0x80000
	s_addc_u32 s19, s19, 0
	s_mov_b32 m0, s28
	v_lshl_add_u64 v[216:217], s[18:19], 0, v[134:135]
	ds_read_b128 v[168:171], v146 offset:32768
	ds_read_b128 v[172:175], v146 offset:33792
	ds_read_b128 v[176:179], v146 offset:34816
	ds_read_b128 v[180:183], v146 offset:35840
	ds_read_b128 v[184:187], v146 offset:36864
	ds_read_b128 v[188:191], v146 offset:37888
	ds_read_b128 v[192:195], v146 offset:38912
	ds_read_b128 v[212:215], v146 offset:39936
	global_load_lds_dwordx4 v[216:217], off
	v_lshl_add_u64 v[216:217], s[18:19], 0, v[132:133]
	s_mov_b32 m0, s29
	s_nop 0
	global_load_lds_dwordx4 v[216:217], off
	s_waitcnt lgkmcnt(6)
	s_setprio 1
	s_barrier
; #define PG8_WAIT_V(n) asm volatile("s_waitcnt vmcnt(" #n ")" ::: "memory")
; #define PG8_WAIT_L(n) asm volatile("s_waitcnt lgkmcnt(" #n ")" ::: "memory")
; #define PG8_BAR __builtin_amdgcn_s_barrier()
; #define PG8_SCHED __builtin_amdgcn_sched_barrier(0)
; template <class Epi, class AddrA, class AddrB>
; __device__ __forceinline__ void gemm_phase(const Sched S, const int lda, const int ldb, const int K, const AddrA addrA,
;                                            const AddrB addrB, const Epi E) {
;     ...
;       PG8_LDB(B0, 0, 0); PG8_SCHED; PG8_LDA(At, 0, 0); PG8_STAGE(PG8_SA(1, 1), a1 + hstepA, voffA);
;       PG8_WAIT_L(8); PG8_BAR; PG8_WAIT_L(0); PG8_MMA(0, 0, At, B0); PG8_BAR; PG8_SCHED;
;       PG8_LDB(B1, 0, 1); PG8_STAGE(PG8_SB(0, 0), b2, voffB);
;       PG8_BAR; PG8_WAIT_L(0); PG8_MMA(0, 1, At, B1); PG8_BAR;
;       PG8_LDA(At, 0, 1); PG8_STAGE(PG8_SA(0, 0), a2, voffA);
;       PG8_BAR; PG8_WAIT_L(0); PG8_MMA(1, 0, At, B0); PG8_BAR; PG8_SCHED;
;       PG8_STAGE(PG8_SB(0, 1), b2 + hstepB, voffB);
;       PG8_WAIT_V(6); PG8_BAR; PG8_MMA(1, 1, At, B1); PG8_BAR;
;       PG8_LDB(B0, 1, 0); PG8_SCHED; PG8_LDA(At, 1, 0); PG8_STAGE(PG8_SA(0, 1), a2 + hstepA, voffA);
;       PG8_WAIT_L(8); PG8_BAR; PG8_WAIT_L(0); PG8_MMA(0, 0, At, B0); PG8_BAR; PG8_SCHED;
;       PG8_LDB(B1, 1, 1); PG8_STAGE(PG8_SB(1, 0), b3, voffB);
;       PG8_BAR; PG8_WAIT_L(0); PG8_MMA(0, 1, At, B1); PG8_BAR;
;       PG8_LDA(At, 1, 1); PG8_STAGE(PG8_SA(1, 0), a3, voffA);
;       PG8_BAR; PG8_WAIT_L(0); PG8_MMA(1, 0, At, B0); PG8_BAR; PG8_SCHED;
;       PG8_STAGE(PG8_SB(1, 1), b3 + hstepB, voffB);
;       PG8_WAIT_V(6); PG8_BAR; PG8_MMA(1, 1, At, B1); PG8_BAR;
	v_mfma_f32_16x16x32_bf16 v[128:131], v[148:151], v[168:171], v[128:131]
	v_mfma_f32_16x16x32_bf16 v[128:131], v[152:155], v[172:175], v[128:131]
	s_waitcnt lgkmcnt(0)
	v_mfma_f32_16x16x32_bf16 v[120:123], v[148:151], v[176:179], v[120:123]
	v_mfma_f32_16x16x32_bf16 v[120:123], v[152:155], v[180:183], v[120:123]
	v_mfma_f32_16x16x32_bf16 v[112:115], v[148:151], v[184:187], v[112:115]
	v_mfma_f32_16x16x32_bf16 v[112:115], v[152:155], v[188:191], v[112:115]
	v_mfma_f32_16x16x32_bf16 v[104:107], v[148:151], v[192:195], v[104:107]
	v_mfma_f32_16x16x32_bf16 v[104:107], v[152:155], v[212:215], v[104:107]
	v_mfma_f32_16x16x32_bf16 v[124:127], v[156:159], v[168:171], v[124:127]
	v_mfma_f32_16x16x32_bf16 v[124:127], v[160:163], v[172:175], v[124:127]
	v_mfma_f32_16x16x32_bf16 v[116:119], v[156:159], v[176:179], v[116:119]
	v_mfma_f32_16x16x32_bf16 v[116:119], v[160:163], v[180:183], v[116:119]
	v_mfma_f32_16x16x32_bf16 v[108:111], v[156:159], v[184:187], v[108:111]
	v_mfma_f32_16x16x32_bf16 v[108:111], v[160:163], v[188:191], v[108:111]
	v_mfma_f32_16x16x32_bf16 v[100:103], v[156:159], v[192:195], v[100:103]
	v_mfma_f32_16x16x32_bf16 v[100:103], v[160:163], v[212:215], v[100:103]
	s_barrier
	s_setprio 0
	s_add_i32 s18, 0, 0x1c000
	s_add_i32 s19, s39, s25
	v_add_u32_e32 v147, s18, v144
	v_lshl_add_u64 v[142:143], v[142:143], 0, s[52:53]
	s_mov_b32 m0, s19
	ds_read_b128 v[216:219], v147
	ds_read_b128 v[220:223], v147 offset:1024
	ds_read_b128 v[224:227], v147 offset:2048
	ds_read_b128 v[228:231], v147 offset:3072
	global_load_lds_dwordx4 v[142:143], off
	v_lshl_add_u64 v[142:143], v[196:197], 0, s[52:53]
	s_add_i32 m0, s19, 0x2000
	s_nop 0
	global_load_lds_dwordx4 v[142:143], off
	s_mov_b32 m0, s30
	v_lshl_add_u64 v[142:143], v[232:233], 0, s[52:53]
	s_waitcnt vmcnt(10)
	s_waitcnt lgkmcnt(0)
	s_setprio 1
	s_barrier
	v_mfma_f32_16x16x32_bf16 v[96:99], v[216:219], v[168:171], v[96:99]
	v_mfma_f32_16x16x32_bf16 v[96:99], v[220:223], v[172:175], v[96:99]
	s_waitcnt lgkmcnt(0)
	v_mfma_f32_16x16x32_bf16 v[88:91], v[216:219], v[176:179], v[88:91]
	v_mfma_f32_16x16x32_bf16 v[88:91], v[220:223], v[180:183], v[88:91]
	v_mfma_f32_16x16x32_bf16 v[80:83], v[216:219], v[184:187], v[80:83]
	v_mfma_f32_16x16x32_bf16 v[80:83], v[220:223], v[188:191], v[80:83]
	v_mfma_f32_16x16x32_bf16 v[72:75], v[216:219], v[192:195], v[72:75]
	v_mfma_f32_16x16x32_bf16 v[72:75], v[220:223], v[212:215], v[72:75]
	v_mfma_f32_16x16x32_bf16 v[92:95], v[224:227], v[168:171], v[92:95]
	v_mfma_f32_16x16x32_bf16 v[92:95], v[228:231], v[172:175], v[92:95]
	v_mfma_f32_16x16x32_bf16 v[84:87], v[224:227], v[176:179], v[84:87]
	v_mfma_f32_16x16x32_bf16 v[84:87], v[228:231], v[180:183], v[84:87]
	v_mfma_f32_16x16x32_bf16 v[76:79], v[224:227], v[184:187], v[76:79]
	v_mfma_f32_16x16x32_bf16 v[76:79], v[228:231], v[188:191], v[76:79]
	v_mfma_f32_16x16x32_bf16 v[68:71], v[224:227], v[192:195], v[68:71]
	v_mfma_f32_16x16x32_bf16 v[68:71], v[228:231], v[212:215], v[68:71]
	s_barrier
	s_setprio 0
	ds_read_b128 v[168:171], v146 offset:49152
	ds_read_b128 v[172:175], v146 offset:50176
	ds_read_b128 v[176:179], v146 offset:51200
	ds_read_b128 v[180:183], v146 offset:52224
	ds_read_b128 v[184:187], v146 offset:53248
	ds_read_b128 v[188:191], v146 offset:54272
	ds_read_b128 v[192:195], v146 offset:55296
	ds_read_b128 v[212:215], v146 offset:56320
	global_load_lds_dwordx4 v[142:143], off
	v_lshl_add_u64 v[142:143], v[234:235], 0, s[52:53]
	s_mov_b32 m0, s31
	s_nop 0
	global_load_lds_dwordx4 v[142:143], off
	s_add_u32 s16, s16, 0x80080
	s_addc_u32 s17, s17, 0
	s_add_i32 s18, s18, s25
	v_lshl_add_u64 v[142:143], s[16:17], 0, v[2:3]
	s_mov_b32 m0, s18
	s_nop 0
	global_load_lds_dwordx4 v[142:143], off
	v_lshl_add_u64 v[142:143], s[16:17], 0, v[0:1]
	s_add_i32 m0, s18, 0x2000
	s_nop 0
	global_load_lds_dwordx4 v[142:143], off
	s_add_i32 s38, s38, 2
	s_add_u32 s36, s36, 0x100
	s_addc_u32 s37, s37, 0
	s_add_u32 s14, s14, 0x100
	s_addc_u32 s15, s15, 0
	s_waitcnt vmcnt(8)
	s_waitcnt lgkmcnt(0)
	s_setprio 1
	s_barrier
	v_mfma_f32_16x16x32_bf16 v[64:67], v[148:151], v[168:171], v[64:67]
	v_mfma_f32_16x16x32_bf16 v[64:67], v[152:155], v[172:175], v[64:67]
	s_waitcnt lgkmcnt(0)
	v_mfma_f32_16x16x32_bf16 v[56:59], v[148:151], v[176:179], v[56:59]
	v_mfma_f32_16x16x32_bf16 v[56:59], v[152:155], v[180:183], v[56:59]
	v_mfma_f32_16x16x32_bf16 v[48:51], v[148:151], v[184:187], v[48:51]
	v_mfma_f32_16x16x32_bf16 v[48:51], v[152:155], v[188:191], v[48:51]
	v_mfma_f32_16x16x32_bf16 v[40:43], v[148:151], v[192:195], v[40:43]
	v_mfma_f32_16x16x32_bf16 v[40:43], v[152:155], v[212:215], v[40:43]
	v_mfma_f32_16x16x32_bf16 v[60:63], v[156:159], v[168:171], v[60:63]
	v_mfma_f32_16x16x32_bf16 v[60:63], v[160:163], v[172:175], v[60:63]
	v_mfma_f32_16x16x32_bf16 v[52:55], v[156:159], v[176:179], v[52:55]
	v_mfma_f32_16x16x32_bf16 v[52:55], v[160:163], v[180:183], v[52:55]
	v_mfma_f32_16x16x32_bf16 v[44:47], v[156:159], v[184:187], v[44:47]
	v_mfma_f32_16x16x32_bf16 v[44:47], v[160:163], v[188:191], v[44:47]
	v_mfma_f32_16x16x32_bf16 v[36:39], v[156:159], v[192:195], v[36:39]
	v_mfma_f32_16x16x32_bf16 v[36:39], v[160:163], v[212:215], v[36:39]
	v_mfma_f32_16x16x32_bf16 v[32:35], v[216:219], v[168:171], v[32:35]
	v_mfma_f32_16x16x32_bf16 v[32:35], v[220:223], v[172:175], v[32:35]
	v_mfma_f32_16x16x32_bf16 v[24:27], v[216:219], v[176:179], v[24:27]
	v_mfma_f32_16x16x32_bf16 v[24:27], v[220:223], v[180:183], v[24:27]
	v_mfma_f32_16x16x32_bf16 v[16:19], v[216:219], v[184:187], v[16:19]
	v_mfma_f32_16x16x32_bf16 v[16:19], v[220:223], v[188:191], v[16:19]
	v_mfma_f32_16x16x32_bf16 v[8:11], v[216:219], v[192:195], v[8:11]
	v_mfma_f32_16x16x32_bf16 v[8:11], v[220:223], v[212:215], v[8:11]
	v_mfma_f32_16x16x32_bf16 v[28:31], v[224:227], v[168:171], v[28:31]
	v_mfma_f32_16x16x32_bf16 v[28:31], v[228:231], v[172:175], v[28:31]
	v_mfma_f32_16x16x32_bf16 v[20:23], v[224:227], v[176:179], v[20:23]
	v_mfma_f32_16x16x32_bf16 v[20:23], v[228:231], v[180:183], v[20:23]
	v_mfma_f32_16x16x32_bf16 v[12:15], v[224:227], v[184:187], v[12:15]
	v_mfma_f32_16x16x32_bf16 v[12:15], v[228:231], v[188:191], v[12:15]
	v_mfma_f32_16x16x32_bf16 v[4:7], v[224:227], v[192:195], v[4:7]
	v_mfma_f32_16x16x32_bf16 v[4:7], v[228:231], v[212:215], v[4:7]
	s_barrier
;   __device__ __forceinline__ void operator()(EPI_ARGS) const {
;     const size_t row0 = (size_t)u.pm * 256 + wr * 64 + fr;
;     const int col0 = u.pn * 256 + wc * 32 + 8 * fq;
; #pragma unroll
;     for (int ai = 0; ai < 2; ++ai)
; #pragma unroll
;       for (int bj = 0; bj < 2; ++bj) {
;         f32x4 x0[4], x1[4];
; #pragma unroll
;         for (int m = 0; m < 4; ++m) {
;           const size_t o = (row0 + ai * HALF + m * 16) * DM + col0 + bj * HALF;
;           x0[m] = *(const f32x4*)(xres + o);
;           x1[m] = *(const f32x4*)(xres + o + 4);
;         }
;         __builtin_amdgcn_sched_barrier(0);
; #pragma unroll
;         for (int m = 0; m < 4; ++m) {
;           const size_t o = (row0 + ai * HALF + m * 16) * DM + col0 + bj * HALF;
;           *(f32x4*)(hbuf + o) = acc[ai][bj][m][0] + x0[m] * ALPHA;
;           *(f32x4*)(hbuf + o + 4) = acc[ai][bj][m][1] + x1[m] * ALPHA;
;         }
;       }
;   }
	s_setprio 0
	s_cmp_gt_u32 s38, 29
	s_cbranch_scc0 .LBB0_619
	s_ashr_i32 s13, s12, 31
	v_lshl_or_b32 v142, s34, 8, v145
	v_ashrrev_i32_e32 v143, 31, v142
	s_lshl_b64 s[12:13], s[12:13], 21
	v_lshlrev_b64 v[184:185], 2, v[142:143]
	v_lshl_add_u64 v[188:189], s[12:13], 0, v[136:137]
	v_lshl_add_u64 v[186:187], s[0:1], 0, v[184:185]
	v_or_b32_e32 v190, 0x20000, v188
	v_mov_b32_e32 v191, v189
	v_or_b32_e32 v192, 0x40000, v188
	v_mov_b32_e32 v193, v189
	v_or_b32_e32 v194, 0x60000, v188
	v_mov_b32_e32 v195, v189
	v_lshl_add_u64 v[142:143], v[186:187], 0, v[188:189]
	v_lshl_add_u64 v[160:161], v[186:187], 0, v[190:191]
	v_lshl_add_u64 v[172:173], v[186:187], 0, v[192:193]
	v_lshl_add_u64 v[180:181], v[186:187], 0, v[194:195]
	flat_load_dwordx4 v[148:151], v[142:143]
	flat_load_dwordx4 v[152:155], v[142:143] offset:16
	flat_load_dwordx4 v[156:159], v[160:161]
	s_nop 0
	flat_load_dwordx4 v[160:163], v[160:161] offset:16
	s_nop 0
	flat_load_dwordx4 v[168:171], v[172:173]
	s_nop 0
	flat_load_dwordx4 v[172:175], v[172:173] offset:16
	s_nop 0
	flat_load_dwordx4 v[176:179], v[180:181]
	s_nop 0
	flat_load_dwordx4 v[180:183], v[180:181] offset:16
	v_lshl_add_u64 v[184:185], s[48:49], 0, v[184:185]
	s_mov_b32 s14, 0x3fb504f3
	s_waitcnt vmcnt(0) lgkmcnt(0)
	v_pk_fma_f32 v[148:149], v[148:149], s[14:15], v[128:129] op_sel_hi:[1,0,1]
	v_lshl_add_u64 v[128:129], v[184:185], 0, v[188:189]
	v_pk_fma_f32 v[126:127], v[154:155], s[14:15], v[126:127] op_sel_hi:[1,0,1]
	v_pk_fma_f32 v[124:125], v[152:153], s[14:15], v[124:125] op_sel_hi:[1,0,1]
	global_store_dwordx4 v[128:129], v[124:127], off offset:16
	v_pk_fma_f32 v[118:119], v[162:163], s[14:15], v[118:119] op_sel_hi:[1,0,1]
	v_pk_fma_f32 v[116:117], v[160:161], s[14:15], v[116:117] op_sel_hi:[1,0,1]
	v_lshl_add_u64 v[124:125], v[184:185], 0, v[190:191]
	v_pk_fma_f32 v[122:123], v[158:159], s[14:15], v[122:123] op_sel_hi:[1,0,1]
	v_pk_fma_f32 v[120:121], v[156:157], s[14:15], v[120:121] op_sel_hi:[1,0,1]
	global_store_dwordx4 v[124:125], v[116:119], off offset:16
	v_pk_fma_f32 v[110:111], v[174:175], s[14:15], v[110:111] op_sel_hi:[1,0,1]
	v_pk_fma_f32 v[108:109], v[172:173], s[14:15], v[108:109] op_sel_hi:[1,0,1]
	v_lshl_add_u64 v[116:117], v[184:185], 0, v[192:193]
	s_mov_b64 s[12:13], 0x200
	v_pk_fma_f32 v[150:151], v[150:151], s[14:15], v[130:131] op_sel_hi:[1,0,1]
	global_store_dwordx4 v[124:125], v[120:123], off
	v_pk_fma_f32 v[114:115], v[170:171], s[14:15], v[114:115] op_sel_hi:[1,0,1]
	v_pk_fma_f32 v[112:113], v[168:169], s[14:15], v[112:113] op_sel_hi:[1,0,1]
	global_store_dwordx4 v[116:117], v[108:111], off offset:16
	v_pk_fma_f32 v[106:107], v[178:179], s[14:15], v[106:107] op_sel_hi:[1,0,1]
	v_pk_fma_f32 v[104:105], v[176:177], s[14:15], v[104:105] op_sel_hi:[1,0,1]
	v_lshl_add_u64 v[108:109], v[184:185], 0, v[194:195]
	v_pk_fma_f32 v[102:103], v[182:183], s[14:15], v[102:103] op_sel_hi:[1,0,1]
	v_pk_fma_f32 v[100:101], v[180:181], s[14:15], v[100:101] op_sel_hi:[1,0,1]
	v_lshl_add_u64 v[124:125], v[186:187], 0, s[12:13]
	global_store_dwordx4 v[128:129], v[148:151], off
	global_store_dwordx4 v[116:117], v[112:115], off
	global_store_dwordx4 v[108:109], v[104:107], off
	global_store_dwordx4 v[108:109], v[100:103], off offset:16
	v_lshl_add_u64 v[112:113], v[124:125], 0, v[190:191]
	v_lshl_add_u64 v[120:121], v[124:125], 0, v[192:193]
	v_lshl_add_u64 v[130:131], v[124:125], 0, v[194:195]
	flat_load_dwordx4 v[100:103], v[142:143] offset:512
	flat_load_dwordx4 v[104:107], v[142:143] offset:528
	flat_load_dwordx4 v[108:111], v[112:113]
	s_nop 0
	flat_load_dwordx4 v[112:115], v[112:113] offset:16
	s_nop 0
	flat_load_dwordx4 v[116:119], v[120:121]
	s_nop 0
	flat_load_dwordx4 v[120:123], v[120:121] offset:16
	s_nop 0
	flat_load_dwordx4 v[124:127], v[130:131]
	flat_load_dwordx4 v[148:151], v[130:131] offset:16
	s_mov_b32 s3, 0x100000
	s_waitcnt vmcnt(0) lgkmcnt(0)
	v_pk_fma_f32 v[96:97], v[100:101], s[14:15], v[96:97] op_sel_hi:[1,0,1]
	v_add_co_u32_e32 v100, vcc, s3, v142
	s_mov_b32 s5, 0x120000
	s_nop 0
	v_addc_co_u32_e32 v101, vcc, 0, v143, vcc
	v_pk_fma_f32 v[98:99], v[102:103], s[14:15], v[98:99] op_sel_hi:[1,0,1]
	v_add_co_u32_e32 v102, vcc, s5, v142
	v_lshl_add_u64 v[130:131], v[184:185], 0, s[12:13]
	v_pk_fma_f32 v[94:95], v[106:107], s[14:15], v[94:95] op_sel_hi:[1,0,1]
	v_pk_fma_f32 v[92:93], v[104:105], s[14:15], v[92:93] op_sel_hi:[1,0,1]
	v_addc_co_u32_e32 v103, vcc, 0, v143, vcc
	s_mov_b32 s12, 0x140000
	global_store_dwordx4 v[128:129], v[92:95], off offset:528
	v_pk_fma_f32 v[86:87], v[114:115], s[14:15], v[86:87] op_sel_hi:[1,0,1]
	v_pk_fma_f32 v[84:85], v[112:113], s[14:15], v[84:85] op_sel_hi:[1,0,1]
	v_lshl_add_u64 v[92:93], v[130:131], 0, v[190:191]
	v_add_co_u32_e32 v104, vcc, s12, v142
	global_store_dwordx4 v[92:93], v[84:87], off offset:16
	v_pk_fma_f32 v[78:79], v[122:123], s[14:15], v[78:79] op_sel_hi:[1,0,1]
	v_pk_fma_f32 v[76:77], v[120:121], s[14:15], v[76:77] op_sel_hi:[1,0,1]
	v_lshl_add_u64 v[84:85], v[130:131], 0, v[192:193]
	v_addc_co_u32_e32 v105, vcc, 0, v143, vcc
	s_mov_b32 s13, 0x160000
	v_pk_fma_f32 v[90:91], v[110:111], s[14:15], v[90:91] op_sel_hi:[1,0,1]
	v_pk_fma_f32 v[88:89], v[108:109], s[14:15], v[88:89] op_sel_hi:[1,0,1]
	v_pk_fma_f32 v[82:83], v[118:119], s[14:15], v[82:83] op_sel_hi:[1,0,1]
	v_pk_fma_f32 v[80:81], v[116:117], s[14:15], v[80:81] op_sel_hi:[1,0,1]
	global_store_dwordx4 v[84:85], v[76:79], off offset:16
	v_pk_fma_f32 v[74:75], v[126:127], s[14:15], v[74:75] op_sel_hi:[1,0,1]
	v_pk_fma_f32 v[72:73], v[124:125], s[14:15], v[72:73] op_sel_hi:[1,0,1]
	v_lshl_add_u64 v[76:77], v[130:131], 0, v[194:195]
	v_pk_fma_f32 v[70:71], v[150:151], s[14:15], v[70:71] op_sel_hi:[1,0,1]
	v_pk_fma_f32 v[68:69], v[148:149], s[14:15], v[68:69] op_sel_hi:[1,0,1]
	s_mov_b64 s[16:17], 0x100000
	s_mov_b64 s[18:19], 0x120000
	s_mov_b64 s[34:35], 0x140000
	s_mov_b64 s[36:37], 0x160000
	v_add_co_u32_e32 v106, vcc, s13, v142
	global_store_dwordx4 v[128:129], v[96:99], off offset:512
	global_store_dwordx4 v[92:93], v[88:91], off
	global_store_dwordx4 v[84:85], v[80:83], off
	global_store_dwordx4 v[76:77], v[72:75], off
	global_store_dwordx4 v[76:77], v[68:71], off offset:16
	v_lshl_add_u64 v[80:81], v[142:143], 0, s[18:19]
	v_lshl_add_u64 v[72:73], v[142:143], 0, s[16:17]
	v_lshl_add_u64 v[88:89], v[142:143], 0, s[34:35]
	v_lshl_add_u64 v[96:97], v[142:143], 0, s[36:37]
	v_addc_co_u32_e32 v107, vcc, 0, v143, vcc
	flat_load_dwordx4 v[68:71], v[100:101]
	s_nop 0
	flat_load_dwordx4 v[72:75], v[72:73] offset:16
	s_nop 0
	flat_load_dwordx4 v[76:79], v[102:103]
	s_nop 0
	flat_load_dwordx4 v[80:83], v[80:81] offset:16
	s_nop 0
	flat_load_dwordx4 v[84:87], v[104:105]
	s_nop 0
	flat_load_dwordx4 v[88:91], v[88:89] offset:16
	s_nop 0
	flat_load_dwordx4 v[92:95], v[106:107]
	s_nop 0
	flat_load_dwordx4 v[96:99], v[96:97] offset:16
	s_waitcnt vmcnt(0) lgkmcnt(0)
; #define PG8_WAIT_V(n) asm volatile("s_waitcnt vmcnt(" #n ")" ::: "memory")
; #define PG8_BAR __builtin_amdgcn_s_barrier()
; template <class Epi, class AddrA, class AddrB>
; __device__ __forceinline__ void gemm_phase(const Sched S, const int lda, const int ldb, const int K, const AddrA addrA,
;                                            const AddrB addrB, const Epi E) {
;     ...
;   PG8_WAIT_V(0);
;   if (wr == 0) PG8_BAR;
;   PG8_BAR;
;   __device__ __forceinline__ void operator()(EPI_ARGS) const {
;     ...
; #pragma unroll
;         for (int m = 0; m < 4; ++m) {
;           const size_t o = (row0 + ai * HALF + m * 16) * DM + col0 + bj * HALF;
;           x0[m] = *(const f32x4*)(xres + o);
;           x1[m] = *(const f32x4*)(xres + o + 4);
;         }
;         __builtin_amdgcn_sched_barrier(0);
; #pragma unroll
;         for (int m = 0; m < 4; ++m) {
;           const size_t o = (row0 + ai * HALF + m * 16) * DM + col0 + bj * HALF;
;           *(f32x4*)(hbuf + o) = acc[ai][bj][m][0] + x0[m] * ALPHA;
;           *(f32x4*)(hbuf + o + 4) = acc[ai][bj][m][1] + x1[m] * ALPHA;
;         }
;       }
;   }
	v_pk_fma_f32 v[66:67], v[70:71], s[14:15], v[66:67] op_sel_hi:[1,0,1]
	v_add_co_u32_e32 v70, vcc, s3, v128
	v_pk_fma_f32 v[64:65], v[68:69], s[14:15], v[64:65] op_sel_hi:[1,0,1]
	v_lshl_add_u64 v[68:69], v[128:129], 0, s[16:17]
	v_addc_co_u32_e32 v71, vcc, 0, v129, vcc
	v_pk_fma_f32 v[62:63], v[74:75], s[14:15], v[62:63] op_sel_hi:[1,0,1]
	v_pk_fma_f32 v[60:61], v[72:73], s[14:15], v[60:61] op_sel_hi:[1,0,1]
	global_store_dwordx4 v[68:69], v[60:63], off offset:16
	v_add_co_u32_e32 v68, vcc, s5, v128
	s_nop 0
	v_lshl_add_u64 v[60:61], v[128:129], 0, s[18:19]
	v_addc_co_u32_e32 v69, vcc, 0, v129, vcc
	v_add_co_u32_e32 v72, vcc, s12, v128
	v_pk_fma_f32 v[54:55], v[82:83], s[14:15], v[54:55] op_sel_hi:[1,0,1]
	v_pk_fma_f32 v[52:53], v[80:81], s[14:15], v[52:53] op_sel_hi:[1,0,1]
	v_addc_co_u32_e32 v73, vcc, 0, v129, vcc
	global_store_dwordx4 v[60:61], v[52:55], off offset:16
	v_pk_fma_f32 v[46:47], v[90:91], s[14:15], v[46:47] op_sel_hi:[1,0,1]
	v_pk_fma_f32 v[44:45], v[88:89], s[14:15], v[44:45] op_sel_hi:[1,0,1]
	v_lshl_add_u64 v[52:53], v[128:129], 0, s[34:35]
	v_add_co_u32_e32 v74, vcc, s13, v128
	v_pk_fma_f32 v[58:59], v[78:79], s[14:15], v[58:59] op_sel_hi:[1,0,1]
	v_pk_fma_f32 v[56:57], v[76:77], s[14:15], v[56:57] op_sel_hi:[1,0,1]
	v_pk_fma_f32 v[50:51], v[86:87], s[14:15], v[50:51] op_sel_hi:[1,0,1]
	v_pk_fma_f32 v[48:49], v[84:85], s[14:15], v[48:49] op_sel_hi:[1,0,1]
	global_store_dwordx4 v[52:53], v[44:47], off offset:16
	v_pk_fma_f32 v[42:43], v[94:95], s[14:15], v[42:43] op_sel_hi:[1,0,1]
	v_pk_fma_f32 v[40:41], v[92:93], s[14:15], v[40:41] op_sel_hi:[1,0,1]
	v_lshl_add_u64 v[44:45], v[128:129], 0, s[36:37]
	v_addc_co_u32_e32 v75, vcc, 0, v129, vcc
	v_pk_fma_f32 v[38:39], v[98:99], s[14:15], v[38:39] op_sel_hi:[1,0,1]
	v_pk_fma_f32 v[36:37], v[96:97], s[14:15], v[36:37] op_sel_hi:[1,0,1]
	s_mov_b64 s[12:13], 0x100200
	s_mov_b64 s[16:17], 0x120200
	s_mov_b64 s[18:19], 0x140200
	s_mov_b64 s[34:35], 0x160200
	global_store_dwordx4 v[70:71], v[64:67], off
	global_store_dwordx4 v[68:69], v[56:59], off
	global_store_dwordx4 v[72:73], v[48:51], off
	global_store_dwordx4 v[74:75], v[40:43], off
	global_store_dwordx4 v[44:45], v[36:39], off offset:16
	v_lshl_add_u64 v[44:45], v[142:143], 0, s[12:13]
	v_lshl_add_u64 v[48:49], v[142:143], 0, s[16:17]
	v_lshl_add_u64 v[60:61], v[142:143], 0, s[18:19]
	v_lshl_add_u64 v[64:65], v[142:143], 0, s[34:35]
	flat_load_dwordx4 v[36:39], v[100:101] offset:512
	flat_load_dwordx4 v[40:43], v[102:103] offset:512
	s_nop 0
	flat_load_dwordx4 v[44:47], v[44:45] offset:16
	s_nop 0
	flat_load_dwordx4 v[48:51], v[48:49] offset:16
	s_nop 0
	flat_load_dwordx4 v[52:55], v[104:105] offset:512
	flat_load_dwordx4 v[56:59], v[106:107] offset:512
	s_nop 0
	flat_load_dwordx4 v[60:63], v[60:61] offset:16
	s_nop 0
	flat_load_dwordx4 v[64:67], v[64:65] offset:16
	s_waitcnt vmcnt(0) lgkmcnt(0)
	v_pk_fma_f32 v[32:33], v[36:37], s[14:15], v[32:33] op_sel_hi:[1,0,1]
	v_lshl_add_u64 v[36:37], v[128:129], 0, s[12:13]
	v_pk_fma_f32 v[30:31], v[46:47], s[14:15], v[30:31] op_sel_hi:[1,0,1]
	v_pk_fma_f32 v[28:29], v[44:45], s[14:15], v[28:29] op_sel_hi:[1,0,1]
	global_store_dwordx4 v[36:37], v[28:31], off offset:16
	v_pk_fma_f32 v[22:23], v[50:51], s[14:15], v[22:23] op_sel_hi:[1,0,1]
	v_pk_fma_f32 v[20:21], v[48:49], s[14:15], v[20:21] op_sel_hi:[1,0,1]
	v_lshl_add_u64 v[28:29], v[128:129], 0, s[16:17]
	global_store_dwordx4 v[28:29], v[20:23], off offset:16
	v_pk_fma_f32 v[14:15], v[62:63], s[14:15], v[14:15] op_sel_hi:[1,0,1]
	v_pk_fma_f32 v[12:13], v[60:61], s[14:15], v[12:13] op_sel_hi:[1,0,1]
	v_lshl_add_u64 v[20:21], v[128:129], 0, s[18:19]
	v_pk_fma_f32 v[34:35], v[38:39], s[14:15], v[34:35] op_sel_hi:[1,0,1]
	v_pk_fma_f32 v[26:27], v[42:43], s[14:15], v[26:27] op_sel_hi:[1,0,1]
	v_pk_fma_f32 v[24:25], v[40:41], s[14:15], v[24:25] op_sel_hi:[1,0,1]
	v_pk_fma_f32 v[18:19], v[54:55], s[14:15], v[18:19] op_sel_hi:[1,0,1]
	v_pk_fma_f32 v[16:17], v[52:53], s[14:15], v[16:17] op_sel_hi:[1,0,1]
	global_store_dwordx4 v[20:21], v[12:15], off offset:16
	v_pk_fma_f32 v[10:11], v[58:59], s[14:15], v[10:11] op_sel_hi:[1,0,1]
	v_pk_fma_f32 v[8:9], v[56:57], s[14:15], v[8:9] op_sel_hi:[1,0,1]
	v_lshl_add_u64 v[12:13], v[128:129], 0, s[34:35]
	v_pk_fma_f32 v[6:7], v[66:67], s[14:15], v[6:7] op_sel_hi:[1,0,1]
	v_pk_fma_f32 v[4:5], v[64:65], s[14:15], v[4:5] op_sel_hi:[1,0,1]
	s_and_b64 vcc, exec, s[6:7]
	s_mov_b32 s34, s4
	s_mov_b32 s12, s2
	s_mov_b64 s[14:15], s[10:11]
	s_mov_b64 s[16:17], s[8:9]
	global_store_dwordx4 v[70:71], v[32:35], off offset:512
	global_store_dwordx4 v[68:69], v[24:27], off offset:512
	global_store_dwordx4 v[72:73], v[16:19], off offset:512
	global_store_dwordx4 v[74:75], v[8:11], off offset:512
	global_store_dwordx4 v[12:13], v[4:7], off offset:16
	s_cbranch_vccz .LBB0_616
	s_waitcnt vmcnt(0)
	s_cmpk_gt_u32 s20, 0xff
	s_cbranch_scc1 .LBB0_623
	s_barrier
